# GEMM loops: barrier hand-off trimmed (vmcnt and lgkmcnt waits merged into one s_waitcnt before the barrier, redundant wait after it removed; priority kept through trailing barrier)
# speedup vs baseline: 1.0177x; 1.0084x over previous
; #define PG8_STAGE(bufoff, gbase, voff) do { _Pragma("unroll") for (int _i = 0; _i < 2; ++_i) \
;         __builtin_amdgcn_global_load_lds((const unsigned*)((const char*)(gbase) + (voff)[_i]), (PG8_LAS unsigned*)(lds + (bufoff) + ldsw + _i * 8192), 16, 0, 0); } while (0)
; #define PG8_LDA(dst, b, h) do { _Pragma("unroll") for (int m = 0; m < 4; ++m) _Pragma("unroll") for (int k = 0; k < 2; ++k) dst[m][k] = *(const PG8_LAS bf16x8*)(lds + PG8_SA(b, h) + aoff + m * 2048 + k * 1024); } while (0)
; #define PG8_LDB(dst, b, h) do { _Pragma("unroll") for (int n = 0; n < 2; ++n) _Pragma("unroll") for (int k = 0; k < 2; ++k) dst[n][k] = *(const PG8_LAS bf16x8*)(lds + PG8_SB(b, h) + boff + n * 2048 + k * 1024); } while (0)
; #define PG8_MMA(ai, bj, At, Bt) do { __builtin_amdgcn_s_setprio(1); _Pragma("unroll") for (int m = 0; m < 4; ++m) _Pragma("unroll") for (int n = 0; n < 2; ++n) _Pragma("unroll") for (int k = 0; k < 2; ++k) \
;         acc[ai][bj][m][n] = __builtin_amdgcn_mfma_f32_16x16x32_bf16(Bt[n][k], At[m][k], acc[ai][bj][m][n], 0, 0, 0); __builtin_amdgcn_s_setprio(0); } while (0)
; #define PG8_WAIT_V(n) asm volatile("s_waitcnt vmcnt(" #n ")" ::: "memory")
; #define PG8_BAR __builtin_amdgcn_s_barrier()
; template <class Epi, class Sched, bool ALIGN_EPI = false, bool SP2 = false>
; __device__ __forceinline__ void gemm_phase(PG8_LAS unsigned char* lds, const Gemm g, const Sched& S, const Epi& E) {
;     ...
;         for (int t = 0; t < nt; t += 2) {
;             const bool last = (t == nt - 2);
;             const char* a1 = cA + (size_t)(t + 1) * kstep;
;             const char* a2 = last ? nA : cA + (size_t)(t + 2) * kstep; const char* b2 = last ? nB : cB + (size_t)(t + 2) * kstep;
;             const char* a3 = a2 + kstep; const char* b3 = b2 + kstep;
;             if (last && has_next) S.a_ready(nxt);
;             if constexpr (SP2) {
;             PG8_LDB(B0, 0, 0); PG8_LDB(B1, 0, 1); PG8_SCHED; PG8_LDA(At, 0, 0); PG8_STAGE(PG8_SA(1, 1), a1 + hstepA, voffA);
;             PG8_WAIT_V(8); PG8_WAIT_L(0); PG8_BAR; PG8_MMA(0, 0, At, B0); PG8_MMA(0, 1, At, B1); PG8_BAR; PG8_SCHED;
;             PG8_LDA(At, 0, 1); PG8_STAGE(PG8_SB(0, 0), b2, voffB); PG8_STAGE(PG8_SB(0, 1), b2 + hstepB, voffB); PG8_STAGE(PG8_SA(0, 0), a2, voffA);
;             PG8_WAIT_V(8); PG8_WAIT_L(0); PG8_BAR; PG8_MMA(1, 0, At, B0); PG8_MMA(1, 1, At, B1); PG8_BAR; PG8_SCHED;
.LBB0_244:
	ds_read_b128 v[152:155], v147
	ds_read_b128 v[156:159], v147 offset:1024
	ds_read_b128 v[160:163], v147 offset:2048
	ds_read_b128 v[164:167], v147 offset:3072
	ds_read_b128 v[168:171], v148
	ds_read_b128 v[172:175], v148 offset:1024
	ds_read_b128 v[176:179], v148 offset:2048
	ds_read_b128 v[180:183], v148 offset:3072
	s_add_u32 s28, s26, 0xfffc0080
	s_addc_u32 s29, s27, -1
	s_cmp_eq_u32 s68, 12
	s_cselect_b32 s31, s15, s29
	s_cselect_b32 s30, s62, s28
	s_cselect_b32 s29, s13, s67
	s_cselect_b32 s28, s63, s66
	v_lshl_add_u64 v[184:185], s[26:27], 0, v[136:137]
	s_add_i32 m0, s25, 0xc000
	ds_read_b128 v[188:191], v149
	ds_read_b128 v[192:195], v149 offset:1024
	ds_read_b128 v[196:199], v149 offset:2048
	ds_read_b128 v[200:203], v149 offset:3072
	ds_read_b128 v[204:207], v149 offset:4096
	ds_read_b128 v[208:211], v149 offset:5120
	ds_read_b128 v[212:215], v149 offset:6144
	ds_read_b128 v[216:219], v149 offset:7168
	global_load_lds_dwordx4 v[184:185], off
	v_lshl_add_u64 v[184:185], s[26:27], 0, v[138:139]
	s_add_i32 m0, s25, 0xe000
	s_nop 0
	global_load_lds_dwordx4 v[184:185], off
	s_waitcnt vmcnt(8) lgkmcnt(0)
	s_barrier
	s_setprio 1
	v_mfma_f32_16x16x32_bf16 v[116:119], v[152:155], v[188:191], v[116:119]
	v_mfma_f32_16x16x32_bf16 v[108:111], v[160:163], v[188:191], v[108:111]
	v_mfma_f32_16x16x32_bf16 v[104:107], v[152:155], v[196:199], v[104:107]
	v_mfma_f32_16x16x32_bf16 v[100:103], v[160:163], v[196:199], v[100:103]
	v_mfma_f32_16x16x32_bf16 v[92:95], v[152:155], v[204:207], v[92:95]
	v_mfma_f32_16x16x32_bf16 v[84:87], v[160:163], v[204:207], v[84:87]
	v_mfma_f32_16x16x32_bf16 v[76:79], v[152:155], v[212:215], v[76:79]
	v_mfma_f32_16x16x32_bf16 v[68:71], v[160:163], v[212:215], v[68:71]
	v_mfma_f32_16x16x32_bf16 v[116:119], v[156:159], v[192:195], v[116:119]
	v_mfma_f32_16x16x32_bf16 v[108:111], v[164:167], v[192:195], v[108:111]
	v_mfma_f32_16x16x32_bf16 v[104:107], v[156:159], v[200:203], v[104:107]
	v_mfma_f32_16x16x32_bf16 v[100:103], v[164:167], v[200:203], v[100:103]
	v_mfma_f32_16x16x32_bf16 v[92:95], v[156:159], v[208:211], v[92:95]
	v_mfma_f32_16x16x32_bf16 v[84:87], v[164:167], v[208:211], v[84:87]
	v_mfma_f32_16x16x32_bf16 v[76:79], v[156:159], v[216:219], v[76:79]
	v_mfma_f32_16x16x32_bf16 v[68:71], v[164:167], v[216:219], v[68:71]
	s_setprio 0
	s_setprio 1
	v_mfma_f32_16x16x32_bf16 v[124:127], v[168:171], v[188:191], v[124:127]
	v_mfma_f32_16x16x32_bf16 v[120:123], v[176:179], v[188:191], v[120:123]
	v_mfma_f32_16x16x32_bf16 v[112:115], v[168:171], v[196:199], v[112:115]
	v_mfma_f32_16x16x32_bf16 v[96:99], v[176:179], v[196:199], v[96:99]
	v_mfma_f32_16x16x32_bf16 v[88:91], v[168:171], v[204:207], v[88:91]
	v_mfma_f32_16x16x32_bf16 v[80:83], v[176:179], v[204:207], v[80:83]
	v_mfma_f32_16x16x32_bf16 v[72:75], v[168:171], v[212:215], v[72:75]
	v_mfma_f32_16x16x32_bf16 v[64:67], v[176:179], v[212:215], v[64:67]
	v_mfma_f32_16x16x32_bf16 v[124:127], v[172:175], v[192:195], v[124:127]
	v_mfma_f32_16x16x32_bf16 v[120:123], v[180:183], v[192:195], v[120:123]
	v_mfma_f32_16x16x32_bf16 v[112:115], v[172:175], v[200:203], v[112:115]
	v_mfma_f32_16x16x32_bf16 v[96:99], v[180:183], v[200:203], v[96:99]
	v_mfma_f32_16x16x32_bf16 v[88:91], v[172:175], v[208:211], v[88:91]
	v_mfma_f32_16x16x32_bf16 v[80:83], v[180:183], v[208:211], v[80:83]
	v_mfma_f32_16x16x32_bf16 v[72:75], v[172:175], v[216:219], v[72:75]
	v_mfma_f32_16x16x32_bf16 v[64:67], v[180:183], v[216:219], v[64:67]
	s_barrier
	s_setprio 0
	s_add_i32 s58, s46, s36
	v_lshl_add_u64 v[184:185], s[28:29], 0, v[132:133]
	s_mov_b32 m0, s58
	ds_read_b128 v[188:191], v149 offset:16384
	ds_read_b128 v[192:195], v149 offset:17408
	ds_read_b128 v[196:199], v149 offset:18432
	ds_read_b128 v[200:203], v149 offset:19456
	ds_read_b128 v[204:207], v149 offset:20480
	ds_read_b128 v[208:211], v149 offset:21504
	ds_read_b128 v[212:215], v149 offset:22528
	ds_read_b128 v[216:219], v149 offset:23552
	global_load_lds_dwordx4 v[184:185], off
	s_add_i32 m0, s58, 0x2000
	s_add_u32 s58, s28, 0x40000
	v_lshl_add_u64 v[220:221], s[28:29], 0, v[128:129]
	s_addc_u32 s59, s29, 0
	s_add_i32 s69, s47, s36
	global_load_lds_dwordx4 v[220:221], off
	v_lshl_add_u64 v[222:223], s[58:59], 0, v[132:133]
	s_mov_b32 m0, s69
	v_lshl_add_u64 v[224:225], s[30:31], 0, v[130:131]
	global_load_lds_dwordx4 v[222:223], off
	v_lshl_add_u64 v[222:223], s[58:59], 0, v[128:129]
	s_add_i32 m0, s69, 0x2000
	s_nop 0
	global_load_lds_dwordx4 v[222:223], off
	v_lshl_add_u64 v[222:223], s[30:31], 0, v[134:135]
	s_mov_b32 m0, s25
	s_nop 0
	global_load_lds_dwordx4 v[222:223], off
	s_mov_b32 m0, s39
	s_nop 0
	global_load_lds_dwordx4 v[224:225], off
	s_waitcnt vmcnt(8) lgkmcnt(0)
	s_barrier
; #define PG8_STAGE(bufoff, gbase, voff) do { _Pragma("unroll") for (int _i = 0; _i < 2; ++_i) \
;         __builtin_amdgcn_global_load_lds((const unsigned*)((const char*)(gbase) + (voff)[_i]), (PG8_LAS unsigned*)(lds + (bufoff) + ldsw + _i * 8192), 16, 0, 0); } while (0)
; #define PG8_LDA(dst, b, h) do { _Pragma("unroll") for (int m = 0; m < 4; ++m) _Pragma("unroll") for (int k = 0; k < 2; ++k) dst[m][k] = *(const PG8_LAS bf16x8*)(lds + PG8_SA(b, h) + aoff + m * 2048 + k * 1024); } while (0)
; #define PG8_LDB(dst, b, h) do { _Pragma("unroll") for (int n = 0; n < 2; ++n) _Pragma("unroll") for (int k = 0; k < 2; ++k) dst[n][k] = *(const PG8_LAS bf16x8*)(lds + PG8_SB(b, h) + boff + n * 2048 + k * 1024); } while (0)
; #define PG8_MMA(ai, bj, At, Bt) do { __builtin_amdgcn_s_setprio(1); _Pragma("unroll") for (int m = 0; m < 4; ++m) _Pragma("unroll") for (int n = 0; n < 2; ++n) _Pragma("unroll") for (int k = 0; k < 2; ++k) \
;         acc[ai][bj][m][n] = __builtin_amdgcn_mfma_f32_16x16x32_bf16(Bt[n][k], At[m][k], acc[ai][bj][m][n], 0, 0, 0); __builtin_amdgcn_s_setprio(0); } while (0)
; #define PG8_WAIT_V(n) asm volatile("s_waitcnt vmcnt(" #n ")" ::: "memory")
; #define PG8_WAIT_L(n) asm volatile("s_waitcnt lgkmcnt(" #n ")" ::: "memory")
; #define PG8_BAR __builtin_amdgcn_s_barrier()
; #define PG8_SCHED __builtin_amdgcn_sched_barrier(0)
; template <class Epi, class Sched, bool ALIGN_EPI = false, bool SP2 = false>
; __device__ __forceinline__ void gemm_phase(PG8_LAS unsigned char* lds, const Gemm g, const Sched& S, const Epi& E) {
;     ...
;             PG8_WAIT_V(8); PG8_WAIT_L(0); PG8_BAR; PG8_MMA(1, 0, At, B0); PG8_MMA(1, 1, At, B1); PG8_BAR; PG8_SCHED;
;             PG8_LDB(B0, 1, 0); PG8_LDB(B1, 1, 1); PG8_SCHED; PG8_LDA(At, 1, 0); PG8_STAGE(PG8_SA(0, 1), a2 + hstepA, voffA);
;             PG8_WAIT_V(8); PG8_WAIT_L(0); PG8_BAR; PG8_MMA(0, 0, At, B0); PG8_MMA(0, 1, At, B1); PG8_BAR; PG8_SCHED;
	s_setprio 1
	v_mfma_f32_16x16x32_bf16 v[60:63], v[152:155], v[188:191], v[60:63]
	v_mfma_f32_16x16x32_bf16 v[52:55], v[160:163], v[188:191], v[52:55]
	v_mfma_f32_16x16x32_bf16 v[44:47], v[152:155], v[196:199], v[44:47]
	v_mfma_f32_16x16x32_bf16 v[36:39], v[160:163], v[196:199], v[36:39]
	v_mfma_f32_16x16x32_bf16 v[28:31], v[152:155], v[204:207], v[28:31]
	v_mfma_f32_16x16x32_bf16 v[20:23], v[160:163], v[204:207], v[20:23]
	v_mfma_f32_16x16x32_bf16 v[12:15], v[152:155], v[212:215], v[12:15]
	v_mfma_f32_16x16x32_bf16 v[4:7], v[160:163], v[212:215], v[4:7]
	v_mfma_f32_16x16x32_bf16 v[60:63], v[156:159], v[192:195], v[60:63]
	v_mfma_f32_16x16x32_bf16 v[52:55], v[164:167], v[192:195], v[52:55]
	v_mfma_f32_16x16x32_bf16 v[44:47], v[156:159], v[200:203], v[44:47]
	v_mfma_f32_16x16x32_bf16 v[36:39], v[164:167], v[200:203], v[36:39]
	v_mfma_f32_16x16x32_bf16 v[28:31], v[156:159], v[208:211], v[28:31]
	v_mfma_f32_16x16x32_bf16 v[20:23], v[164:167], v[208:211], v[20:23]
	v_mfma_f32_16x16x32_bf16 v[12:15], v[156:159], v[216:219], v[12:15]
	v_mfma_f32_16x16x32_bf16 v[4:7], v[164:167], v[216:219], v[4:7]
	s_setprio 0
	s_setprio 1
	v_mfma_f32_16x16x32_bf16 v[56:59], v[168:171], v[188:191], v[56:59]
	v_mfma_f32_16x16x32_bf16 v[48:51], v[176:179], v[188:191], v[48:51]
	v_mfma_f32_16x16x32_bf16 v[40:43], v[168:171], v[196:199], v[40:43]
	v_mfma_f32_16x16x32_bf16 v[32:35], v[176:179], v[196:199], v[32:35]
	v_mfma_f32_16x16x32_bf16 v[24:27], v[168:171], v[204:207], v[24:27]
	v_mfma_f32_16x16x32_bf16 v[16:19], v[176:179], v[204:207], v[16:19]
	v_mfma_f32_16x16x32_bf16 v[8:11], v[168:171], v[212:215], v[8:11]
	v_mfma_f32_16x16x32_bf16 v[0:3], v[176:179], v[212:215], v[0:3]
	v_mfma_f32_16x16x32_bf16 v[56:59], v[172:175], v[192:195], v[56:59]
	v_mfma_f32_16x16x32_bf16 v[48:51], v[180:183], v[192:195], v[48:51]
	v_mfma_f32_16x16x32_bf16 v[40:43], v[172:175], v[200:203], v[40:43]
	v_mfma_f32_16x16x32_bf16 v[32:35], v[180:183], v[200:203], v[32:35]
	v_mfma_f32_16x16x32_bf16 v[24:27], v[172:175], v[208:211], v[24:27]
	v_mfma_f32_16x16x32_bf16 v[16:19], v[180:183], v[208:211], v[16:19]
	v_mfma_f32_16x16x32_bf16 v[8:11], v[172:175], v[216:219], v[8:11]
	v_mfma_f32_16x16x32_bf16 v[0:3], v[180:183], v[216:219], v[0:3]
	s_barrier
	s_setprio 0
	s_add_i32 s58, 0, 0x18000
	v_add_u32_e32 v151, s58, v145
	s_add_i32 s59, 0, 0x1c000
	ds_read_b128 v[152:155], v151
	ds_read_b128 v[156:159], v151 offset:1024
	ds_read_b128 v[160:163], v151 offset:2048
	ds_read_b128 v[164:167], v151 offset:3072
	v_add_u32_e32 v151, s59, v145
	ds_read_b128 v[168:171], v151
	ds_read_b128 v[172:175], v151 offset:1024
	ds_read_b128 v[176:179], v151 offset:2048
	ds_read_b128 v[180:183], v151 offset:3072
	s_add_u32 s30, s30, 0x40000
	s_addc_u32 s31, s31, 0
	s_mov_b32 m0, s40
	v_lshl_add_u64 v[226:227], s[30:31], 0, v[134:135]
	ds_read_b128 v[188:191], v149 offset:32768
	ds_read_b128 v[192:195], v149 offset:33792
	ds_read_b128 v[196:199], v149 offset:34816
	ds_read_b128 v[200:203], v149 offset:35840
	ds_read_b128 v[204:207], v149 offset:36864
	ds_read_b128 v[208:211], v149 offset:37888
	ds_read_b128 v[212:215], v149 offset:38912
	ds_read_b128 v[216:219], v149 offset:39936
	global_load_lds_dwordx4 v[226:227], off
	v_lshl_add_u64 v[226:227], s[30:31], 0, v[130:131]
	s_mov_b32 m0, s41
	s_nop 0
	global_load_lds_dwordx4 v[226:227], off
	s_waitcnt vmcnt(8) lgkmcnt(0)
	s_barrier
	s_setprio 1
	v_mfma_f32_16x16x32_bf16 v[116:119], v[152:155], v[188:191], v[116:119]
	v_mfma_f32_16x16x32_bf16 v[108:111], v[160:163], v[188:191], v[108:111]
	v_mfma_f32_16x16x32_bf16 v[104:107], v[152:155], v[196:199], v[104:107]
	v_mfma_f32_16x16x32_bf16 v[100:103], v[160:163], v[196:199], v[100:103]
	v_mfma_f32_16x16x32_bf16 v[92:95], v[152:155], v[204:207], v[92:95]
	v_mfma_f32_16x16x32_bf16 v[84:87], v[160:163], v[204:207], v[84:87]
	v_mfma_f32_16x16x32_bf16 v[76:79], v[152:155], v[212:215], v[76:79]
	v_mfma_f32_16x16x32_bf16 v[68:71], v[160:163], v[212:215], v[68:71]
	v_mfma_f32_16x16x32_bf16 v[116:119], v[156:159], v[192:195], v[116:119]
	v_mfma_f32_16x16x32_bf16 v[108:111], v[164:167], v[192:195], v[108:111]
	v_mfma_f32_16x16x32_bf16 v[104:107], v[156:159], v[200:203], v[104:107]
	v_mfma_f32_16x16x32_bf16 v[100:103], v[164:167], v[200:203], v[100:103]
	v_mfma_f32_16x16x32_bf16 v[92:95], v[156:159], v[208:211], v[92:95]
	v_mfma_f32_16x16x32_bf16 v[84:87], v[164:167], v[208:211], v[84:87]
	v_mfma_f32_16x16x32_bf16 v[76:79], v[156:159], v[216:219], v[76:79]
	v_mfma_f32_16x16x32_bf16 v[68:71], v[164:167], v[216:219], v[68:71]
	s_setprio 0
	s_setprio 1
	v_mfma_f32_16x16x32_bf16 v[124:127], v[168:171], v[188:191], v[124:127]
	v_mfma_f32_16x16x32_bf16 v[120:123], v[176:179], v[188:191], v[120:123]
	v_mfma_f32_16x16x32_bf16 v[112:115], v[168:171], v[196:199], v[112:115]
	v_mfma_f32_16x16x32_bf16 v[96:99], v[176:179], v[196:199], v[96:99]
	v_mfma_f32_16x16x32_bf16 v[88:91], v[168:171], v[204:207], v[88:91]
	v_mfma_f32_16x16x32_bf16 v[80:83], v[176:179], v[204:207], v[80:83]
	v_mfma_f32_16x16x32_bf16 v[72:75], v[168:171], v[212:215], v[72:75]
	v_mfma_f32_16x16x32_bf16 v[64:67], v[176:179], v[212:215], v[64:67]
	v_mfma_f32_16x16x32_bf16 v[124:127], v[172:175], v[192:195], v[124:127]
	v_mfma_f32_16x16x32_bf16 v[120:123], v[180:183], v[192:195], v[120:123]
	v_mfma_f32_16x16x32_bf16 v[112:115], v[172:175], v[200:203], v[112:115]
	v_mfma_f32_16x16x32_bf16 v[96:99], v[180:183], v[200:203], v[96:99]
	v_mfma_f32_16x16x32_bf16 v[88:91], v[172:175], v[208:211], v[88:91]
	v_mfma_f32_16x16x32_bf16 v[80:83], v[180:183], v[208:211], v[80:83]
	v_mfma_f32_16x16x32_bf16 v[72:75], v[172:175], v[216:219], v[72:75]
	v_mfma_f32_16x16x32_bf16 v[64:67], v[180:183], v[216:219], v[64:67]
	s_barrier
; #define PG8_STAGE(bufoff, gbase, voff) do { _Pragma("unroll") for (int _i = 0; _i < 2; ++_i) \
;         __builtin_amdgcn_global_load_lds((const unsigned*)((const char*)(gbase) + (voff)[_i]), (PG8_LAS unsigned*)(lds + (bufoff) + ldsw + _i * 8192), 16, 0, 0); } while (0)
; #define PG8_LDA(dst, b, h) do { _Pragma("unroll") for (int m = 0; m < 4; ++m) _Pragma("unroll") for (int k = 0; k < 2; ++k) dst[m][k] = *(const PG8_LAS bf16x8*)(lds + PG8_SA(b, h) + aoff + m * 2048 + k * 1024); } while (0)
; #define PG8_MMA(ai, bj, At, Bt) do { __builtin_amdgcn_s_setprio(1); _Pragma("unroll") for (int m = 0; m < 4; ++m) _Pragma("unroll") for (int n = 0; n < 2; ++n) _Pragma("unroll") for (int k = 0; k < 2; ++k) \
;         acc[ai][bj][m][n] = __builtin_amdgcn_mfma_f32_16x16x32_bf16(Bt[n][k], At[m][k], acc[ai][bj][m][n], 0, 0, 0); __builtin_amdgcn_s_setprio(0); } while (0)
; #define PG8_WAIT_V(n) asm volatile("s_waitcnt vmcnt(" #n ")" ::: "memory")
; #define PG8_WAIT_L(n) asm volatile("s_waitcnt lgkmcnt(" #n ")" ::: "memory")
; #define PG8_BAR __builtin_amdgcn_s_barrier()
; #define PG8_SCHED __builtin_amdgcn_sched_barrier(0)
; template <class Epi, class Sched, bool ALIGN_EPI = false, bool SP2 = false>
; __device__ __forceinline__ void gemm_phase(PG8_LAS unsigned char* lds, const Gemm g, const Sched& S, const Epi& E) {
;     ...
;             PG8_LDA(At, 1, 1); PG8_STAGE(PG8_SB(1, 0), b3, voffB); PG8_STAGE(PG8_SB(1, 1), b3 + hstepB, voffB); PG8_STAGE(PG8_SA(1, 0), a3, voffA);
;             PG8_WAIT_V(8); PG8_WAIT_L(0); PG8_BAR; PG8_MMA(1, 0, At, B0); PG8_MMA(1, 1, At, B1); PG8_BAR; PG8_SCHED;
;     ...
;         if constexpr (ALIGN_EPI) { if (wr == 0) PG8_BAR; }
	s_setprio 0
	s_add_i32 s30, s58, s36
	v_lshl_add_u64 v[184:185], v[184:185], 0, s[8:9]
	s_mov_b32 m0, s30
	ds_read_b128 v[188:191], v149 offset:49152
	ds_read_b128 v[192:195], v149 offset:50176
	ds_read_b128 v[196:199], v149 offset:51200
	ds_read_b128 v[200:203], v149 offset:52224
	ds_read_b128 v[204:207], v149 offset:53248
	ds_read_b128 v[208:211], v149 offset:54272
	ds_read_b128 v[212:215], v149 offset:55296
	ds_read_b128 v[216:219], v149 offset:56320
	global_load_lds_dwordx4 v[184:185], off
	s_add_i32 m0, s30, 0x2000
	s_add_u32 s28, s28, 0x40080
	v_lshl_add_u64 v[184:185], v[220:221], 0, s[8:9]
	s_addc_u32 s29, s29, 0
	s_add_i32 s30, s59, s36
	global_load_lds_dwordx4 v[184:185], off
	v_lshl_add_u64 v[184:185], s[28:29], 0, v[132:133]
	s_mov_b32 m0, s30
	s_nop 0
	global_load_lds_dwordx4 v[184:185], off
	v_lshl_add_u64 v[184:185], s[28:29], 0, v[128:129]
	s_add_i32 m0, s30, 0x2000
	s_nop 0
	global_load_lds_dwordx4 v[184:185], off
	v_lshl_add_u64 v[184:185], v[222:223], 0, s[8:9]
	s_mov_b32 m0, s43
	s_nop 0
	global_load_lds_dwordx4 v[184:185], off
	v_lshl_add_u64 v[184:185], v[224:225], 0, s[8:9]
	s_mov_b32 m0, s44
	s_nop 0
	global_load_lds_dwordx4 v[184:185], off
	s_waitcnt vmcnt(8) lgkmcnt(0)
	s_barrier
	s_setprio 1
	v_mfma_f32_16x16x32_bf16 v[60:63], v[152:155], v[188:191], v[60:63]
	v_mfma_f32_16x16x32_bf16 v[52:55], v[160:163], v[188:191], v[52:55]
	v_mfma_f32_16x16x32_bf16 v[44:47], v[152:155], v[196:199], v[44:47]
	v_mfma_f32_16x16x32_bf16 v[36:39], v[160:163], v[196:199], v[36:39]
	v_mfma_f32_16x16x32_bf16 v[28:31], v[152:155], v[204:207], v[28:31]
	v_mfma_f32_16x16x32_bf16 v[20:23], v[160:163], v[204:207], v[20:23]
	v_mfma_f32_16x16x32_bf16 v[12:15], v[152:155], v[212:215], v[12:15]
	v_mfma_f32_16x16x32_bf16 v[4:7], v[160:163], v[212:215], v[4:7]
	v_mfma_f32_16x16x32_bf16 v[60:63], v[156:159], v[192:195], v[60:63]
	v_mfma_f32_16x16x32_bf16 v[52:55], v[164:167], v[192:195], v[52:55]
	v_mfma_f32_16x16x32_bf16 v[44:47], v[156:159], v[200:203], v[44:47]
	v_mfma_f32_16x16x32_bf16 v[36:39], v[164:167], v[200:203], v[36:39]
	v_mfma_f32_16x16x32_bf16 v[28:31], v[156:159], v[208:211], v[28:31]
	v_mfma_f32_16x16x32_bf16 v[20:23], v[164:167], v[208:211], v[20:23]
	v_mfma_f32_16x16x32_bf16 v[12:15], v[156:159], v[216:219], v[12:15]
	v_mfma_f32_16x16x32_bf16 v[4:7], v[164:167], v[216:219], v[4:7]
	s_setprio 0
	s_setprio 1
	v_mfma_f32_16x16x32_bf16 v[56:59], v[168:171], v[188:191], v[56:59]
	v_mfma_f32_16x16x32_bf16 v[48:51], v[176:179], v[188:191], v[48:51]
	v_mfma_f32_16x16x32_bf16 v[40:43], v[168:171], v[196:199], v[40:43]
	v_mfma_f32_16x16x32_bf16 v[32:35], v[176:179], v[196:199], v[32:35]
	v_mfma_f32_16x16x32_bf16 v[24:27], v[168:171], v[204:207], v[24:27]
	v_mfma_f32_16x16x32_bf16 v[16:19], v[176:179], v[204:207], v[16:19]
	v_mfma_f32_16x16x32_bf16 v[8:11], v[168:171], v[212:215], v[8:11]
	v_mfma_f32_16x16x32_bf16 v[0:3], v[176:179], v[212:215], v[0:3]
	v_mfma_f32_16x16x32_bf16 v[56:59], v[172:175], v[192:195], v[56:59]
	v_mfma_f32_16x16x32_bf16 v[48:51], v[180:183], v[192:195], v[48:51]
	v_mfma_f32_16x16x32_bf16 v[40:43], v[172:175], v[200:203], v[40:43]
	v_mfma_f32_16x16x32_bf16 v[32:35], v[180:183], v[200:203], v[32:35]
	v_mfma_f32_16x16x32_bf16 v[24:27], v[172:175], v[208:211], v[24:27]
	v_mfma_f32_16x16x32_bf16 v[16:19], v[180:183], v[208:211], v[16:19]
	v_mfma_f32_16x16x32_bf16 v[8:11], v[172:175], v[216:219], v[8:11]
	v_mfma_f32_16x16x32_bf16 v[0:3], v[180:183], v[216:219], v[0:3]
	s_barrier
	s_setprio 0
	s_add_i32 s68, s68, 2
	s_add_u32 s26, s26, 0x100
	s_addc_u32 s27, s27, 0
	s_add_u32 s66, s66, 0x100
	s_addc_u32 s67, s67, 0
	s_cmp_gt_u32 s68, 13
	s_cbranch_scc0 .LBB0_244
	s_and_b64 vcc, exec, s[10:11]
	s_cbranch_vccz .LBB0_247
	s_barrier

; #define PG8_STAGE(bufoff, gbase, voff) do { _Pragma("unroll") for (int _i = 0; _i < 2; ++_i) \
;         __builtin_amdgcn_global_load_lds((const unsigned*)((const char*)(gbase) + (voff)[_i]), (PG8_LAS unsigned*)(lds + (bufoff) + ldsw + _i * 8192), 16, 0, 0); } while (0)
; #define PG8_LDA(dst, b, h) do { _Pragma("unroll") for (int m = 0; m < 4; ++m) _Pragma("unroll") for (int k = 0; k < 2; ++k) dst[m][k] = *(const PG8_LAS bf16x8*)(lds + PG8_SA(b, h) + aoff + m * 2048 + k * 1024); } while (0)
; #define PG8_LDB(dst, b, h) do { _Pragma("unroll") for (int n = 0; n < 2; ++n) _Pragma("unroll") for (int k = 0; k < 2; ++k) dst[n][k] = *(const PG8_LAS bf16x8*)(lds + PG8_SB(b, h) + boff + n * 2048 + k * 1024); } while (0)
; #define PG8_MMA(ai, bj, At, Bt) do { __builtin_amdgcn_s_setprio(1); _Pragma("unroll") for (int m = 0; m < 4; ++m) _Pragma("unroll") for (int n = 0; n < 2; ++n) _Pragma("unroll") for (int k = 0; k < 2; ++k) \
;         acc[ai][bj][m][n] = __builtin_amdgcn_mfma_f32_16x16x32_bf16(Bt[n][k], At[m][k], acc[ai][bj][m][n], 0, 0, 0); __builtin_amdgcn_s_setprio(0); } while (0)
; #define PG8_WAIT_V(n) asm volatile("s_waitcnt vmcnt(" #n ")" ::: "memory")
; #define PG8_BAR __builtin_amdgcn_s_barrier()
; template <class Epi, class Sched, bool ALIGN_EPI = false, bool SP2 = false>
; __device__ __forceinline__ void gemm_phase(PG8_LAS unsigned char* lds, const Gemm g, const Sched& S, const Epi& E) {
;     ...
;         for (int t = 0; t < nt; t += 2) {
;             const bool last = (t == nt - 2);
;             const char* a1 = cA + (size_t)(t + 1) * kstep;
;             const char* a2 = last ? nA : cA + (size_t)(t + 2) * kstep; const char* b2 = last ? nB : cB + (size_t)(t + 2) * kstep;
;             const char* a3 = a2 + kstep; const char* b3 = b2 + kstep;
;             if (last && has_next) S.a_ready(nxt);
;             if constexpr (SP2) {
;             PG8_LDB(B0, 0, 0); PG8_LDB(B1, 0, 1); PG8_SCHED; PG8_LDA(At, 0, 0); PG8_STAGE(PG8_SA(1, 1), a1 + hstepA, voffA);
;             PG8_WAIT_V(8); PG8_WAIT_L(0); PG8_BAR; PG8_MMA(0, 0, At, B0); PG8_MMA(0, 1, At, B1); PG8_BAR; PG8_SCHED;
;             PG8_LDA(At, 0, 1); PG8_STAGE(PG8_SB(0, 0), b2, voffB); PG8_STAGE(PG8_SB(0, 1), b2 + hstepB, voffB); PG8_STAGE(PG8_SA(0, 0), a2, voffA);
;             PG8_WAIT_V(8); PG8_WAIT_L(0); PG8_BAR; PG8_MMA(1, 0, At, B0); PG8_MMA(1, 1, At, B1); PG8_BAR; PG8_SCHED;
.LBB0_318:
	ds_read_b128 v[128:131], v191
	ds_read_b128 v[132:135], v191 offset:1024
	ds_read_b128 v[136:139], v191 offset:2048
	ds_read_b128 v[140:143], v191 offset:3072
	ds_read_b128 v[144:147], v192
	ds_read_b128 v[148:151], v192 offset:1024
	ds_read_b128 v[168:171], v192 offset:2048
	ds_read_b128 v[172:175], v192 offset:3072
	s_add_u32 s28, s26, 0x100
	s_addc_u32 s29, s27, 0
	s_cmp_eq_u32 s72, 40
	s_cselect_b32 s35, s11, s29
	s_cselect_b32 s34, s10, s28
	s_cselect_b32 s31, s23, s71
	s_cselect_b32 s30, s22, s70
	v_lshl_add_u64 v[184:185], s[26:27], 0, v[160:161]
	s_add_i32 m0, s39, 0xc000
	ds_read_b128 v[176:179], v193
	ds_read_b128 v[180:183], v193 offset:1024
	ds_read_b128 v[196:199], v193 offset:2048
	ds_read_b128 v[200:203], v193 offset:3072
	ds_read_b128 v[204:207], v193 offset:4096
	ds_read_b128 v[208:211], v193 offset:5120
	ds_read_b128 v[212:215], v193 offset:6144
	ds_read_b128 v[216:219], v193 offset:7168
	global_load_lds_dwordx4 v[184:185], off
	v_lshl_add_u64 v[184:185], s[26:27], 0, v[162:163]
	s_add_i32 m0, s39, 0xe000
	s_nop 0
	global_load_lds_dwordx4 v[184:185], off
	s_waitcnt vmcnt(8) lgkmcnt(0)
	s_barrier
	s_setprio 1
	v_mfma_f32_16x16x32_bf16 v[124:127], v[128:131], v[176:179], v[124:127]
	v_mfma_f32_16x16x32_bf16 v[120:123], v[136:139], v[176:179], v[120:123]
	v_mfma_f32_16x16x32_bf16 v[108:111], v[128:131], v[196:199], v[108:111]
	v_mfma_f32_16x16x32_bf16 v[104:107], v[136:139], v[196:199], v[104:107]
	v_mfma_f32_16x16x32_bf16 v[92:95], v[128:131], v[204:207], v[92:95]
	v_mfma_f32_16x16x32_bf16 v[88:91], v[136:139], v[204:207], v[88:91]
	v_mfma_f32_16x16x32_bf16 v[76:79], v[128:131], v[212:215], v[76:79]
	v_mfma_f32_16x16x32_bf16 v[72:75], v[136:139], v[212:215], v[72:75]
	v_mfma_f32_16x16x32_bf16 v[124:127], v[132:135], v[180:183], v[124:127]
	v_mfma_f32_16x16x32_bf16 v[120:123], v[140:143], v[180:183], v[120:123]
	v_mfma_f32_16x16x32_bf16 v[108:111], v[132:135], v[200:203], v[108:111]
	v_mfma_f32_16x16x32_bf16 v[104:107], v[140:143], v[200:203], v[104:107]
	v_mfma_f32_16x16x32_bf16 v[92:95], v[132:135], v[208:211], v[92:95]
	v_mfma_f32_16x16x32_bf16 v[88:91], v[140:143], v[208:211], v[88:91]
	v_mfma_f32_16x16x32_bf16 v[76:79], v[132:135], v[216:219], v[76:79]
	v_mfma_f32_16x16x32_bf16 v[72:75], v[140:143], v[216:219], v[72:75]
	s_setprio 0
	s_setprio 1
	v_mfma_f32_16x16x32_bf16 v[116:119], v[144:147], v[176:179], v[116:119]
	v_mfma_f32_16x16x32_bf16 v[112:115], v[168:171], v[176:179], v[112:115]
	v_mfma_f32_16x16x32_bf16 v[100:103], v[144:147], v[196:199], v[100:103]
	v_mfma_f32_16x16x32_bf16 v[96:99], v[168:171], v[196:199], v[96:99]
	v_mfma_f32_16x16x32_bf16 v[84:87], v[144:147], v[204:207], v[84:87]
	v_mfma_f32_16x16x32_bf16 v[80:83], v[168:171], v[204:207], v[80:83]
	v_mfma_f32_16x16x32_bf16 v[68:71], v[144:147], v[212:215], v[68:71]
	v_mfma_f32_16x16x32_bf16 v[64:67], v[168:171], v[212:215], v[64:67]
	v_mfma_f32_16x16x32_bf16 v[116:119], v[148:151], v[180:183], v[116:119]
	v_mfma_f32_16x16x32_bf16 v[112:115], v[172:175], v[180:183], v[112:115]
	v_mfma_f32_16x16x32_bf16 v[100:103], v[148:151], v[200:203], v[100:103]
	v_mfma_f32_16x16x32_bf16 v[96:99], v[172:175], v[200:203], v[96:99]
	v_mfma_f32_16x16x32_bf16 v[84:87], v[148:151], v[208:211], v[84:87]
	v_mfma_f32_16x16x32_bf16 v[80:83], v[172:175], v[208:211], v[80:83]
	v_mfma_f32_16x16x32_bf16 v[68:71], v[148:151], v[216:219], v[68:71]
	v_mfma_f32_16x16x32_bf16 v[64:67], v[172:175], v[216:219], v[64:67]
	s_barrier
	s_setprio 0
	s_add_i32 s26, s49, s38
	v_lshl_add_u64 v[184:185], s[30:31], 0, v[154:155]
	s_mov_b32 m0, s26
	ds_read_b128 v[176:179], v193 offset:16384
	ds_read_b128 v[180:183], v193 offset:17408
	ds_read_b128 v[196:199], v193 offset:18432
	ds_read_b128 v[200:203], v193 offset:19456
	ds_read_b128 v[204:207], v193 offset:20480
	ds_read_b128 v[208:211], v193 offset:21504
	ds_read_b128 v[212:215], v193 offset:22528
	ds_read_b128 v[216:219], v193 offset:23552
	global_load_lds_dwordx4 v[184:185], off
	s_add_i32 m0, s26, 0x2000
	s_add_u32 s26, s30, 0xb0000
	v_lshl_add_u64 v[220:221], s[30:31], 0, v[158:159]
	s_addc_u32 s27, s31, 0
	s_add_i32 s58, s62, s38
	global_load_lds_dwordx4 v[220:221], off
	v_lshl_add_u64 v[222:223], s[26:27], 0, v[154:155]
	s_mov_b32 m0, s58
	v_lshl_add_u64 v[224:225], s[34:35], 0, v[156:157]
	global_load_lds_dwordx4 v[222:223], off
	v_lshl_add_u64 v[222:223], s[26:27], 0, v[158:159]
	s_add_i32 m0, s58, 0x2000
	s_nop 0
	global_load_lds_dwordx4 v[222:223], off
	v_lshl_add_u64 v[222:223], s[34:35], 0, v[152:153]
	s_mov_b32 m0, s39
	s_nop 0
	global_load_lds_dwordx4 v[222:223], off
	s_mov_b32 m0, s40
	s_nop 0
	global_load_lds_dwordx4 v[224:225], off
	s_waitcnt vmcnt(8) lgkmcnt(0)
	s_barrier
; #define PG8_STAGE(bufoff, gbase, voff) do { _Pragma("unroll") for (int _i = 0; _i < 2; ++_i) \
;         __builtin_amdgcn_global_load_lds((const unsigned*)((const char*)(gbase) + (voff)[_i]), (PG8_LAS unsigned*)(lds + (bufoff) + ldsw + _i * 8192), 16, 0, 0); } while (0)
; #define PG8_LDA(dst, b, h) do { _Pragma("unroll") for (int m = 0; m < 4; ++m) _Pragma("unroll") for (int k = 0; k < 2; ++k) dst[m][k] = *(const PG8_LAS bf16x8*)(lds + PG8_SA(b, h) + aoff + m * 2048 + k * 1024); } while (0)
; #define PG8_LDB(dst, b, h) do { _Pragma("unroll") for (int n = 0; n < 2; ++n) _Pragma("unroll") for (int k = 0; k < 2; ++k) dst[n][k] = *(const PG8_LAS bf16x8*)(lds + PG8_SB(b, h) + boff + n * 2048 + k * 1024); } while (0)
; #define PG8_MMA(ai, bj, At, Bt) do { __builtin_amdgcn_s_setprio(1); _Pragma("unroll") for (int m = 0; m < 4; ++m) _Pragma("unroll") for (int n = 0; n < 2; ++n) _Pragma("unroll") for (int k = 0; k < 2; ++k) \
;         acc[ai][bj][m][n] = __builtin_amdgcn_mfma_f32_16x16x32_bf16(Bt[n][k], At[m][k], acc[ai][bj][m][n], 0, 0, 0); __builtin_amdgcn_s_setprio(0); } while (0)
; #define PG8_WAIT_V(n) asm volatile("s_waitcnt vmcnt(" #n ")" ::: "memory")
; #define PG8_WAIT_L(n) asm volatile("s_waitcnt lgkmcnt(" #n ")" ::: "memory")
; #define PG8_BAR __builtin_amdgcn_s_barrier()
; #define PG8_SCHED __builtin_amdgcn_sched_barrier(0)
; template <class Epi, class Sched, bool ALIGN_EPI = false, bool SP2 = false>
; __device__ __forceinline__ void gemm_phase(PG8_LAS unsigned char* lds, const Gemm g, const Sched& S, const Epi& E) {
;     ...
;             PG8_WAIT_V(8); PG8_WAIT_L(0); PG8_BAR; PG8_MMA(1, 0, At, B0); PG8_MMA(1, 1, At, B1); PG8_BAR; PG8_SCHED;
;             PG8_LDB(B0, 1, 0); PG8_LDB(B1, 1, 1); PG8_SCHED; PG8_LDA(At, 1, 0); PG8_STAGE(PG8_SA(0, 1), a2 + hstepA, voffA);
;             PG8_WAIT_V(8); PG8_WAIT_L(0); PG8_BAR; PG8_MMA(0, 0, At, B0); PG8_MMA(0, 1, At, B1); PG8_BAR; PG8_SCHED;
	s_setprio 1
	v_mfma_f32_16x16x32_bf16 v[60:63], v[128:131], v[176:179], v[60:63]
	v_mfma_f32_16x16x32_bf16 v[56:59], v[136:139], v[176:179], v[56:59]
	v_mfma_f32_16x16x32_bf16 v[44:47], v[128:131], v[196:199], v[44:47]
	v_mfma_f32_16x16x32_bf16 v[40:43], v[136:139], v[196:199], v[40:43]
	v_mfma_f32_16x16x32_bf16 v[28:31], v[128:131], v[204:207], v[28:31]
	v_mfma_f32_16x16x32_bf16 v[24:27], v[136:139], v[204:207], v[24:27]
	v_mfma_f32_16x16x32_bf16 v[12:15], v[128:131], v[212:215], v[12:15]
	v_mfma_f32_16x16x32_bf16 v[8:11], v[136:139], v[212:215], v[8:11]
	v_mfma_f32_16x16x32_bf16 v[60:63], v[132:135], v[180:183], v[60:63]
	v_mfma_f32_16x16x32_bf16 v[56:59], v[140:143], v[180:183], v[56:59]
	v_mfma_f32_16x16x32_bf16 v[44:47], v[132:135], v[200:203], v[44:47]
	v_mfma_f32_16x16x32_bf16 v[40:43], v[140:143], v[200:203], v[40:43]
	v_mfma_f32_16x16x32_bf16 v[28:31], v[132:135], v[208:211], v[28:31]
	v_mfma_f32_16x16x32_bf16 v[24:27], v[140:143], v[208:211], v[24:27]
	v_mfma_f32_16x16x32_bf16 v[12:15], v[132:135], v[216:219], v[12:15]
	v_mfma_f32_16x16x32_bf16 v[8:11], v[140:143], v[216:219], v[8:11]
	s_setprio 0
	s_setprio 1
	v_mfma_f32_16x16x32_bf16 v[52:55], v[144:147], v[176:179], v[52:55]
	v_mfma_f32_16x16x32_bf16 v[48:51], v[168:171], v[176:179], v[48:51]
	v_mfma_f32_16x16x32_bf16 v[36:39], v[144:147], v[196:199], v[36:39]
	v_mfma_f32_16x16x32_bf16 v[32:35], v[168:171], v[196:199], v[32:35]
	v_mfma_f32_16x16x32_bf16 v[20:23], v[144:147], v[204:207], v[20:23]
	v_mfma_f32_16x16x32_bf16 v[16:19], v[168:171], v[204:207], v[16:19]
	v_mfma_f32_16x16x32_bf16 v[4:7], v[144:147], v[212:215], v[4:7]
	v_mfma_f32_16x16x32_bf16 v[0:3], v[168:171], v[212:215], v[0:3]
	v_mfma_f32_16x16x32_bf16 v[52:55], v[148:151], v[180:183], v[52:55]
	v_mfma_f32_16x16x32_bf16 v[48:51], v[172:175], v[180:183], v[48:51]
	v_mfma_f32_16x16x32_bf16 v[36:39], v[148:151], v[200:203], v[36:39]
	v_mfma_f32_16x16x32_bf16 v[32:35], v[172:175], v[200:203], v[32:35]
	v_mfma_f32_16x16x32_bf16 v[20:23], v[148:151], v[208:211], v[20:23]
	v_mfma_f32_16x16x32_bf16 v[16:19], v[172:175], v[208:211], v[16:19]
	v_mfma_f32_16x16x32_bf16 v[4:7], v[148:151], v[216:219], v[4:7]
	v_mfma_f32_16x16x32_bf16 v[0:3], v[172:175], v[216:219], v[0:3]
	s_barrier
	s_setprio 0
	s_add_i32 s58, 0, 0x18000
	s_add_i32 s59, 0, 0x1c000
	v_add_u32_e32 v140, s58, v189
	v_add_u32_e32 v172, s59, v189
	ds_read_b128 v[128:131], v140
	ds_read_b128 v[132:135], v140 offset:1024
	ds_read_b128 v[136:139], v140 offset:2048
	ds_read_b128 v[140:143], v140 offset:3072
	ds_read_b128 v[144:147], v172
	ds_read_b128 v[148:151], v172 offset:1024
	ds_read_b128 v[168:171], v172 offset:2048
	ds_read_b128 v[172:175], v172 offset:3072
	s_add_u32 s26, s34, 0xb0000
	s_addc_u32 s27, s35, 0
	s_mov_b32 m0, s41
	v_lshl_add_u64 v[226:227], s[26:27], 0, v[152:153]
	ds_read_b128 v[176:179], v193 offset:32768
	ds_read_b128 v[180:183], v193 offset:33792
	ds_read_b128 v[196:199], v193 offset:34816
	ds_read_b128 v[200:203], v193 offset:35840
	ds_read_b128 v[204:207], v193 offset:36864
	ds_read_b128 v[208:211], v193 offset:37888
	ds_read_b128 v[212:215], v193 offset:38912
	ds_read_b128 v[216:219], v193 offset:39936
	global_load_lds_dwordx4 v[226:227], off
	v_lshl_add_u64 v[226:227], s[26:27], 0, v[156:157]
	s_mov_b32 m0, s42
	s_nop 0
	global_load_lds_dwordx4 v[226:227], off
	s_waitcnt vmcnt(8) lgkmcnt(0)
	s_barrier
	s_setprio 1
	v_mfma_f32_16x16x32_bf16 v[124:127], v[128:131], v[176:179], v[124:127]
	v_mfma_f32_16x16x32_bf16 v[120:123], v[136:139], v[176:179], v[120:123]
	v_mfma_f32_16x16x32_bf16 v[108:111], v[128:131], v[196:199], v[108:111]
	v_mfma_f32_16x16x32_bf16 v[104:107], v[136:139], v[196:199], v[104:107]
	v_mfma_f32_16x16x32_bf16 v[92:95], v[128:131], v[204:207], v[92:95]
	v_mfma_f32_16x16x32_bf16 v[88:91], v[136:139], v[204:207], v[88:91]
	v_mfma_f32_16x16x32_bf16 v[76:79], v[128:131], v[212:215], v[76:79]
	v_mfma_f32_16x16x32_bf16 v[72:75], v[136:139], v[212:215], v[72:75]
	v_mfma_f32_16x16x32_bf16 v[124:127], v[132:135], v[180:183], v[124:127]
	v_mfma_f32_16x16x32_bf16 v[120:123], v[140:143], v[180:183], v[120:123]
	v_mfma_f32_16x16x32_bf16 v[108:111], v[132:135], v[200:203], v[108:111]
	v_mfma_f32_16x16x32_bf16 v[104:107], v[140:143], v[200:203], v[104:107]
	v_mfma_f32_16x16x32_bf16 v[92:95], v[132:135], v[208:211], v[92:95]
	v_mfma_f32_16x16x32_bf16 v[88:91], v[140:143], v[208:211], v[88:91]
	v_mfma_f32_16x16x32_bf16 v[76:79], v[132:135], v[216:219], v[76:79]
	v_mfma_f32_16x16x32_bf16 v[72:75], v[140:143], v[216:219], v[72:75]
	s_setprio 0
	s_setprio 1
	v_mfma_f32_16x16x32_bf16 v[116:119], v[144:147], v[176:179], v[116:119]
	v_mfma_f32_16x16x32_bf16 v[112:115], v[168:171], v[176:179], v[112:115]
	v_mfma_f32_16x16x32_bf16 v[100:103], v[144:147], v[196:199], v[100:103]
	v_mfma_f32_16x16x32_bf16 v[96:99], v[168:171], v[196:199], v[96:99]
	v_mfma_f32_16x16x32_bf16 v[84:87], v[144:147], v[204:207], v[84:87]
	v_mfma_f32_16x16x32_bf16 v[80:83], v[168:171], v[204:207], v[80:83]
	v_mfma_f32_16x16x32_bf16 v[68:71], v[144:147], v[212:215], v[68:71]
	v_mfma_f32_16x16x32_bf16 v[64:67], v[168:171], v[212:215], v[64:67]
	v_mfma_f32_16x16x32_bf16 v[116:119], v[148:151], v[180:183], v[116:119]
	v_mfma_f32_16x16x32_bf16 v[112:115], v[172:175], v[180:183], v[112:115]
	v_mfma_f32_16x16x32_bf16 v[100:103], v[148:151], v[200:203], v[100:103]
	v_mfma_f32_16x16x32_bf16 v[96:99], v[172:175], v[200:203], v[96:99]
	v_mfma_f32_16x16x32_bf16 v[84:87], v[148:151], v[208:211], v[84:87]
	v_mfma_f32_16x16x32_bf16 v[80:83], v[172:175], v[208:211], v[80:83]
	v_mfma_f32_16x16x32_bf16 v[68:71], v[148:151], v[216:219], v[68:71]
	v_mfma_f32_16x16x32_bf16 v[64:67], v[172:175], v[216:219], v[64:67]
	s_barrier
; #define PG8_STAGE(bufoff, gbase, voff) do { _Pragma("unroll") for (int _i = 0; _i < 2; ++_i) \
;         __builtin_amdgcn_global_load_lds((const unsigned*)((const char*)(gbase) + (voff)[_i]), (PG8_LAS unsigned*)(lds + (bufoff) + ldsw + _i * 8192), 16, 0, 0); } while (0)
; #define PG8_LDA(dst, b, h) do { _Pragma("unroll") for (int m = 0; m < 4; ++m) _Pragma("unroll") for (int k = 0; k < 2; ++k) dst[m][k] = *(const PG8_LAS bf16x8*)(lds + PG8_SA(b, h) + aoff + m * 2048 + k * 1024); } while (0)
; #define PG8_MMA(ai, bj, At, Bt) do { __builtin_amdgcn_s_setprio(1); _Pragma("unroll") for (int m = 0; m < 4; ++m) _Pragma("unroll") for (int n = 0; n < 2; ++n) _Pragma("unroll") for (int k = 0; k < 2; ++k) \
;         acc[ai][bj][m][n] = __builtin_amdgcn_mfma_f32_16x16x32_bf16(Bt[n][k], At[m][k], acc[ai][bj][m][n], 0, 0, 0); __builtin_amdgcn_s_setprio(0); } while (0)
; #define PG8_WAIT_V(n) asm volatile("s_waitcnt vmcnt(" #n ")" ::: "memory")
; #define PG8_WAIT_L(n) asm volatile("s_waitcnt lgkmcnt(" #n ")" ::: "memory")
; #define PG8_BAR __builtin_amdgcn_s_barrier()
; #define PG8_SCHED __builtin_amdgcn_sched_barrier(0)
; template <class Epi, class Sched, bool ALIGN_EPI = false, bool SP2 = false>
; __device__ __forceinline__ void gemm_phase(PG8_LAS unsigned char* lds, const Gemm g, const Sched& S, const Epi& E) {
;     ...
;             PG8_LDA(At, 1, 1); PG8_STAGE(PG8_SB(1, 0), b3, voffB); PG8_STAGE(PG8_SB(1, 1), b3 + hstepB, voffB); PG8_STAGE(PG8_SA(1, 0), a3, voffA);
;             PG8_WAIT_V(8); PG8_WAIT_L(0); PG8_BAR; PG8_MMA(1, 0, At, B0); PG8_MMA(1, 1, At, B1); PG8_BAR; PG8_SCHED;
;     ...
;         if constexpr (ALIGN_EPI) { if (wr == 0) PG8_BAR; }
	s_setprio 0
	s_add_i32 s26, s58, s38
	v_lshl_add_u64 v[184:185], v[184:185], 0, s[14:15]
	s_mov_b32 m0, s26
	ds_read_b128 v[176:179], v193 offset:49152
	ds_read_b128 v[180:183], v193 offset:50176
	ds_read_b128 v[196:199], v193 offset:51200
	ds_read_b128 v[200:203], v193 offset:52224
	ds_read_b128 v[204:207], v193 offset:53248
	ds_read_b128 v[208:211], v193 offset:54272
	ds_read_b128 v[212:215], v193 offset:55296
	ds_read_b128 v[216:219], v193 offset:56320
	global_load_lds_dwordx4 v[184:185], off
	s_add_i32 m0, s26, 0x2000
	s_add_u32 s26, s30, 0xb0080
	v_lshl_add_u64 v[184:185], v[220:221], 0, s[14:15]
	s_addc_u32 s27, s31, 0
	s_add_i32 s30, s59, s38
	global_load_lds_dwordx4 v[184:185], off
	v_lshl_add_u64 v[184:185], s[26:27], 0, v[154:155]
	s_mov_b32 m0, s30
	s_nop 0
	global_load_lds_dwordx4 v[184:185], off
	v_lshl_add_u64 v[184:185], s[26:27], 0, v[158:159]
	s_add_i32 m0, s30, 0x2000
	s_nop 0
	global_load_lds_dwordx4 v[184:185], off
	v_lshl_add_u64 v[184:185], v[222:223], 0, s[14:15]
	s_mov_b32 m0, s44
	s_nop 0
	global_load_lds_dwordx4 v[184:185], off
	v_lshl_add_u64 v[184:185], v[224:225], 0, s[14:15]
	s_mov_b32 m0, s45
	s_nop 0
	global_load_lds_dwordx4 v[184:185], off
	s_waitcnt vmcnt(8) lgkmcnt(0)
	s_barrier
	s_setprio 1
	v_mfma_f32_16x16x32_bf16 v[60:63], v[128:131], v[176:179], v[60:63]
	v_mfma_f32_16x16x32_bf16 v[56:59], v[136:139], v[176:179], v[56:59]
	v_mfma_f32_16x16x32_bf16 v[44:47], v[128:131], v[196:199], v[44:47]
	v_mfma_f32_16x16x32_bf16 v[40:43], v[136:139], v[196:199], v[40:43]
	v_mfma_f32_16x16x32_bf16 v[28:31], v[128:131], v[204:207], v[28:31]
	v_mfma_f32_16x16x32_bf16 v[24:27], v[136:139], v[204:207], v[24:27]
	v_mfma_f32_16x16x32_bf16 v[12:15], v[128:131], v[212:215], v[12:15]
	v_mfma_f32_16x16x32_bf16 v[8:11], v[136:139], v[212:215], v[8:11]
	v_mfma_f32_16x16x32_bf16 v[60:63], v[132:135], v[180:183], v[60:63]
	v_mfma_f32_16x16x32_bf16 v[56:59], v[140:143], v[180:183], v[56:59]
	v_mfma_f32_16x16x32_bf16 v[44:47], v[132:135], v[200:203], v[44:47]
	v_mfma_f32_16x16x32_bf16 v[40:43], v[140:143], v[200:203], v[40:43]
	v_mfma_f32_16x16x32_bf16 v[28:31], v[132:135], v[208:211], v[28:31]
	v_mfma_f32_16x16x32_bf16 v[24:27], v[140:143], v[208:211], v[24:27]
	v_mfma_f32_16x16x32_bf16 v[12:15], v[132:135], v[216:219], v[12:15]
	v_mfma_f32_16x16x32_bf16 v[8:11], v[140:143], v[216:219], v[8:11]
	s_setprio 0
	s_setprio 1
	v_mfma_f32_16x16x32_bf16 v[52:55], v[144:147], v[176:179], v[52:55]
	v_mfma_f32_16x16x32_bf16 v[48:51], v[168:171], v[176:179], v[48:51]
	v_mfma_f32_16x16x32_bf16 v[36:39], v[144:147], v[196:199], v[36:39]
	v_mfma_f32_16x16x32_bf16 v[32:35], v[168:171], v[196:199], v[32:35]
	v_mfma_f32_16x16x32_bf16 v[20:23], v[144:147], v[204:207], v[20:23]
	v_mfma_f32_16x16x32_bf16 v[16:19], v[168:171], v[204:207], v[16:19]
	v_mfma_f32_16x16x32_bf16 v[4:7], v[144:147], v[212:215], v[4:7]
	v_mfma_f32_16x16x32_bf16 v[0:3], v[168:171], v[212:215], v[0:3]
	v_mfma_f32_16x16x32_bf16 v[52:55], v[148:151], v[180:183], v[52:55]
	v_mfma_f32_16x16x32_bf16 v[48:51], v[172:175], v[180:183], v[48:51]
	v_mfma_f32_16x16x32_bf16 v[36:39], v[148:151], v[200:203], v[36:39]
	v_mfma_f32_16x16x32_bf16 v[32:35], v[172:175], v[200:203], v[32:35]
	v_mfma_f32_16x16x32_bf16 v[20:23], v[148:151], v[208:211], v[20:23]
	v_mfma_f32_16x16x32_bf16 v[16:19], v[172:175], v[208:211], v[16:19]
	v_mfma_f32_16x16x32_bf16 v[4:7], v[148:151], v[216:219], v[4:7]
	v_mfma_f32_16x16x32_bf16 v[0:3], v[172:175], v[216:219], v[0:3]
	s_barrier
	s_setprio 0
	s_add_i32 s72, s72, 2
	s_add_u32 s70, s70, 0x100
	s_addc_u32 s71, s71, 0
	s_cmp_gt_u32 s72, 41
	s_mov_b64 s[26:27], s[28:29]
	s_cbranch_scc0 .LBB0_318
	s_and_b64 vcc, exec, s[20:21]
	s_cbranch_vccz .LBB0_321
	s_barrier

; #define PG8_STAGE(bufoff, gbase, voff) do { _Pragma("unroll") for (int _i = 0; _i < 2; ++_i) \
;         __builtin_amdgcn_global_load_lds((const unsigned*)((const char*)(gbase) + (voff)[_i]), (PG8_LAS unsigned*)(lds + (bufoff) + ldsw + _i * 8192), 16, 0, 0); } while (0)
; #define PG8_LDA(dst, b, h) do { _Pragma("unroll") for (int m = 0; m < 4; ++m) _Pragma("unroll") for (int k = 0; k < 2; ++k) dst[m][k] = *(const PG8_LAS bf16x8*)(lds + PG8_SA(b, h) + aoff + m * 2048 + k * 1024); } while (0)
; #define PG8_LDB(dst, b, h) do { _Pragma("unroll") for (int n = 0; n < 2; ++n) _Pragma("unroll") for (int k = 0; k < 2; ++k) dst[n][k] = *(const PG8_LAS bf16x8*)(lds + PG8_SB(b, h) + boff + n * 2048 + k * 1024); } while (0)
; #define PG8_MMA(ai, bj, At, Bt) do { __builtin_amdgcn_s_setprio(1); _Pragma("unroll") for (int m = 0; m < 4; ++m) _Pragma("unroll") for (int n = 0; n < 2; ++n) _Pragma("unroll") for (int k = 0; k < 2; ++k) \
;         acc[ai][bj][m][n] = __builtin_amdgcn_mfma_f32_16x16x32_bf16(Bt[n][k], At[m][k], acc[ai][bj][m][n], 0, 0, 0); __builtin_amdgcn_s_setprio(0); } while (0)
; #define PG8_WAIT_V(n) asm volatile("s_waitcnt vmcnt(" #n ")" ::: "memory")
; #define PG8_BAR __builtin_amdgcn_s_barrier()
; template <class Epi, class Sched, bool ALIGN_EPI = false, bool SP2 = false>
; __device__ __forceinline__ void gemm_phase(PG8_LAS unsigned char* lds, const Gemm g, const Sched& S, const Epi& E) {
;     ...
;         for (int t = 0; t < nt; t += 2) {
;             const bool last = (t == nt - 2);
;             const char* a1 = cA + (size_t)(t + 1) * kstep;
;             const char* a2 = last ? nA : cA + (size_t)(t + 2) * kstep; const char* b2 = last ? nB : cB + (size_t)(t + 2) * kstep;
;             const char* a3 = a2 + kstep; const char* b3 = b2 + kstep;
;             if (last && has_next) S.a_ready(nxt);
;             if constexpr (SP2) {
;             PG8_LDB(B0, 0, 0); PG8_LDB(B1, 0, 1); PG8_SCHED; PG8_LDA(At, 0, 0); PG8_STAGE(PG8_SA(1, 1), a1 + hstepA, voffA);
;             PG8_WAIT_V(8); PG8_WAIT_L(0); PG8_BAR; PG8_MMA(0, 0, At, B0); PG8_MMA(0, 1, At, B1); PG8_BAR; PG8_SCHED;
;             PG8_LDA(At, 0, 1); PG8_STAGE(PG8_SB(0, 0), b2, voffB); PG8_STAGE(PG8_SB(0, 1), b2 + hstepB, voffB); PG8_STAGE(PG8_SA(0, 0), a2, voffA);
;             PG8_WAIT_V(8); PG8_WAIT_L(0); PG8_BAR; PG8_MMA(1, 0, At, B0); PG8_MMA(1, 1, At, B1); PG8_BAR; PG8_SCHED;
.LBB0_404:
	ds_read_b128 v[152:155], v165
	ds_read_b128 v[156:159], v165 offset:1024
	ds_read_b128 v[178:181], v165 offset:2048
	ds_read_b128 v[182:185], v165 offset:3072
	ds_read_b128 v[188:191], v166
	ds_read_b128 v[192:195], v166 offset:1024
	ds_read_b128 v[196:199], v166 offset:2048
	ds_read_b128 v[200:203], v166 offset:3072
	s_add_u32 s46, s14, 0xfffc0080
	s_addc_u32 s47, s15, -1
	s_cmp_eq_u32 s91, 12
	s_cselect_b32 s49, s11, s47
	s_cselect_b32 s48, s13, s46
	s_cselect_b32 s47, s39, s67
	s_cselect_b32 s46, s41, s66
	v_lshl_add_u64 v[160:161], s[14:15], 0, v[144:145]
	s_add_i32 m0, s71, 0xc000
	ds_read_b128 v[204:207], v167
	ds_read_b128 v[208:211], v167 offset:1024
	ds_read_b128 v[212:215], v167 offset:2048
	ds_read_b128 v[216:219], v167 offset:3072
	ds_read_b128 v[220:223], v167 offset:4096
	ds_read_b128 v[224:227], v167 offset:5120
	ds_read_b128 v[228:231], v167 offset:6144
	ds_read_b128 v[232:235], v167 offset:7168
	global_load_lds_dwordx4 v[160:161], off
	v_lshl_add_u64 v[160:161], s[14:15], 0, v[146:147]
	s_add_i32 m0, s71, 0xe000
	s_nop 0
	global_load_lds_dwordx4 v[160:161], off
	s_waitcnt vmcnt(8) lgkmcnt(0)
	s_barrier
	s_setprio 1
	v_mfma_f32_16x16x32_bf16 v[124:127], v[152:155], v[204:207], v[124:127]
	v_mfma_f32_16x16x32_bf16 v[120:123], v[178:181], v[204:207], v[120:123]
	v_mfma_f32_16x16x32_bf16 v[108:111], v[152:155], v[212:215], v[108:111]
	v_mfma_f32_16x16x32_bf16 v[104:107], v[178:181], v[212:215], v[104:107]
	v_mfma_f32_16x16x32_bf16 v[92:95], v[152:155], v[220:223], v[92:95]
	v_mfma_f32_16x16x32_bf16 v[88:91], v[178:181], v[220:223], v[88:91]
	v_mfma_f32_16x16x32_bf16 v[76:79], v[152:155], v[228:231], v[76:79]
	v_mfma_f32_16x16x32_bf16 v[72:75], v[178:181], v[228:231], v[72:75]
	v_mfma_f32_16x16x32_bf16 v[124:127], v[156:159], v[208:211], v[124:127]
	v_mfma_f32_16x16x32_bf16 v[120:123], v[182:185], v[208:211], v[120:123]
	v_mfma_f32_16x16x32_bf16 v[108:111], v[156:159], v[216:219], v[108:111]
	v_mfma_f32_16x16x32_bf16 v[104:107], v[182:185], v[216:219], v[104:107]
	v_mfma_f32_16x16x32_bf16 v[92:95], v[156:159], v[224:227], v[92:95]
	v_mfma_f32_16x16x32_bf16 v[88:91], v[182:185], v[224:227], v[88:91]
	v_mfma_f32_16x16x32_bf16 v[76:79], v[156:159], v[232:235], v[76:79]
	v_mfma_f32_16x16x32_bf16 v[72:75], v[182:185], v[232:235], v[72:75]
	s_setprio 0
	s_setprio 1
	v_mfma_f32_16x16x32_bf16 v[116:119], v[188:191], v[204:207], v[116:119]
	v_mfma_f32_16x16x32_bf16 v[112:115], v[196:199], v[204:207], v[112:115]
	v_mfma_f32_16x16x32_bf16 v[100:103], v[188:191], v[212:215], v[100:103]
	v_mfma_f32_16x16x32_bf16 v[96:99], v[196:199], v[212:215], v[96:99]
	v_mfma_f32_16x16x32_bf16 v[84:87], v[188:191], v[220:223], v[84:87]
	v_mfma_f32_16x16x32_bf16 v[80:83], v[196:199], v[220:223], v[80:83]
	v_mfma_f32_16x16x32_bf16 v[68:71], v[188:191], v[228:231], v[68:71]
	v_mfma_f32_16x16x32_bf16 v[64:67], v[196:199], v[228:231], v[64:67]
	v_mfma_f32_16x16x32_bf16 v[116:119], v[192:195], v[208:211], v[116:119]
	v_mfma_f32_16x16x32_bf16 v[112:115], v[200:203], v[208:211], v[112:115]
	v_mfma_f32_16x16x32_bf16 v[100:103], v[192:195], v[216:219], v[100:103]
	v_mfma_f32_16x16x32_bf16 v[96:99], v[200:203], v[216:219], v[96:99]
	v_mfma_f32_16x16x32_bf16 v[84:87], v[192:195], v[224:227], v[84:87]
	v_mfma_f32_16x16x32_bf16 v[80:83], v[200:203], v[224:227], v[80:83]
	v_mfma_f32_16x16x32_bf16 v[68:71], v[192:195], v[232:235], v[68:71]
	v_mfma_f32_16x16x32_bf16 v[64:67], v[200:203], v[232:235], v[64:67]
	s_barrier
	s_setprio 0
	s_add_i32 s58, s83, s70
	v_lshl_add_u64 v[160:161], s[46:47], 0, v[130:131]
	s_mov_b32 m0, s58
	ds_read_b128 v[204:207], v167 offset:16384
	ds_read_b128 v[208:211], v167 offset:17408
	ds_read_b128 v[212:215], v167 offset:18432
	ds_read_b128 v[216:219], v167 offset:19456
	ds_read_b128 v[220:223], v167 offset:20480
	ds_read_b128 v[224:227], v167 offset:21504
	ds_read_b128 v[228:231], v167 offset:22528
	ds_read_b128 v[232:235], v167 offset:23552
	global_load_lds_dwordx4 v[160:161], off
	s_add_i32 m0, s58, 0x2000
	s_add_u32 s58, s46, 0x40000
	v_lshl_add_u64 v[236:237], s[46:47], 0, v[134:135]
	s_addc_u32 s59, s47, 0
	s_add_i32 s92, s84, s70
	global_load_lds_dwordx4 v[236:237], off
	v_lshl_add_u64 v[238:239], s[58:59], 0, v[130:131]
	s_mov_b32 m0, s92
	v_lshl_add_u64 v[240:241], s[48:49], 0, v[132:133]
	global_load_lds_dwordx4 v[238:239], off
	v_lshl_add_u64 v[238:239], s[58:59], 0, v[134:135]
	s_add_i32 m0, s92, 0x2000
	s_nop 0
	global_load_lds_dwordx4 v[238:239], off
	v_lshl_add_u64 v[238:239], s[48:49], 0, v[128:129]
	s_mov_b32 m0, s71
	s_nop 0
	global_load_lds_dwordx4 v[238:239], off
	s_mov_b32 m0, s72
	s_nop 0
	global_load_lds_dwordx4 v[240:241], off
	s_waitcnt vmcnt(8) lgkmcnt(0)
	s_barrier
; #define PG8_STAGE(bufoff, gbase, voff) do { _Pragma("unroll") for (int _i = 0; _i < 2; ++_i) \
;         __builtin_amdgcn_global_load_lds((const unsigned*)((const char*)(gbase) + (voff)[_i]), (PG8_LAS unsigned*)(lds + (bufoff) + ldsw + _i * 8192), 16, 0, 0); } while (0)
; #define PG8_LDA(dst, b, h) do { _Pragma("unroll") for (int m = 0; m < 4; ++m) _Pragma("unroll") for (int k = 0; k < 2; ++k) dst[m][k] = *(const PG8_LAS bf16x8*)(lds + PG8_SA(b, h) + aoff + m * 2048 + k * 1024); } while (0)
; #define PG8_LDB(dst, b, h) do { _Pragma("unroll") for (int n = 0; n < 2; ++n) _Pragma("unroll") for (int k = 0; k < 2; ++k) dst[n][k] = *(const PG8_LAS bf16x8*)(lds + PG8_SB(b, h) + boff + n * 2048 + k * 1024); } while (0)
; #define PG8_MMA(ai, bj, At, Bt) do { __builtin_amdgcn_s_setprio(1); _Pragma("unroll") for (int m = 0; m < 4; ++m) _Pragma("unroll") for (int n = 0; n < 2; ++n) _Pragma("unroll") for (int k = 0; k < 2; ++k) \
;         acc[ai][bj][m][n] = __builtin_amdgcn_mfma_f32_16x16x32_bf16(Bt[n][k], At[m][k], acc[ai][bj][m][n], 0, 0, 0); __builtin_amdgcn_s_setprio(0); } while (0)
; #define PG8_WAIT_V(n) asm volatile("s_waitcnt vmcnt(" #n ")" ::: "memory")
; #define PG8_WAIT_L(n) asm volatile("s_waitcnt lgkmcnt(" #n ")" ::: "memory")
; #define PG8_BAR __builtin_amdgcn_s_barrier()
; #define PG8_SCHED __builtin_amdgcn_sched_barrier(0)
; template <class Epi, class Sched, bool ALIGN_EPI = false, bool SP2 = false>
; __device__ __forceinline__ void gemm_phase(PG8_LAS unsigned char* lds, const Gemm g, const Sched& S, const Epi& E) {
;     ...
;             PG8_WAIT_V(8); PG8_WAIT_L(0); PG8_BAR; PG8_MMA(1, 0, At, B0); PG8_MMA(1, 1, At, B1); PG8_BAR; PG8_SCHED;
;             PG8_LDB(B0, 1, 0); PG8_LDB(B1, 1, 1); PG8_SCHED; PG8_LDA(At, 1, 0); PG8_STAGE(PG8_SA(0, 1), a2 + hstepA, voffA);
;             PG8_WAIT_V(8); PG8_WAIT_L(0); PG8_BAR; PG8_MMA(0, 0, At, B0); PG8_MMA(0, 1, At, B1); PG8_BAR; PG8_SCHED;
	s_setprio 1
	v_mfma_f32_16x16x32_bf16 v[60:63], v[152:155], v[204:207], v[60:63]
	v_mfma_f32_16x16x32_bf16 v[56:59], v[178:181], v[204:207], v[56:59]
	v_mfma_f32_16x16x32_bf16 v[44:47], v[152:155], v[212:215], v[44:47]
	v_mfma_f32_16x16x32_bf16 v[40:43], v[178:181], v[212:215], v[40:43]
	v_mfma_f32_16x16x32_bf16 v[28:31], v[152:155], v[220:223], v[28:31]
	v_mfma_f32_16x16x32_bf16 v[24:27], v[178:181], v[220:223], v[24:27]
	v_mfma_f32_16x16x32_bf16 v[12:15], v[152:155], v[228:231], v[12:15]
	v_mfma_f32_16x16x32_bf16 v[8:11], v[178:181], v[228:231], v[8:11]
	v_mfma_f32_16x16x32_bf16 v[60:63], v[156:159], v[208:211], v[60:63]
	v_mfma_f32_16x16x32_bf16 v[56:59], v[182:185], v[208:211], v[56:59]
	v_mfma_f32_16x16x32_bf16 v[44:47], v[156:159], v[216:219], v[44:47]
	v_mfma_f32_16x16x32_bf16 v[40:43], v[182:185], v[216:219], v[40:43]
	v_mfma_f32_16x16x32_bf16 v[28:31], v[156:159], v[224:227], v[28:31]
	v_mfma_f32_16x16x32_bf16 v[24:27], v[182:185], v[224:227], v[24:27]
	v_mfma_f32_16x16x32_bf16 v[12:15], v[156:159], v[232:235], v[12:15]
	v_mfma_f32_16x16x32_bf16 v[8:11], v[182:185], v[232:235], v[8:11]
	s_setprio 0
	s_setprio 1
	v_mfma_f32_16x16x32_bf16 v[52:55], v[188:191], v[204:207], v[52:55]
	v_mfma_f32_16x16x32_bf16 v[48:51], v[196:199], v[204:207], v[48:51]
	v_mfma_f32_16x16x32_bf16 v[36:39], v[188:191], v[212:215], v[36:39]
	v_mfma_f32_16x16x32_bf16 v[32:35], v[196:199], v[212:215], v[32:35]
	v_mfma_f32_16x16x32_bf16 v[20:23], v[188:191], v[220:223], v[20:23]
	v_mfma_f32_16x16x32_bf16 v[16:19], v[196:199], v[220:223], v[16:19]
	v_mfma_f32_16x16x32_bf16 v[4:7], v[188:191], v[228:231], v[4:7]
	v_mfma_f32_16x16x32_bf16 v[0:3], v[196:199], v[228:231], v[0:3]
	v_mfma_f32_16x16x32_bf16 v[52:55], v[192:195], v[208:211], v[52:55]
	v_mfma_f32_16x16x32_bf16 v[48:51], v[200:203], v[208:211], v[48:51]
	v_mfma_f32_16x16x32_bf16 v[36:39], v[192:195], v[216:219], v[36:39]
	v_mfma_f32_16x16x32_bf16 v[32:35], v[200:203], v[216:219], v[32:35]
	v_mfma_f32_16x16x32_bf16 v[20:23], v[192:195], v[224:227], v[20:23]
	v_mfma_f32_16x16x32_bf16 v[16:19], v[200:203], v[224:227], v[16:19]
	v_mfma_f32_16x16x32_bf16 v[4:7], v[192:195], v[232:235], v[4:7]
	v_mfma_f32_16x16x32_bf16 v[0:3], v[200:203], v[232:235], v[0:3]
	s_barrier
	s_setprio 0
	s_add_i32 s58, 0, 0x18000
	v_add_u32_e32 v136, s58, v163
	s_add_i32 s59, 0, 0x1c000
	ds_read_b128 v[152:155], v136
	ds_read_b128 v[156:159], v136 offset:1024
	ds_read_b128 v[178:181], v136 offset:2048
	ds_read_b128 v[182:185], v136 offset:3072
	v_add_u32_e32 v136, s59, v163
	ds_read_b128 v[188:191], v136
	ds_read_b128 v[192:195], v136 offset:1024
	ds_read_b128 v[196:199], v136 offset:2048
	ds_read_b128 v[200:203], v136 offset:3072
	s_add_u32 s48, s48, 0x40000
	s_addc_u32 s49, s49, 0
	s_mov_b32 m0, s73
	v_lshl_add_u64 v[242:243], s[48:49], 0, v[128:129]
	ds_read_b128 v[204:207], v167 offset:32768
	ds_read_b128 v[208:211], v167 offset:33792
	ds_read_b128 v[212:215], v167 offset:34816
	ds_read_b128 v[216:219], v167 offset:35840
	ds_read_b128 v[220:223], v167 offset:36864
	ds_read_b128 v[224:227], v167 offset:37888
	ds_read_b128 v[228:231], v167 offset:38912
	ds_read_b128 v[232:235], v167 offset:39936
	global_load_lds_dwordx4 v[242:243], off
	v_lshl_add_u64 v[242:243], s[48:49], 0, v[132:133]
	s_mov_b32 m0, s74
	s_nop 0
	global_load_lds_dwordx4 v[242:243], off
	s_waitcnt vmcnt(8) lgkmcnt(0)
	s_barrier
	s_setprio 1
	v_mfma_f32_16x16x32_bf16 v[124:127], v[152:155], v[204:207], v[124:127]
	v_mfma_f32_16x16x32_bf16 v[120:123], v[178:181], v[204:207], v[120:123]
	v_mfma_f32_16x16x32_bf16 v[108:111], v[152:155], v[212:215], v[108:111]
	v_mfma_f32_16x16x32_bf16 v[104:107], v[178:181], v[212:215], v[104:107]
	v_mfma_f32_16x16x32_bf16 v[92:95], v[152:155], v[220:223], v[92:95]
	v_mfma_f32_16x16x32_bf16 v[88:91], v[178:181], v[220:223], v[88:91]
	v_mfma_f32_16x16x32_bf16 v[76:79], v[152:155], v[228:231], v[76:79]
	v_mfma_f32_16x16x32_bf16 v[72:75], v[178:181], v[228:231], v[72:75]
	v_mfma_f32_16x16x32_bf16 v[124:127], v[156:159], v[208:211], v[124:127]
	v_mfma_f32_16x16x32_bf16 v[120:123], v[182:185], v[208:211], v[120:123]
	v_mfma_f32_16x16x32_bf16 v[108:111], v[156:159], v[216:219], v[108:111]
	v_mfma_f32_16x16x32_bf16 v[104:107], v[182:185], v[216:219], v[104:107]
	v_mfma_f32_16x16x32_bf16 v[92:95], v[156:159], v[224:227], v[92:95]
	v_mfma_f32_16x16x32_bf16 v[88:91], v[182:185], v[224:227], v[88:91]
	v_mfma_f32_16x16x32_bf16 v[76:79], v[156:159], v[232:235], v[76:79]
	v_mfma_f32_16x16x32_bf16 v[72:75], v[182:185], v[232:235], v[72:75]
	s_setprio 0
	s_setprio 1
	v_mfma_f32_16x16x32_bf16 v[116:119], v[188:191], v[204:207], v[116:119]
	v_mfma_f32_16x16x32_bf16 v[112:115], v[196:199], v[204:207], v[112:115]
	v_mfma_f32_16x16x32_bf16 v[100:103], v[188:191], v[212:215], v[100:103]
	v_mfma_f32_16x16x32_bf16 v[96:99], v[196:199], v[212:215], v[96:99]
	v_mfma_f32_16x16x32_bf16 v[84:87], v[188:191], v[220:223], v[84:87]
	v_mfma_f32_16x16x32_bf16 v[80:83], v[196:199], v[220:223], v[80:83]
	v_mfma_f32_16x16x32_bf16 v[68:71], v[188:191], v[228:231], v[68:71]
	v_mfma_f32_16x16x32_bf16 v[64:67], v[196:199], v[228:231], v[64:67]
	v_mfma_f32_16x16x32_bf16 v[116:119], v[192:195], v[208:211], v[116:119]
	v_mfma_f32_16x16x32_bf16 v[112:115], v[200:203], v[208:211], v[112:115]
	v_mfma_f32_16x16x32_bf16 v[100:103], v[192:195], v[216:219], v[100:103]
	v_mfma_f32_16x16x32_bf16 v[96:99], v[200:203], v[216:219], v[96:99]
	v_mfma_f32_16x16x32_bf16 v[84:87], v[192:195], v[224:227], v[84:87]
	v_mfma_f32_16x16x32_bf16 v[80:83], v[200:203], v[224:227], v[80:83]
	v_mfma_f32_16x16x32_bf16 v[68:71], v[192:195], v[232:235], v[68:71]
	v_mfma_f32_16x16x32_bf16 v[64:67], v[200:203], v[232:235], v[64:67]
	s_barrier
; #define PG8_STAGE(bufoff, gbase, voff) do { _Pragma("unroll") for (int _i = 0; _i < 2; ++_i) \
;         __builtin_amdgcn_global_load_lds((const unsigned*)((const char*)(gbase) + (voff)[_i]), (PG8_LAS unsigned*)(lds + (bufoff) + ldsw + _i * 8192), 16, 0, 0); } while (0)
; #define PG8_LDA(dst, b, h) do { _Pragma("unroll") for (int m = 0; m < 4; ++m) _Pragma("unroll") for (int k = 0; k < 2; ++k) dst[m][k] = *(const PG8_LAS bf16x8*)(lds + PG8_SA(b, h) + aoff + m * 2048 + k * 1024); } while (0)
; #define PG8_MMA(ai, bj, At, Bt) do { __builtin_amdgcn_s_setprio(1); _Pragma("unroll") for (int m = 0; m < 4; ++m) _Pragma("unroll") for (int n = 0; n < 2; ++n) _Pragma("unroll") for (int k = 0; k < 2; ++k) \
;         acc[ai][bj][m][n] = __builtin_amdgcn_mfma_f32_16x16x32_bf16(Bt[n][k], At[m][k], acc[ai][bj][m][n], 0, 0, 0); __builtin_amdgcn_s_setprio(0); } while (0)
; #define PG8_WAIT_V(n) asm volatile("s_waitcnt vmcnt(" #n ")" ::: "memory")
; #define PG8_WAIT_L(n) asm volatile("s_waitcnt lgkmcnt(" #n ")" ::: "memory")
; #define PG8_BAR __builtin_amdgcn_s_barrier()
; #define PG8_SCHED __builtin_amdgcn_sched_barrier(0)
; template <class Epi, class Sched, bool ALIGN_EPI = false, bool SP2 = false>
; __device__ __forceinline__ void gemm_phase(PG8_LAS unsigned char* lds, const Gemm g, const Sched& S, const Epi& E) {
;     ...
;             PG8_LDA(At, 1, 1); PG8_STAGE(PG8_SB(1, 0), b3, voffB); PG8_STAGE(PG8_SB(1, 1), b3 + hstepB, voffB); PG8_STAGE(PG8_SA(1, 0), a3, voffA);
;             PG8_WAIT_V(8); PG8_WAIT_L(0); PG8_BAR; PG8_MMA(1, 0, At, B0); PG8_MMA(1, 1, At, B1); PG8_BAR; PG8_SCHED;
;     ...
;         if constexpr (ALIGN_EPI) { if (wr == 0) PG8_BAR; }
	s_setprio 0
	s_add_i32 s48, s58, s70
	v_lshl_add_u64 v[160:161], v[160:161], 0, s[30:31]
	s_mov_b32 m0, s48
	ds_read_b128 v[204:207], v167 offset:49152
	ds_read_b128 v[208:211], v167 offset:50176
	ds_read_b128 v[212:215], v167 offset:51200
	ds_read_b128 v[216:219], v167 offset:52224
	ds_read_b128 v[220:223], v167 offset:53248
	ds_read_b128 v[224:227], v167 offset:54272
	ds_read_b128 v[228:231], v167 offset:55296
	ds_read_b128 v[232:235], v167 offset:56320
	global_load_lds_dwordx4 v[160:161], off
	s_add_i32 m0, s48, 0x2000
	s_add_u32 s46, s46, 0x40080
	v_lshl_add_u64 v[160:161], v[236:237], 0, s[30:31]
	s_addc_u32 s47, s47, 0
	s_add_i32 s48, s59, s70
	global_load_lds_dwordx4 v[160:161], off
	v_lshl_add_u64 v[160:161], s[46:47], 0, v[130:131]
	s_mov_b32 m0, s48
	s_nop 0
	global_load_lds_dwordx4 v[160:161], off
	v_lshl_add_u64 v[160:161], s[46:47], 0, v[134:135]
	s_add_i32 m0, s48, 0x2000
	s_nop 0
	global_load_lds_dwordx4 v[160:161], off
	v_lshl_add_u64 v[160:161], v[238:239], 0, s[30:31]
	s_mov_b32 m0, s76
	s_nop 0
	global_load_lds_dwordx4 v[160:161], off
	v_lshl_add_u64 v[160:161], v[240:241], 0, s[30:31]
	s_mov_b32 m0, s77
	s_nop 0
	global_load_lds_dwordx4 v[160:161], off
	s_waitcnt vmcnt(8) lgkmcnt(0)
	s_barrier
	s_setprio 1
	v_mfma_f32_16x16x32_bf16 v[60:63], v[152:155], v[204:207], v[60:63]
	v_mfma_f32_16x16x32_bf16 v[56:59], v[178:181], v[204:207], v[56:59]
	v_mfma_f32_16x16x32_bf16 v[44:47], v[152:155], v[212:215], v[44:47]
	v_mfma_f32_16x16x32_bf16 v[40:43], v[178:181], v[212:215], v[40:43]
	v_mfma_f32_16x16x32_bf16 v[28:31], v[152:155], v[220:223], v[28:31]
	v_mfma_f32_16x16x32_bf16 v[24:27], v[178:181], v[220:223], v[24:27]
	v_mfma_f32_16x16x32_bf16 v[12:15], v[152:155], v[228:231], v[12:15]
	v_mfma_f32_16x16x32_bf16 v[8:11], v[178:181], v[228:231], v[8:11]
	v_mfma_f32_16x16x32_bf16 v[60:63], v[156:159], v[208:211], v[60:63]
	v_mfma_f32_16x16x32_bf16 v[56:59], v[182:185], v[208:211], v[56:59]
	v_mfma_f32_16x16x32_bf16 v[44:47], v[156:159], v[216:219], v[44:47]
	v_mfma_f32_16x16x32_bf16 v[40:43], v[182:185], v[216:219], v[40:43]
	v_mfma_f32_16x16x32_bf16 v[28:31], v[156:159], v[224:227], v[28:31]
	v_mfma_f32_16x16x32_bf16 v[24:27], v[182:185], v[224:227], v[24:27]
	v_mfma_f32_16x16x32_bf16 v[12:15], v[156:159], v[232:235], v[12:15]
	v_mfma_f32_16x16x32_bf16 v[8:11], v[182:185], v[232:235], v[8:11]
	s_setprio 0
	s_setprio 1
	v_mfma_f32_16x16x32_bf16 v[52:55], v[188:191], v[204:207], v[52:55]
	v_mfma_f32_16x16x32_bf16 v[48:51], v[196:199], v[204:207], v[48:51]
	v_mfma_f32_16x16x32_bf16 v[36:39], v[188:191], v[212:215], v[36:39]
	v_mfma_f32_16x16x32_bf16 v[32:35], v[196:199], v[212:215], v[32:35]
	v_mfma_f32_16x16x32_bf16 v[20:23], v[188:191], v[220:223], v[20:23]
	v_mfma_f32_16x16x32_bf16 v[16:19], v[196:199], v[220:223], v[16:19]
	v_mfma_f32_16x16x32_bf16 v[4:7], v[188:191], v[228:231], v[4:7]
	v_mfma_f32_16x16x32_bf16 v[0:3], v[196:199], v[228:231], v[0:3]
	v_mfma_f32_16x16x32_bf16 v[52:55], v[192:195], v[208:211], v[52:55]
	v_mfma_f32_16x16x32_bf16 v[48:51], v[200:203], v[208:211], v[48:51]
	v_mfma_f32_16x16x32_bf16 v[36:39], v[192:195], v[216:219], v[36:39]
	v_mfma_f32_16x16x32_bf16 v[32:35], v[200:203], v[216:219], v[32:35]
	v_mfma_f32_16x16x32_bf16 v[20:23], v[192:195], v[224:227], v[20:23]
	v_mfma_f32_16x16x32_bf16 v[16:19], v[200:203], v[224:227], v[16:19]
	v_mfma_f32_16x16x32_bf16 v[4:7], v[192:195], v[232:235], v[4:7]
	v_mfma_f32_16x16x32_bf16 v[0:3], v[200:203], v[232:235], v[0:3]
	s_barrier
	s_setprio 0
	s_add_i32 s91, s91, 2
	s_add_u32 s14, s14, 0x100
	s_addc_u32 s15, s15, 0
	s_add_u32 s66, s66, 0x100
	s_addc_u32 s67, s67, 0
	s_cmp_gt_u32 s91, 13
	s_cbranch_scc0 .LBB0_404
	s_and_b64 vcc, exec, s[34:35]
	s_cbranch_vccz .LBB0_407
	s_barrier

; #define PG8_STAGE(bufoff, gbase, voff) do { _Pragma("unroll") for (int _i = 0; _i < 2; ++_i) \
;         __builtin_amdgcn_global_load_lds((const unsigned*)((const char*)(gbase) + (voff)[_i]), (PG8_LAS unsigned*)(lds + (bufoff) + ldsw + _i * 8192), 16, 0, 0); } while (0)
; #define PG8_LDA(dst, b, h) do { _Pragma("unroll") for (int m = 0; m < 4; ++m) _Pragma("unroll") for (int k = 0; k < 2; ++k) dst[m][k] = *(const PG8_LAS bf16x8*)(lds + PG8_SA(b, h) + aoff + m * 2048 + k * 1024); } while (0)
; #define PG8_LDB(dst, b, h) do { _Pragma("unroll") for (int n = 0; n < 2; ++n) _Pragma("unroll") for (int k = 0; k < 2; ++k) dst[n][k] = *(const PG8_LAS bf16x8*)(lds + PG8_SB(b, h) + boff + n * 2048 + k * 1024); } while (0)
; #define PG8_MMA(ai, bj, At, Bt) do { __builtin_amdgcn_s_setprio(1); _Pragma("unroll") for (int m = 0; m < 4; ++m) _Pragma("unroll") for (int n = 0; n < 2; ++n) _Pragma("unroll") for (int k = 0; k < 2; ++k) \
;         acc[ai][bj][m][n] = __builtin_amdgcn_mfma_f32_16x16x32_bf16(Bt[n][k], At[m][k], acc[ai][bj][m][n], 0, 0, 0); __builtin_amdgcn_s_setprio(0); } while (0)
; #define PG8_WAIT_V(n) asm volatile("s_waitcnt vmcnt(" #n ")" ::: "memory")
; #define PG8_BAR __builtin_amdgcn_s_barrier()
; template <class Epi, class Sched, bool ALIGN_EPI = false, bool SP2 = false>
; __device__ __forceinline__ void gemm_phase(PG8_LAS unsigned char* lds, const Gemm g, const Sched& S, const Epi& E) {
;     ...
;         for (int t = 0; t < nt; t += 2) {
;             const bool last = (t == nt - 2);
;             const char* a1 = cA + (size_t)(t + 1) * kstep;
;             const char* a2 = last ? nA : cA + (size_t)(t + 2) * kstep; const char* b2 = last ? nB : cB + (size_t)(t + 2) * kstep;
;             const char* a3 = a2 + kstep; const char* b3 = b2 + kstep;
;             if (last && has_next) S.a_ready(nxt);
;             if constexpr (SP2) {
;             PG8_LDB(B0, 0, 0); PG8_LDB(B1, 0, 1); PG8_SCHED; PG8_LDA(At, 0, 0); PG8_STAGE(PG8_SA(1, 1), a1 + hstepA, voffA);
;             PG8_WAIT_V(8); PG8_WAIT_L(0); PG8_BAR; PG8_MMA(0, 0, At, B0); PG8_MMA(0, 1, At, B1); PG8_BAR; PG8_SCHED;
;             PG8_LDA(At, 0, 1); PG8_STAGE(PG8_SB(0, 0), b2, voffB); PG8_STAGE(PG8_SB(0, 1), b2 + hstepB, voffB); PG8_STAGE(PG8_SA(0, 0), a2, voffA);
;             PG8_WAIT_V(8); PG8_WAIT_L(0); PG8_BAR; PG8_MMA(1, 0, At, B0); PG8_MMA(1, 1, At, B1); PG8_BAR; PG8_SCHED;
.LBB0_524:
	ds_read_b128 v[144:147], v153
	ds_read_b128 v[158:161], v153 offset:1024
	ds_read_b128 v[162:165], v153 offset:2048
	ds_read_b128 v[166:169], v153 offset:3072
	ds_read_b128 v[170:173], v154
	ds_read_b128 v[174:177], v154 offset:1024
	ds_read_b128 v[178:181], v154 offset:2048
	ds_read_b128 v[182:185], v154 offset:3072
	s_add_u32 s30, s28, 0x100
	s_addc_u32 s31, s29, 0
	s_cmp_eq_u32 s76, 2
	s_cselect_b32 s37, s9, s31
	s_cselect_b32 s36, s8, s30
	s_cselect_b32 s35, s25, s75
	s_cselect_b32 s34, s24, s74
	v_lshl_add_u64 v[148:149], s[28:29], 0, v[136:137]
	s_add_i32 m0, s42, 0xc000
	ds_read_b128 v[188:191], v155
	ds_read_b128 v[192:195], v155 offset:1024
	ds_read_b128 v[196:199], v155 offset:2048
	ds_read_b128 v[200:203], v155 offset:3072
	ds_read_b128 v[204:207], v155 offset:4096
	ds_read_b128 v[208:211], v155 offset:5120
	ds_read_b128 v[212:215], v155 offset:6144
	ds_read_b128 v[216:219], v155 offset:7168
	global_load_lds_dwordx4 v[148:149], off
	v_lshl_add_u64 v[148:149], s[28:29], 0, v[138:139]
	s_add_i32 m0, s42, 0xe000
	s_nop 0
	global_load_lds_dwordx4 v[148:149], off
	s_waitcnt vmcnt(8) lgkmcnt(0)
	s_barrier
	s_setprio 1
	v_mfma_f32_16x16x32_bf16 v[124:127], v[144:147], v[188:191], v[124:127]
	v_mfma_f32_16x16x32_bf16 v[120:123], v[162:165], v[188:191], v[120:123]
	v_mfma_f32_16x16x32_bf16 v[108:111], v[144:147], v[196:199], v[108:111]
	v_mfma_f32_16x16x32_bf16 v[104:107], v[162:165], v[196:199], v[104:107]
	v_mfma_f32_16x16x32_bf16 v[92:95], v[144:147], v[204:207], v[92:95]
	v_mfma_f32_16x16x32_bf16 v[88:91], v[162:165], v[204:207], v[88:91]
	v_mfma_f32_16x16x32_bf16 v[76:79], v[144:147], v[212:215], v[76:79]
	v_mfma_f32_16x16x32_bf16 v[72:75], v[162:165], v[212:215], v[72:75]
	v_mfma_f32_16x16x32_bf16 v[124:127], v[158:161], v[192:195], v[124:127]
	v_mfma_f32_16x16x32_bf16 v[120:123], v[166:169], v[192:195], v[120:123]
	v_mfma_f32_16x16x32_bf16 v[108:111], v[158:161], v[200:203], v[108:111]
	v_mfma_f32_16x16x32_bf16 v[104:107], v[166:169], v[200:203], v[104:107]
	v_mfma_f32_16x16x32_bf16 v[92:95], v[158:161], v[208:211], v[92:95]
	v_mfma_f32_16x16x32_bf16 v[88:91], v[166:169], v[208:211], v[88:91]
	v_mfma_f32_16x16x32_bf16 v[76:79], v[158:161], v[216:219], v[76:79]
	v_mfma_f32_16x16x32_bf16 v[72:75], v[166:169], v[216:219], v[72:75]
	s_setprio 0
	s_setprio 1
	v_mfma_f32_16x16x32_bf16 v[116:119], v[170:173], v[188:191], v[116:119]
	v_mfma_f32_16x16x32_bf16 v[112:115], v[178:181], v[188:191], v[112:115]
	v_mfma_f32_16x16x32_bf16 v[100:103], v[170:173], v[196:199], v[100:103]
	v_mfma_f32_16x16x32_bf16 v[96:99], v[178:181], v[196:199], v[96:99]
	v_mfma_f32_16x16x32_bf16 v[84:87], v[170:173], v[204:207], v[84:87]
	v_mfma_f32_16x16x32_bf16 v[80:83], v[178:181], v[204:207], v[80:83]
	v_mfma_f32_16x16x32_bf16 v[68:71], v[170:173], v[212:215], v[68:71]
	v_mfma_f32_16x16x32_bf16 v[64:67], v[178:181], v[212:215], v[64:67]
	v_mfma_f32_16x16x32_bf16 v[116:119], v[174:177], v[192:195], v[116:119]
	v_mfma_f32_16x16x32_bf16 v[112:115], v[182:185], v[192:195], v[112:115]
	v_mfma_f32_16x16x32_bf16 v[100:103], v[174:177], v[200:203], v[100:103]
	v_mfma_f32_16x16x32_bf16 v[96:99], v[182:185], v[200:203], v[96:99]
	v_mfma_f32_16x16x32_bf16 v[84:87], v[174:177], v[208:211], v[84:87]
	v_mfma_f32_16x16x32_bf16 v[80:83], v[182:185], v[208:211], v[80:83]
	v_mfma_f32_16x16x32_bf16 v[68:71], v[174:177], v[216:219], v[68:71]
	v_mfma_f32_16x16x32_bf16 v[64:67], v[182:185], v[216:219], v[64:67]
	s_barrier
	s_setprio 0
	s_add_i32 s28, s66, s40
	v_lshl_add_u64 v[148:149], s[34:35], 0, v[132:133]
	s_mov_b32 m0, s28
	ds_read_b128 v[188:191], v155 offset:16384
	ds_read_b128 v[192:195], v155 offset:17408
	ds_read_b128 v[196:199], v155 offset:18432
	ds_read_b128 v[200:203], v155 offset:19456
	ds_read_b128 v[204:207], v155 offset:20480
	ds_read_b128 v[208:211], v155 offset:21504
	ds_read_b128 v[212:215], v155 offset:22528
	ds_read_b128 v[216:219], v155 offset:23552
	global_load_lds_dwordx4 v[148:149], off
	s_add_i32 m0, s28, 0x2000
	s_add_u32 s28, s34, 0x18000
	v_lshl_add_u64 v[220:221], s[34:35], 0, v[128:129]
	s_addc_u32 s29, s35, 0
	s_add_i32 s58, s67, s40
	global_load_lds_dwordx4 v[220:221], off
	v_lshl_add_u64 v[222:223], s[28:29], 0, v[132:133]
	s_mov_b32 m0, s58
	v_lshl_add_u64 v[224:225], s[36:37], 0, v[130:131]
	global_load_lds_dwordx4 v[222:223], off
	v_lshl_add_u64 v[222:223], s[28:29], 0, v[128:129]
	s_add_i32 m0, s58, 0x2000
	s_nop 0
	global_load_lds_dwordx4 v[222:223], off
	v_lshl_add_u64 v[222:223], s[36:37], 0, v[134:135]
	s_mov_b32 m0, s42
	s_nop 0
	global_load_lds_dwordx4 v[222:223], off
	s_mov_b32 m0, s43
	s_nop 0
	global_load_lds_dwordx4 v[224:225], off
	s_waitcnt vmcnt(8) lgkmcnt(0)
	s_barrier
; #define PG8_STAGE(bufoff, gbase, voff) do { _Pragma("unroll") for (int _i = 0; _i < 2; ++_i) \
;         __builtin_amdgcn_global_load_lds((const unsigned*)((const char*)(gbase) + (voff)[_i]), (PG8_LAS unsigned*)(lds + (bufoff) + ldsw + _i * 8192), 16, 0, 0); } while (0)
; #define PG8_LDA(dst, b, h) do { _Pragma("unroll") for (int m = 0; m < 4; ++m) _Pragma("unroll") for (int k = 0; k < 2; ++k) dst[m][k] = *(const PG8_LAS bf16x8*)(lds + PG8_SA(b, h) + aoff + m * 2048 + k * 1024); } while (0)
; #define PG8_LDB(dst, b, h) do { _Pragma("unroll") for (int n = 0; n < 2; ++n) _Pragma("unroll") for (int k = 0; k < 2; ++k) dst[n][k] = *(const PG8_LAS bf16x8*)(lds + PG8_SB(b, h) + boff + n * 2048 + k * 1024); } while (0)
; #define PG8_MMA(ai, bj, At, Bt) do { __builtin_amdgcn_s_setprio(1); _Pragma("unroll") for (int m = 0; m < 4; ++m) _Pragma("unroll") for (int n = 0; n < 2; ++n) _Pragma("unroll") for (int k = 0; k < 2; ++k) \
;         acc[ai][bj][m][n] = __builtin_amdgcn_mfma_f32_16x16x32_bf16(Bt[n][k], At[m][k], acc[ai][bj][m][n], 0, 0, 0); __builtin_amdgcn_s_setprio(0); } while (0)
; #define PG8_WAIT_V(n) asm volatile("s_waitcnt vmcnt(" #n ")" ::: "memory")
; #define PG8_WAIT_L(n) asm volatile("s_waitcnt lgkmcnt(" #n ")" ::: "memory")
; #define PG8_BAR __builtin_amdgcn_s_barrier()
; #define PG8_SCHED __builtin_amdgcn_sched_barrier(0)
; template <class Epi, class Sched, bool ALIGN_EPI = false, bool SP2 = false>
; __device__ __forceinline__ void gemm_phase(PG8_LAS unsigned char* lds, const Gemm g, const Sched& S, const Epi& E) {
;     ...
;             PG8_WAIT_V(8); PG8_WAIT_L(0); PG8_BAR; PG8_MMA(1, 0, At, B0); PG8_MMA(1, 1, At, B1); PG8_BAR; PG8_SCHED;
;             PG8_LDB(B0, 1, 0); PG8_LDB(B1, 1, 1); PG8_SCHED; PG8_LDA(At, 1, 0); PG8_STAGE(PG8_SA(0, 1), a2 + hstepA, voffA);
;             PG8_WAIT_V(8); PG8_WAIT_L(0); PG8_BAR; PG8_MMA(0, 0, At, B0); PG8_MMA(0, 1, At, B1); PG8_BAR; PG8_SCHED;
	s_setprio 1
	v_mfma_f32_16x16x32_bf16 v[60:63], v[144:147], v[188:191], v[60:63]
	v_mfma_f32_16x16x32_bf16 v[56:59], v[162:165], v[188:191], v[56:59]
	v_mfma_f32_16x16x32_bf16 v[44:47], v[144:147], v[196:199], v[44:47]
	v_mfma_f32_16x16x32_bf16 v[40:43], v[162:165], v[196:199], v[40:43]
	v_mfma_f32_16x16x32_bf16 v[28:31], v[144:147], v[204:207], v[28:31]
	v_mfma_f32_16x16x32_bf16 v[24:27], v[162:165], v[204:207], v[24:27]
	v_mfma_f32_16x16x32_bf16 v[12:15], v[144:147], v[212:215], v[12:15]
	v_mfma_f32_16x16x32_bf16 v[8:11], v[162:165], v[212:215], v[8:11]
	v_mfma_f32_16x16x32_bf16 v[60:63], v[158:161], v[192:195], v[60:63]
	v_mfma_f32_16x16x32_bf16 v[56:59], v[166:169], v[192:195], v[56:59]
	v_mfma_f32_16x16x32_bf16 v[44:47], v[158:161], v[200:203], v[44:47]
	v_mfma_f32_16x16x32_bf16 v[40:43], v[166:169], v[200:203], v[40:43]
	v_mfma_f32_16x16x32_bf16 v[28:31], v[158:161], v[208:211], v[28:31]
	v_mfma_f32_16x16x32_bf16 v[24:27], v[166:169], v[208:211], v[24:27]
	v_mfma_f32_16x16x32_bf16 v[12:15], v[158:161], v[216:219], v[12:15]
	v_mfma_f32_16x16x32_bf16 v[8:11], v[166:169], v[216:219], v[8:11]
	s_setprio 0
	s_setprio 1
	v_mfma_f32_16x16x32_bf16 v[52:55], v[170:173], v[188:191], v[52:55]
	v_mfma_f32_16x16x32_bf16 v[48:51], v[178:181], v[188:191], v[48:51]
	v_mfma_f32_16x16x32_bf16 v[36:39], v[170:173], v[196:199], v[36:39]
	v_mfma_f32_16x16x32_bf16 v[32:35], v[178:181], v[196:199], v[32:35]
	v_mfma_f32_16x16x32_bf16 v[20:23], v[170:173], v[204:207], v[20:23]
	v_mfma_f32_16x16x32_bf16 v[16:19], v[178:181], v[204:207], v[16:19]
	v_mfma_f32_16x16x32_bf16 v[4:7], v[170:173], v[212:215], v[4:7]
	v_mfma_f32_16x16x32_bf16 v[0:3], v[178:181], v[212:215], v[0:3]
	v_mfma_f32_16x16x32_bf16 v[52:55], v[174:177], v[192:195], v[52:55]
	v_mfma_f32_16x16x32_bf16 v[48:51], v[182:185], v[192:195], v[48:51]
	v_mfma_f32_16x16x32_bf16 v[36:39], v[174:177], v[200:203], v[36:39]
	v_mfma_f32_16x16x32_bf16 v[32:35], v[182:185], v[200:203], v[32:35]
	v_mfma_f32_16x16x32_bf16 v[20:23], v[174:177], v[208:211], v[20:23]
	v_mfma_f32_16x16x32_bf16 v[16:19], v[182:185], v[208:211], v[16:19]
	v_mfma_f32_16x16x32_bf16 v[4:7], v[174:177], v[216:219], v[4:7]
	v_mfma_f32_16x16x32_bf16 v[0:3], v[182:185], v[216:219], v[0:3]
	s_barrier
	s_setprio 0
	s_add_i32 s58, 0, 0x18000
	v_add_u32_e32 v157, s58, v151
	s_add_i32 s59, 0, 0x1c000
	ds_read_b128 v[144:147], v157
	ds_read_b128 v[158:161], v157 offset:1024
	ds_read_b128 v[162:165], v157 offset:2048
	ds_read_b128 v[166:169], v157 offset:3072
	v_add_u32_e32 v157, s59, v151
	ds_read_b128 v[170:173], v157
	ds_read_b128 v[174:177], v157 offset:1024
	ds_read_b128 v[178:181], v157 offset:2048
	ds_read_b128 v[182:185], v157 offset:3072
	s_add_u32 s28, s36, 0x30000
	s_addc_u32 s29, s37, 0
	s_mov_b32 m0, s44
	v_lshl_add_u64 v[226:227], s[28:29], 0, v[134:135]
	ds_read_b128 v[188:191], v155 offset:32768
	ds_read_b128 v[192:195], v155 offset:33792
	ds_read_b128 v[196:199], v155 offset:34816
	ds_read_b128 v[200:203], v155 offset:35840
	ds_read_b128 v[204:207], v155 offset:36864
	ds_read_b128 v[208:211], v155 offset:37888
	ds_read_b128 v[212:215], v155 offset:38912
	ds_read_b128 v[216:219], v155 offset:39936
	global_load_lds_dwordx4 v[226:227], off
	v_lshl_add_u64 v[226:227], s[28:29], 0, v[130:131]
	s_mov_b32 m0, s45
	s_nop 0
	global_load_lds_dwordx4 v[226:227], off
	s_waitcnt vmcnt(8) lgkmcnt(0)
	s_barrier
	s_setprio 1
	v_mfma_f32_16x16x32_bf16 v[124:127], v[144:147], v[188:191], v[124:127]
	v_mfma_f32_16x16x32_bf16 v[120:123], v[162:165], v[188:191], v[120:123]
	v_mfma_f32_16x16x32_bf16 v[108:111], v[144:147], v[196:199], v[108:111]
	v_mfma_f32_16x16x32_bf16 v[104:107], v[162:165], v[196:199], v[104:107]
	v_mfma_f32_16x16x32_bf16 v[92:95], v[144:147], v[204:207], v[92:95]
	v_mfma_f32_16x16x32_bf16 v[88:91], v[162:165], v[204:207], v[88:91]
	v_mfma_f32_16x16x32_bf16 v[76:79], v[144:147], v[212:215], v[76:79]
	v_mfma_f32_16x16x32_bf16 v[72:75], v[162:165], v[212:215], v[72:75]
	v_mfma_f32_16x16x32_bf16 v[124:127], v[158:161], v[192:195], v[124:127]
	v_mfma_f32_16x16x32_bf16 v[120:123], v[166:169], v[192:195], v[120:123]
	v_mfma_f32_16x16x32_bf16 v[108:111], v[158:161], v[200:203], v[108:111]
	v_mfma_f32_16x16x32_bf16 v[104:107], v[166:169], v[200:203], v[104:107]
	v_mfma_f32_16x16x32_bf16 v[92:95], v[158:161], v[208:211], v[92:95]
	v_mfma_f32_16x16x32_bf16 v[88:91], v[166:169], v[208:211], v[88:91]
	v_mfma_f32_16x16x32_bf16 v[76:79], v[158:161], v[216:219], v[76:79]
	v_mfma_f32_16x16x32_bf16 v[72:75], v[166:169], v[216:219], v[72:75]
	s_setprio 0
	s_setprio 1
	v_mfma_f32_16x16x32_bf16 v[116:119], v[170:173], v[188:191], v[116:119]
	v_mfma_f32_16x16x32_bf16 v[112:115], v[178:181], v[188:191], v[112:115]
	v_mfma_f32_16x16x32_bf16 v[100:103], v[170:173], v[196:199], v[100:103]
	v_mfma_f32_16x16x32_bf16 v[96:99], v[178:181], v[196:199], v[96:99]
	v_mfma_f32_16x16x32_bf16 v[84:87], v[170:173], v[204:207], v[84:87]
	v_mfma_f32_16x16x32_bf16 v[80:83], v[178:181], v[204:207], v[80:83]
	v_mfma_f32_16x16x32_bf16 v[68:71], v[170:173], v[212:215], v[68:71]
	v_mfma_f32_16x16x32_bf16 v[64:67], v[178:181], v[212:215], v[64:67]
	v_mfma_f32_16x16x32_bf16 v[116:119], v[174:177], v[192:195], v[116:119]
	v_mfma_f32_16x16x32_bf16 v[112:115], v[182:185], v[192:195], v[112:115]
	v_mfma_f32_16x16x32_bf16 v[100:103], v[174:177], v[200:203], v[100:103]
	v_mfma_f32_16x16x32_bf16 v[96:99], v[182:185], v[200:203], v[96:99]
	v_mfma_f32_16x16x32_bf16 v[84:87], v[174:177], v[208:211], v[84:87]
	v_mfma_f32_16x16x32_bf16 v[80:83], v[182:185], v[208:211], v[80:83]
	v_mfma_f32_16x16x32_bf16 v[68:71], v[174:177], v[216:219], v[68:71]
	v_mfma_f32_16x16x32_bf16 v[64:67], v[182:185], v[216:219], v[64:67]
	s_barrier
; #define PG8_STAGE(bufoff, gbase, voff) do { _Pragma("unroll") for (int _i = 0; _i < 2; ++_i) \
;         __builtin_amdgcn_global_load_lds((const unsigned*)((const char*)(gbase) + (voff)[_i]), (PG8_LAS unsigned*)(lds + (bufoff) + ldsw + _i * 8192), 16, 0, 0); } while (0)
; #define PG8_LDA(dst, b, h) do { _Pragma("unroll") for (int m = 0; m < 4; ++m) _Pragma("unroll") for (int k = 0; k < 2; ++k) dst[m][k] = *(const PG8_LAS bf16x8*)(lds + PG8_SA(b, h) + aoff + m * 2048 + k * 1024); } while (0)
; #define PG8_MMA(ai, bj, At, Bt) do { __builtin_amdgcn_s_setprio(1); _Pragma("unroll") for (int m = 0; m < 4; ++m) _Pragma("unroll") for (int n = 0; n < 2; ++n) _Pragma("unroll") for (int k = 0; k < 2; ++k) \
;         acc[ai][bj][m][n] = __builtin_amdgcn_mfma_f32_16x16x32_bf16(Bt[n][k], At[m][k], acc[ai][bj][m][n], 0, 0, 0); __builtin_amdgcn_s_setprio(0); } while (0)
; #define PG8_WAIT_V(n) asm volatile("s_waitcnt vmcnt(" #n ")" ::: "memory")
; #define PG8_WAIT_L(n) asm volatile("s_waitcnt lgkmcnt(" #n ")" ::: "memory")
; #define PG8_BAR __builtin_amdgcn_s_barrier()
; #define PG8_SCHED __builtin_amdgcn_sched_barrier(0)
; template <class Epi, class Sched, bool ALIGN_EPI = false, bool SP2 = false>
; __device__ __forceinline__ void gemm_phase(PG8_LAS unsigned char* lds, const Gemm g, const Sched& S, const Epi& E) {
;     ...
;             PG8_LDA(At, 1, 1); PG8_STAGE(PG8_SB(1, 0), b3, voffB); PG8_STAGE(PG8_SB(1, 1), b3 + hstepB, voffB); PG8_STAGE(PG8_SA(1, 0), a3, voffA);
;             PG8_WAIT_V(8); PG8_WAIT_L(0); PG8_BAR; PG8_MMA(1, 0, At, B0); PG8_MMA(1, 1, At, B1); PG8_BAR; PG8_SCHED;
;     ...
;         if constexpr (ALIGN_EPI) { if (wr == 0) PG8_BAR; }
	s_setprio 0
	s_add_i32 s28, s58, s40
	v_lshl_add_u64 v[148:149], v[148:149], 0, s[12:13]
	s_mov_b32 m0, s28
	ds_read_b128 v[188:191], v155 offset:49152
	ds_read_b128 v[192:195], v155 offset:50176
	ds_read_b128 v[196:199], v155 offset:51200
	ds_read_b128 v[200:203], v155 offset:52224
	ds_read_b128 v[204:207], v155 offset:53248
	ds_read_b128 v[208:211], v155 offset:54272
	ds_read_b128 v[212:215], v155 offset:55296
	ds_read_b128 v[216:219], v155 offset:56320
	global_load_lds_dwordx4 v[148:149], off
	s_add_i32 m0, s28, 0x2000
	s_add_u32 s28, s34, 0x18080
	v_lshl_add_u64 v[148:149], v[220:221], 0, s[12:13]
	s_addc_u32 s29, s35, 0
	s_add_i32 s34, s59, s40
	global_load_lds_dwordx4 v[148:149], off
	v_lshl_add_u64 v[148:149], s[28:29], 0, v[132:133]
	s_mov_b32 m0, s34
	s_nop 0
	global_load_lds_dwordx4 v[148:149], off
	v_lshl_add_u64 v[148:149], s[28:29], 0, v[128:129]
	s_add_i32 m0, s34, 0x2000
	s_nop 0
	global_load_lds_dwordx4 v[148:149], off
	v_lshl_add_u64 v[148:149], v[222:223], 0, s[12:13]
	s_mov_b32 m0, s47
	s_nop 0
	global_load_lds_dwordx4 v[148:149], off
	v_lshl_add_u64 v[148:149], v[224:225], 0, s[12:13]
	s_mov_b32 m0, s48
	s_nop 0
	global_load_lds_dwordx4 v[148:149], off
	s_waitcnt vmcnt(8) lgkmcnt(0)
	s_barrier
	s_setprio 1
	v_mfma_f32_16x16x32_bf16 v[60:63], v[144:147], v[188:191], v[60:63]
	v_mfma_f32_16x16x32_bf16 v[56:59], v[162:165], v[188:191], v[56:59]
	v_mfma_f32_16x16x32_bf16 v[44:47], v[144:147], v[196:199], v[44:47]
	v_mfma_f32_16x16x32_bf16 v[40:43], v[162:165], v[196:199], v[40:43]
	v_mfma_f32_16x16x32_bf16 v[28:31], v[144:147], v[204:207], v[28:31]
	v_mfma_f32_16x16x32_bf16 v[24:27], v[162:165], v[204:207], v[24:27]
	v_mfma_f32_16x16x32_bf16 v[12:15], v[144:147], v[212:215], v[12:15]
	v_mfma_f32_16x16x32_bf16 v[8:11], v[162:165], v[212:215], v[8:11]
	v_mfma_f32_16x16x32_bf16 v[60:63], v[158:161], v[192:195], v[60:63]
	v_mfma_f32_16x16x32_bf16 v[56:59], v[166:169], v[192:195], v[56:59]
	v_mfma_f32_16x16x32_bf16 v[44:47], v[158:161], v[200:203], v[44:47]
	v_mfma_f32_16x16x32_bf16 v[40:43], v[166:169], v[200:203], v[40:43]
	v_mfma_f32_16x16x32_bf16 v[28:31], v[158:161], v[208:211], v[28:31]
	v_mfma_f32_16x16x32_bf16 v[24:27], v[166:169], v[208:211], v[24:27]
	v_mfma_f32_16x16x32_bf16 v[12:15], v[158:161], v[216:219], v[12:15]
	v_mfma_f32_16x16x32_bf16 v[8:11], v[166:169], v[216:219], v[8:11]
	s_setprio 0
	s_setprio 1
	v_mfma_f32_16x16x32_bf16 v[52:55], v[170:173], v[188:191], v[52:55]
	v_mfma_f32_16x16x32_bf16 v[48:51], v[178:181], v[188:191], v[48:51]
	v_mfma_f32_16x16x32_bf16 v[36:39], v[170:173], v[196:199], v[36:39]
	v_mfma_f32_16x16x32_bf16 v[32:35], v[178:181], v[196:199], v[32:35]
	v_mfma_f32_16x16x32_bf16 v[20:23], v[170:173], v[204:207], v[20:23]
	v_mfma_f32_16x16x32_bf16 v[16:19], v[178:181], v[204:207], v[16:19]
	v_mfma_f32_16x16x32_bf16 v[4:7], v[170:173], v[212:215], v[4:7]
	v_mfma_f32_16x16x32_bf16 v[0:3], v[178:181], v[212:215], v[0:3]
	v_mfma_f32_16x16x32_bf16 v[52:55], v[174:177], v[192:195], v[52:55]
	v_mfma_f32_16x16x32_bf16 v[48:51], v[182:185], v[192:195], v[48:51]
	v_mfma_f32_16x16x32_bf16 v[36:39], v[174:177], v[200:203], v[36:39]
	v_mfma_f32_16x16x32_bf16 v[32:35], v[182:185], v[200:203], v[32:35]
	v_mfma_f32_16x16x32_bf16 v[20:23], v[174:177], v[208:211], v[20:23]
	v_mfma_f32_16x16x32_bf16 v[16:19], v[182:185], v[208:211], v[16:19]
	v_mfma_f32_16x16x32_bf16 v[4:7], v[174:177], v[216:219], v[4:7]
	v_mfma_f32_16x16x32_bf16 v[0:3], v[182:185], v[216:219], v[0:3]
	s_barrier
	s_setprio 0
	s_add_i32 s76, s76, 2
	s_add_u32 s74, s74, 0x100
	s_addc_u32 s75, s75, 0
	s_cmp_gt_u32 s76, 3
	s_mov_b64 s[28:29], s[30:31]
	s_cbranch_scc0 .LBB0_524
	s_and_b64 vcc, exec, s[14:15]
	s_cbranch_vccz .LBB0_527
	s_barrier

; #define PG8_STAGE(bufoff, gbase, voff) do { _Pragma("unroll") for (int _i = 0; _i < 2; ++_i) \
;         __builtin_amdgcn_global_load_lds((const unsigned*)((const char*)(gbase) + (voff)[_i]), (PG8_LAS unsigned*)(lds + (bufoff) + ldsw + _i * 8192), 16, 0, 0); } while (0)
; #define PG8_LDA(dst, b, h) do { _Pragma("unroll") for (int m = 0; m < 4; ++m) _Pragma("unroll") for (int k = 0; k < 2; ++k) dst[m][k] = *(const PG8_LAS bf16x8*)(lds + PG8_SA(b, h) + aoff + m * 2048 + k * 1024); } while (0)
; #define PG8_LDB(dst, b, h) do { _Pragma("unroll") for (int n = 0; n < 2; ++n) _Pragma("unroll") for (int k = 0; k < 2; ++k) dst[n][k] = *(const PG8_LAS bf16x8*)(lds + PG8_SB(b, h) + boff + n * 2048 + k * 1024); } while (0)
; #define PG8_WAIT_V(n) asm volatile("s_waitcnt vmcnt(" #n ")" ::: "memory")
; #define PG8_WAIT_L(n) asm volatile("s_waitcnt lgkmcnt(" #n ")" ::: "memory")
; #define PG8_BAR __builtin_amdgcn_s_barrier()
; #define PG8_SCHED __builtin_amdgcn_sched_barrier(0)
; template <class Epi, class Sched, bool ALIGN_EPI = false, bool SP2 = false>
; __device__ __forceinline__ void gemm_phase(PG8_LAS unsigned char* lds, const Gemm g, const Sched& S, const Epi& E) {
;     ...
;         const bool has_next = S.next(ui + 1, nxt);
;         const char* nA = has_next ? (const char*)g.A + (size_t)nxt.pm * tstepA : cA; const char* nB = has_next ? (const char*)g.Bt + (size_t)nxt.pn * tstepB : cB;
;         for (int t = 0; t < nt; t += 2) {
;             const bool last = (t == nt - 2);
;             const char* a1 = cA + (size_t)(t + 1) * kstep;
;             const char* a2 = last ? nA : cA + (size_t)(t + 2) * kstep; const char* b2 = last ? nB : cB + (size_t)(t + 2) * kstep;
;             const char* a3 = a2 + kstep; const char* b3 = b2 + kstep;
;             if (last && has_next) S.a_ready(nxt);
;             if constexpr (SP2) {
;             PG8_LDB(B0, 0, 0); PG8_LDB(B1, 0, 1); PG8_SCHED; PG8_LDA(At, 0, 0); PG8_STAGE(PG8_SA(1, 1), a1 + hstepA, voffA);
;             PG8_WAIT_V(8); PG8_WAIT_L(0); PG8_BAR; PG8_MMA(0, 0, At, B0); PG8_MMA(0, 1, At, B1); PG8_BAR; PG8_SCHED;
;             PG8_LDA(At, 0, 1); PG8_STAGE(PG8_SB(0, 0), b2, voffB); PG8_STAGE(PG8_SB(0, 1), b2 + hstepB, voffB); PG8_STAGE(PG8_SA(0, 0), a2, voffA);
;             PG8_WAIT_V(8); PG8_WAIT_L(0); PG8_BAR; PG8_MMA(1, 0, At, B0); PG8_MMA(1, 1, At, B1); PG8_BAR; PG8_SCHED;
.LBB0_542:
	s_add_u32 s39, s34, s38
	s_addc_u32 s44, s35, 0
	s_add_u32 s42, s39, 0x100
	s_addc_u32 s43, s44, 0
	s_and_b64 s[40:41], s[36:37], exec
	s_cselect_b32 s41, s27, s43
	s_cselect_b32 s40, s26, s42
	s_add_u32 s38, s30, s38
	s_addc_u32 s42, s31, 0
	s_add_u32 s38, s38, 0x100
	s_addc_u32 s42, s42, 0
	s_and_b64 s[36:37], s[36:37], exec
	s_cselect_b32 s43, s25, s42
	s_cselect_b32 s42, s89, s38
	s_add_u32 s46, s39, 0x30080
	ds_read_b128 v[140:143], v149
	ds_read_b128 v[154:157], v149 offset:1024
	ds_read_b128 v[158:161], v149 offset:2048
	ds_read_b128 v[162:165], v149 offset:3072
	ds_read_b128 v[166:169], v150
	ds_read_b128 v[170:173], v150 offset:1024
	ds_read_b128 v[174:177], v150 offset:2048
	ds_read_b128 v[178:181], v150 offset:3072
	s_addc_u32 s47, s44, 0
	s_add_i32 vcc_hi, s78, s68
	s_add_i32 m0, s70, 0xc000
	s_add_i32 s58, s70, 0xe000
	s_add_i32 s96, vcc_hi, 0x2000
	s_add_u32 s44, s42, 0x10000
	s_addc_u32 s45, s43, 0
	s_add_i32 vcc_lo, s79, s68
	s_add_i32 s97, vcc_lo, 0x2000
	s_add_i32 s95, 0, 0x18000
	s_add_i32 s94, 0, 0x1c000
	s_add_u32 s38, s40, 0x30000
	s_addc_u32 s39, s41, 0
	s_add_i32 s93, s95, s68
	s_add_i32 s91, s93, 0x2000
	s_add_u32 s36, s42, 0x10080
	s_addc_u32 s37, s43, 0
	s_add_i32 s92, s94, s68
	s_add_i32 s90, s92, 0x2000
	v_lshl_add_u64 v[144:145], s[46:47], 0, v[134:135]
	ds_read_b128 v[182:185], v151
	ds_read_b128 v[188:191], v151 offset:1024
	ds_read_b128 v[192:195], v151 offset:2048
	ds_read_b128 v[196:199], v151 offset:3072
	ds_read_b128 v[200:203], v151 offset:4096
	ds_read_b128 v[204:207], v151 offset:5120
	ds_read_b128 v[208:211], v151 offset:6144
	ds_read_b128 v[212:215], v151 offset:7168
	global_load_lds_dwordx4 v[144:145], off
	v_lshl_add_u64 v[144:145], s[46:47], 0, v[130:131]
	s_mov_b32 m0, s58
	s_nop 0
	global_load_lds_dwordx4 v[144:145], off
	s_waitcnt vmcnt(8) lgkmcnt(0)
	s_barrier
	s_setprio 1
	v_mfma_f32_16x16x32_bf16 v[124:127], v[140:143], v[182:185], v[124:127]
	v_mfma_f32_16x16x32_bf16 v[120:123], v[158:161], v[182:185], v[120:123]
	v_mfma_f32_16x16x32_bf16 v[108:111], v[140:143], v[192:195], v[108:111]
	v_mfma_f32_16x16x32_bf16 v[104:107], v[158:161], v[192:195], v[104:107]
	v_mfma_f32_16x16x32_bf16 v[92:95], v[140:143], v[200:203], v[92:95]
	v_mfma_f32_16x16x32_bf16 v[88:91], v[158:161], v[200:203], v[88:91]
	v_mfma_f32_16x16x32_bf16 v[76:79], v[140:143], v[208:211], v[76:79]
	v_mfma_f32_16x16x32_bf16 v[72:75], v[158:161], v[208:211], v[72:75]
	v_mfma_f32_16x16x32_bf16 v[124:127], v[154:157], v[188:191], v[124:127]
	v_mfma_f32_16x16x32_bf16 v[120:123], v[162:165], v[188:191], v[120:123]
	v_mfma_f32_16x16x32_bf16 v[108:111], v[154:157], v[196:199], v[108:111]
	v_mfma_f32_16x16x32_bf16 v[104:107], v[162:165], v[196:199], v[104:107]
	v_mfma_f32_16x16x32_bf16 v[92:95], v[154:157], v[204:207], v[92:95]
	v_mfma_f32_16x16x32_bf16 v[88:91], v[162:165], v[204:207], v[88:91]
	v_mfma_f32_16x16x32_bf16 v[76:79], v[154:157], v[212:215], v[76:79]
	v_mfma_f32_16x16x32_bf16 v[72:75], v[162:165], v[212:215], v[72:75]
	s_setprio 0
	s_setprio 1
	v_mfma_f32_16x16x32_bf16 v[116:119], v[166:169], v[182:185], v[116:119]
	v_mfma_f32_16x16x32_bf16 v[112:115], v[174:177], v[182:185], v[112:115]
	v_mfma_f32_16x16x32_bf16 v[100:103], v[166:169], v[192:195], v[100:103]
	v_mfma_f32_16x16x32_bf16 v[96:99], v[174:177], v[192:195], v[96:99]
	v_mfma_f32_16x16x32_bf16 v[84:87], v[166:169], v[200:203], v[84:87]
	v_mfma_f32_16x16x32_bf16 v[80:83], v[174:177], v[200:203], v[80:83]
	v_mfma_f32_16x16x32_bf16 v[68:71], v[166:169], v[208:211], v[68:71]
	v_mfma_f32_16x16x32_bf16 v[64:67], v[174:177], v[208:211], v[64:67]
	v_mfma_f32_16x16x32_bf16 v[116:119], v[170:173], v[188:191], v[116:119]
	v_mfma_f32_16x16x32_bf16 v[112:115], v[178:181], v[188:191], v[112:115]
	v_mfma_f32_16x16x32_bf16 v[100:103], v[170:173], v[196:199], v[100:103]
	v_mfma_f32_16x16x32_bf16 v[96:99], v[178:181], v[196:199], v[96:99]
	v_mfma_f32_16x16x32_bf16 v[84:87], v[170:173], v[204:207], v[84:87]
	v_mfma_f32_16x16x32_bf16 v[80:83], v[178:181], v[204:207], v[80:83]
	v_mfma_f32_16x16x32_bf16 v[68:71], v[170:173], v[212:215], v[68:71]
	v_mfma_f32_16x16x32_bf16 v[64:67], v[178:181], v[212:215], v[64:67]
	s_barrier
	s_setprio 0
	s_mov_b32 m0, vcc_hi
	v_lshl_add_u64 v[144:145], s[42:43], 0, v[132:133]
	ds_read_b128 v[182:185], v151 offset:16384
	ds_read_b128 v[188:191], v151 offset:17408
	ds_read_b128 v[192:195], v151 offset:18432
	ds_read_b128 v[196:199], v151 offset:19456
	ds_read_b128 v[200:203], v151 offset:20480
	ds_read_b128 v[204:207], v151 offset:21504
	ds_read_b128 v[208:211], v151 offset:22528
	ds_read_b128 v[212:215], v151 offset:23552
	global_load_lds_dwordx4 v[144:145], off
	v_lshl_add_u64 v[216:217], s[42:43], 0, v[128:129]
	s_mov_b32 m0, s96
	v_lshl_add_u64 v[218:219], s[44:45], 0, v[132:133]
	global_load_lds_dwordx4 v[216:217], off
	s_mov_b32 m0, vcc_lo
	v_lshl_add_u64 v[220:221], s[40:41], 0, v[130:131]
	global_load_lds_dwordx4 v[218:219], off
	v_lshl_add_u64 v[218:219], s[44:45], 0, v[128:129]
	s_mov_b32 m0, s97
	s_nop 0
	global_load_lds_dwordx4 v[218:219], off
	v_lshl_add_u64 v[218:219], s[40:41], 0, v[134:135]
	s_mov_b32 m0, s70
	s_nop 0
	global_load_lds_dwordx4 v[218:219], off
	s_mov_b32 m0, s71
	s_nop 0
	global_load_lds_dwordx4 v[220:221], off
	s_waitcnt vmcnt(8) lgkmcnt(0)
	s_barrier
; #define PG8_STAGE(bufoff, gbase, voff) do { _Pragma("unroll") for (int _i = 0; _i < 2; ++_i) \
;         __builtin_amdgcn_global_load_lds((const unsigned*)((const char*)(gbase) + (voff)[_i]), (PG8_LAS unsigned*)(lds + (bufoff) + ldsw + _i * 8192), 16, 0, 0); } while (0)
; #define PG8_LDA(dst, b, h) do { _Pragma("unroll") for (int m = 0; m < 4; ++m) _Pragma("unroll") for (int k = 0; k < 2; ++k) dst[m][k] = *(const PG8_LAS bf16x8*)(lds + PG8_SA(b, h) + aoff + m * 2048 + k * 1024); } while (0)
; #define PG8_LDB(dst, b, h) do { _Pragma("unroll") for (int n = 0; n < 2; ++n) _Pragma("unroll") for (int k = 0; k < 2; ++k) dst[n][k] = *(const PG8_LAS bf16x8*)(lds + PG8_SB(b, h) + boff + n * 2048 + k * 1024); } while (0)
; #define PG8_MMA(ai, bj, At, Bt) do { __builtin_amdgcn_s_setprio(1); _Pragma("unroll") for (int m = 0; m < 4; ++m) _Pragma("unroll") for (int n = 0; n < 2; ++n) _Pragma("unroll") for (int k = 0; k < 2; ++k) \
;         acc[ai][bj][m][n] = __builtin_amdgcn_mfma_f32_16x16x32_bf16(Bt[n][k], At[m][k], acc[ai][bj][m][n], 0, 0, 0); __builtin_amdgcn_s_setprio(0); } while (0)
; #define PG8_WAIT_V(n) asm volatile("s_waitcnt vmcnt(" #n ")" ::: "memory")
; #define PG8_WAIT_L(n) asm volatile("s_waitcnt lgkmcnt(" #n ")" ::: "memory")
; #define PG8_BAR __builtin_amdgcn_s_barrier()
; #define PG8_SCHED __builtin_amdgcn_sched_barrier(0)
; template <class Epi, class Sched, bool ALIGN_EPI = false, bool SP2 = false>
; __device__ __forceinline__ void gemm_phase(PG8_LAS unsigned char* lds, const Gemm g, const Sched& S, const Epi& E) {
;     ...
;             PG8_WAIT_V(8); PG8_WAIT_L(0); PG8_BAR; PG8_MMA(1, 0, At, B0); PG8_MMA(1, 1, At, B1); PG8_BAR; PG8_SCHED;
;             PG8_LDB(B0, 1, 0); PG8_LDB(B1, 1, 1); PG8_SCHED; PG8_LDA(At, 1, 0); PG8_STAGE(PG8_SA(0, 1), a2 + hstepA, voffA);
;             PG8_WAIT_V(8); PG8_WAIT_L(0); PG8_BAR; PG8_MMA(0, 0, At, B0); PG8_MMA(0, 1, At, B1); PG8_BAR; PG8_SCHED;
	s_setprio 1
	v_mfma_f32_16x16x32_bf16 v[60:63], v[140:143], v[182:185], v[60:63]
	v_mfma_f32_16x16x32_bf16 v[56:59], v[158:161], v[182:185], v[56:59]
	v_mfma_f32_16x16x32_bf16 v[44:47], v[140:143], v[192:195], v[44:47]
	v_mfma_f32_16x16x32_bf16 v[40:43], v[158:161], v[192:195], v[40:43]
	v_mfma_f32_16x16x32_bf16 v[28:31], v[140:143], v[200:203], v[28:31]
	v_mfma_f32_16x16x32_bf16 v[24:27], v[158:161], v[200:203], v[24:27]
	v_mfma_f32_16x16x32_bf16 v[12:15], v[140:143], v[208:211], v[12:15]
	v_mfma_f32_16x16x32_bf16 v[8:11], v[158:161], v[208:211], v[8:11]
	v_mfma_f32_16x16x32_bf16 v[60:63], v[154:157], v[188:191], v[60:63]
	v_mfma_f32_16x16x32_bf16 v[56:59], v[162:165], v[188:191], v[56:59]
	v_mfma_f32_16x16x32_bf16 v[44:47], v[154:157], v[196:199], v[44:47]
	v_mfma_f32_16x16x32_bf16 v[40:43], v[162:165], v[196:199], v[40:43]
	v_mfma_f32_16x16x32_bf16 v[28:31], v[154:157], v[204:207], v[28:31]
	v_mfma_f32_16x16x32_bf16 v[24:27], v[162:165], v[204:207], v[24:27]
	v_mfma_f32_16x16x32_bf16 v[12:15], v[154:157], v[212:215], v[12:15]
	v_mfma_f32_16x16x32_bf16 v[8:11], v[162:165], v[212:215], v[8:11]
	s_setprio 0
	s_setprio 1
	v_mfma_f32_16x16x32_bf16 v[52:55], v[166:169], v[182:185], v[52:55]
	v_mfma_f32_16x16x32_bf16 v[48:51], v[174:177], v[182:185], v[48:51]
	v_mfma_f32_16x16x32_bf16 v[36:39], v[166:169], v[192:195], v[36:39]
	v_mfma_f32_16x16x32_bf16 v[32:35], v[174:177], v[192:195], v[32:35]
	v_mfma_f32_16x16x32_bf16 v[20:23], v[166:169], v[200:203], v[20:23]
	v_mfma_f32_16x16x32_bf16 v[16:19], v[174:177], v[200:203], v[16:19]
	v_mfma_f32_16x16x32_bf16 v[4:7], v[166:169], v[208:211], v[4:7]
	v_mfma_f32_16x16x32_bf16 v[0:3], v[174:177], v[208:211], v[0:3]
	v_mfma_f32_16x16x32_bf16 v[52:55], v[170:173], v[188:191], v[52:55]
	v_mfma_f32_16x16x32_bf16 v[48:51], v[178:181], v[188:191], v[48:51]
	v_mfma_f32_16x16x32_bf16 v[36:39], v[170:173], v[196:199], v[36:39]
	v_mfma_f32_16x16x32_bf16 v[32:35], v[178:181], v[196:199], v[32:35]
	v_mfma_f32_16x16x32_bf16 v[20:23], v[170:173], v[204:207], v[20:23]
	v_mfma_f32_16x16x32_bf16 v[16:19], v[178:181], v[204:207], v[16:19]
	v_mfma_f32_16x16x32_bf16 v[4:7], v[170:173], v[212:215], v[4:7]
	v_mfma_f32_16x16x32_bf16 v[0:3], v[178:181], v[212:215], v[0:3]
	s_barrier
	s_setprio 0
	v_add_u32_e32 v153, s95, v147
	ds_read_b128 v[140:143], v153
	ds_read_b128 v[154:157], v153 offset:1024
	ds_read_b128 v[158:161], v153 offset:2048
	ds_read_b128 v[162:165], v153 offset:3072
	v_add_u32_e32 v153, s94, v147
	ds_read_b128 v[166:169], v153
	ds_read_b128 v[170:173], v153 offset:1024
	ds_read_b128 v[174:177], v153 offset:2048
	ds_read_b128 v[178:181], v153 offset:3072
	s_mov_b32 m0, s72
	v_lshl_add_u64 v[222:223], s[38:39], 0, v[134:135]
	ds_read_b128 v[182:185], v151 offset:32768
	ds_read_b128 v[188:191], v151 offset:33792
	ds_read_b128 v[192:195], v151 offset:34816
	ds_read_b128 v[196:199], v151 offset:35840
	ds_read_b128 v[200:203], v151 offset:36864
	ds_read_b128 v[204:207], v151 offset:37888
	ds_read_b128 v[208:211], v151 offset:38912
	ds_read_b128 v[212:215], v151 offset:39936
	global_load_lds_dwordx4 v[222:223], off
	v_lshl_add_u64 v[222:223], s[38:39], 0, v[130:131]
	s_mov_b32 m0, s73
	s_nop 0
	global_load_lds_dwordx4 v[222:223], off
	s_waitcnt vmcnt(8) lgkmcnt(0)
	s_barrier
	s_setprio 1
	v_mfma_f32_16x16x32_bf16 v[124:127], v[140:143], v[182:185], v[124:127]
	v_mfma_f32_16x16x32_bf16 v[120:123], v[158:161], v[182:185], v[120:123]
	v_mfma_f32_16x16x32_bf16 v[108:111], v[140:143], v[192:195], v[108:111]
	v_mfma_f32_16x16x32_bf16 v[104:107], v[158:161], v[192:195], v[104:107]
	v_mfma_f32_16x16x32_bf16 v[92:95], v[140:143], v[200:203], v[92:95]
	v_mfma_f32_16x16x32_bf16 v[88:91], v[158:161], v[200:203], v[88:91]
	v_mfma_f32_16x16x32_bf16 v[76:79], v[140:143], v[208:211], v[76:79]
	v_mfma_f32_16x16x32_bf16 v[72:75], v[158:161], v[208:211], v[72:75]
	v_mfma_f32_16x16x32_bf16 v[124:127], v[154:157], v[188:191], v[124:127]
	v_mfma_f32_16x16x32_bf16 v[120:123], v[162:165], v[188:191], v[120:123]
	v_mfma_f32_16x16x32_bf16 v[108:111], v[154:157], v[196:199], v[108:111]
	v_mfma_f32_16x16x32_bf16 v[104:107], v[162:165], v[196:199], v[104:107]
	v_mfma_f32_16x16x32_bf16 v[92:95], v[154:157], v[204:207], v[92:95]
	v_mfma_f32_16x16x32_bf16 v[88:91], v[162:165], v[204:207], v[88:91]
	v_mfma_f32_16x16x32_bf16 v[76:79], v[154:157], v[212:215], v[76:79]
	v_mfma_f32_16x16x32_bf16 v[72:75], v[162:165], v[212:215], v[72:75]
	s_setprio 0
	s_setprio 1
	v_mfma_f32_16x16x32_bf16 v[116:119], v[166:169], v[182:185], v[116:119]
	v_mfma_f32_16x16x32_bf16 v[112:115], v[174:177], v[182:185], v[112:115]
	v_mfma_f32_16x16x32_bf16 v[100:103], v[166:169], v[192:195], v[100:103]
	v_mfma_f32_16x16x32_bf16 v[96:99], v[174:177], v[192:195], v[96:99]
	v_mfma_f32_16x16x32_bf16 v[84:87], v[166:169], v[200:203], v[84:87]
	v_mfma_f32_16x16x32_bf16 v[80:83], v[174:177], v[200:203], v[80:83]
	v_mfma_f32_16x16x32_bf16 v[68:71], v[166:169], v[208:211], v[68:71]
	v_mfma_f32_16x16x32_bf16 v[64:67], v[174:177], v[208:211], v[64:67]
	v_mfma_f32_16x16x32_bf16 v[116:119], v[170:173], v[188:191], v[116:119]
	v_mfma_f32_16x16x32_bf16 v[112:115], v[178:181], v[188:191], v[112:115]
	v_mfma_f32_16x16x32_bf16 v[100:103], v[170:173], v[196:199], v[100:103]
	v_mfma_f32_16x16x32_bf16 v[96:99], v[178:181], v[196:199], v[96:99]
	v_mfma_f32_16x16x32_bf16 v[84:87], v[170:173], v[204:207], v[84:87]
	v_mfma_f32_16x16x32_bf16 v[80:83], v[178:181], v[204:207], v[80:83]
	v_mfma_f32_16x16x32_bf16 v[68:71], v[170:173], v[212:215], v[68:71]
	v_mfma_f32_16x16x32_bf16 v[64:67], v[178:181], v[212:215], v[64:67]
	s_barrier
; #define PG8_STAGE(bufoff, gbase, voff) do { _Pragma("unroll") for (int _i = 0; _i < 2; ++_i) \
;         __builtin_amdgcn_global_load_lds((const unsigned*)((const char*)(gbase) + (voff)[_i]), (PG8_LAS unsigned*)(lds + (bufoff) + ldsw + _i * 8192), 16, 0, 0); } while (0)
; #define PG8_LDA(dst, b, h) do { _Pragma("unroll") for (int m = 0; m < 4; ++m) _Pragma("unroll") for (int k = 0; k < 2; ++k) dst[m][k] = *(const PG8_LAS bf16x8*)(lds + PG8_SA(b, h) + aoff + m * 2048 + k * 1024); } while (0)
; #define PG8_MMA(ai, bj, At, Bt) do { __builtin_amdgcn_s_setprio(1); _Pragma("unroll") for (int m = 0; m < 4; ++m) _Pragma("unroll") for (int n = 0; n < 2; ++n) _Pragma("unroll") for (int k = 0; k < 2; ++k) \
;         acc[ai][bj][m][n] = __builtin_amdgcn_mfma_f32_16x16x32_bf16(Bt[n][k], At[m][k], acc[ai][bj][m][n], 0, 0, 0); __builtin_amdgcn_s_setprio(0); } while (0)
; #define PG8_WAIT_V(n) asm volatile("s_waitcnt vmcnt(" #n ")" ::: "memory")
; #define PG8_WAIT_L(n) asm volatile("s_waitcnt lgkmcnt(" #n ")" ::: "memory")
; #define PG8_BAR __builtin_amdgcn_s_barrier()
; #define PG8_SCHED __builtin_amdgcn_sched_barrier(0)
; template <class Epi, class Sched, bool ALIGN_EPI = false, bool SP2 = false>
; __device__ __forceinline__ void gemm_phase(PG8_LAS unsigned char* lds, const Gemm g, const Sched& S, const Epi& E) {
;     ...
;             PG8_LDA(At, 1, 1); PG8_STAGE(PG8_SB(1, 0), b3, voffB); PG8_STAGE(PG8_SB(1, 1), b3 + hstepB, voffB); PG8_STAGE(PG8_SA(1, 0), a3, voffA);
;             PG8_WAIT_V(8); PG8_WAIT_L(0); PG8_BAR; PG8_MMA(1, 0, At, B0); PG8_MMA(1, 1, At, B1); PG8_BAR; PG8_SCHED;
;     ...
;         if constexpr (ALIGN_EPI) { if (wr == 0) PG8_BAR; }
	s_setprio 0
	s_mov_b32 m0, s93
	v_lshl_add_u64 v[144:145], v[144:145], 0, s[12:13]
	ds_read_b128 v[182:185], v151 offset:49152
	ds_read_b128 v[188:191], v151 offset:50176
	ds_read_b128 v[192:195], v151 offset:51200
	ds_read_b128 v[196:199], v151 offset:52224
	ds_read_b128 v[200:203], v151 offset:53248
	ds_read_b128 v[204:207], v151 offset:54272
	ds_read_b128 v[208:211], v151 offset:55296
	ds_read_b128 v[212:215], v151 offset:56320
	global_load_lds_dwordx4 v[144:145], off
	v_lshl_add_u64 v[144:145], v[216:217], 0, s[12:13]
	s_mov_b32 m0, s91
	s_nop 0
	global_load_lds_dwordx4 v[144:145], off
	v_lshl_add_u64 v[144:145], s[36:37], 0, v[132:133]
	s_mov_b32 m0, s92
	s_nop 0
	global_load_lds_dwordx4 v[144:145], off
	v_lshl_add_u64 v[144:145], s[36:37], 0, v[128:129]
	s_mov_b32 m0, s90
	s_nop 0
	global_load_lds_dwordx4 v[144:145], off
	v_lshl_add_u64 v[144:145], v[218:219], 0, s[12:13]
	s_mov_b32 m0, s75
	s_nop 0
	global_load_lds_dwordx4 v[144:145], off
	v_lshl_add_u64 v[144:145], v[220:221], 0, s[12:13]
	s_mov_b32 m0, s76
	s_nop 0
	global_load_lds_dwordx4 v[144:145], off
	s_waitcnt vmcnt(8) lgkmcnt(0)
	s_barrier
	s_setprio 1
	v_mfma_f32_16x16x32_bf16 v[60:63], v[140:143], v[182:185], v[60:63]
	v_mfma_f32_16x16x32_bf16 v[56:59], v[158:161], v[182:185], v[56:59]
	v_mfma_f32_16x16x32_bf16 v[44:47], v[140:143], v[192:195], v[44:47]
	v_mfma_f32_16x16x32_bf16 v[40:43], v[158:161], v[192:195], v[40:43]
	v_mfma_f32_16x16x32_bf16 v[28:31], v[140:143], v[200:203], v[28:31]
	v_mfma_f32_16x16x32_bf16 v[24:27], v[158:161], v[200:203], v[24:27]
	v_mfma_f32_16x16x32_bf16 v[12:15], v[140:143], v[208:211], v[12:15]
	v_mfma_f32_16x16x32_bf16 v[8:11], v[158:161], v[208:211], v[8:11]
	v_mfma_f32_16x16x32_bf16 v[60:63], v[154:157], v[188:191], v[60:63]
	v_mfma_f32_16x16x32_bf16 v[56:59], v[162:165], v[188:191], v[56:59]
	v_mfma_f32_16x16x32_bf16 v[44:47], v[154:157], v[196:199], v[44:47]
	v_mfma_f32_16x16x32_bf16 v[40:43], v[162:165], v[196:199], v[40:43]
	v_mfma_f32_16x16x32_bf16 v[28:31], v[154:157], v[204:207], v[28:31]
	v_mfma_f32_16x16x32_bf16 v[24:27], v[162:165], v[204:207], v[24:27]
	v_mfma_f32_16x16x32_bf16 v[12:15], v[154:157], v[212:215], v[12:15]
	v_mfma_f32_16x16x32_bf16 v[8:11], v[162:165], v[212:215], v[8:11]
	s_setprio 0
	s_setprio 1
	v_mfma_f32_16x16x32_bf16 v[52:55], v[166:169], v[182:185], v[52:55]
	v_mfma_f32_16x16x32_bf16 v[48:51], v[174:177], v[182:185], v[48:51]
	v_mfma_f32_16x16x32_bf16 v[36:39], v[166:169], v[192:195], v[36:39]
	v_mfma_f32_16x16x32_bf16 v[32:35], v[174:177], v[192:195], v[32:35]
	v_mfma_f32_16x16x32_bf16 v[20:23], v[166:169], v[200:203], v[20:23]
	v_mfma_f32_16x16x32_bf16 v[16:19], v[174:177], v[200:203], v[16:19]
	v_mfma_f32_16x16x32_bf16 v[4:7], v[166:169], v[208:211], v[4:7]
	v_mfma_f32_16x16x32_bf16 v[0:3], v[174:177], v[208:211], v[0:3]
	v_mfma_f32_16x16x32_bf16 v[52:55], v[170:173], v[188:191], v[52:55]
	v_mfma_f32_16x16x32_bf16 v[48:51], v[178:181], v[188:191], v[48:51]
	v_mfma_f32_16x16x32_bf16 v[36:39], v[170:173], v[196:199], v[36:39]
	v_mfma_f32_16x16x32_bf16 v[32:35], v[178:181], v[196:199], v[32:35]
	v_mfma_f32_16x16x32_bf16 v[20:23], v[170:173], v[204:207], v[20:23]
	v_mfma_f32_16x16x32_bf16 v[16:19], v[178:181], v[204:207], v[16:19]
	v_mfma_f32_16x16x32_bf16 v[4:7], v[170:173], v[212:215], v[4:7]
	v_mfma_f32_16x16x32_bf16 v[0:3], v[178:181], v[212:215], v[0:3]
	s_barrier
	s_setprio 0
	s_movk_i32 s38, 0x100
	s_andn2_b64 vcc, exec, s[8:9]
	s_mov_b64 s[36:37], -1
	s_mov_b64 s[8:9], 0
	s_cbranch_vccz .LBB0_542
	s_and_b64 vcc, exec, s[14:15]
	s_cbranch_vccz .LBB0_545
	s_barrier

; #define PG8_STAGE(bufoff, gbase, voff) do { _Pragma("unroll") for (int _i = 0; _i < 2; ++_i) \
;         __builtin_amdgcn_global_load_lds((const unsigned*)((const char*)(gbase) + (voff)[_i]), (PG8_LAS unsigned*)(lds + (bufoff) + ldsw + _i * 8192), 16, 0, 0); } while (0)
; #define PG8_LDA(dst, b, h) do { _Pragma("unroll") for (int m = 0; m < 4; ++m) _Pragma("unroll") for (int k = 0; k < 2; ++k) dst[m][k] = *(const PG8_LAS bf16x8*)(lds + PG8_SA(b, h) + aoff + m * 2048 + k * 1024); } while (0)
; #define PG8_LDB(dst, b, h) do { _Pragma("unroll") for (int n = 0; n < 2; ++n) _Pragma("unroll") for (int k = 0; k < 2; ++k) dst[n][k] = *(const PG8_LAS bf16x8*)(lds + PG8_SB(b, h) + boff + n * 2048 + k * 1024); } while (0)
; #define PG8_MMA(ai, bj, At, Bt) do { __builtin_amdgcn_s_setprio(1); _Pragma("unroll") for (int m = 0; m < 4; ++m) _Pragma("unroll") for (int n = 0; n < 2; ++n) _Pragma("unroll") for (int k = 0; k < 2; ++k) \
;         acc[ai][bj][m][n] = __builtin_amdgcn_mfma_f32_16x16x32_bf16(Bt[n][k], At[m][k], acc[ai][bj][m][n], 0, 0, 0); __builtin_amdgcn_s_setprio(0); } while (0)
; #define PG8_WAIT_V(n) asm volatile("s_waitcnt vmcnt(" #n ")" ::: "memory")
; #define PG8_BAR __builtin_amdgcn_s_barrier()
; template <class Epi, class Sched, bool ALIGN_EPI = false, bool SP2 = false>
; __device__ __forceinline__ void gemm_phase(PG8_LAS unsigned char* lds, const Gemm g, const Sched& S, const Epi& E) {
;     ...
;         for (int t = 0; t < nt; t += 2) {
;             const bool last = (t == nt - 2);
;             const char* a1 = cA + (size_t)(t + 1) * kstep;
;             const char* a2 = last ? nA : cA + (size_t)(t + 2) * kstep; const char* b2 = last ? nB : cB + (size_t)(t + 2) * kstep;
;             const char* a3 = a2 + kstep; const char* b3 = b2 + kstep;
;             if (last && has_next) S.a_ready(nxt);
;             if constexpr (SP2) {
;             PG8_LDB(B0, 0, 0); PG8_LDB(B1, 0, 1); PG8_SCHED; PG8_LDA(At, 0, 0); PG8_STAGE(PG8_SA(1, 1), a1 + hstepA, voffA);
;             PG8_WAIT_V(8); PG8_WAIT_L(0); PG8_BAR; PG8_MMA(0, 0, At, B0); PG8_MMA(0, 1, At, B1); PG8_BAR; PG8_SCHED;
;             PG8_LDA(At, 0, 1); PG8_STAGE(PG8_SB(0, 0), b2, voffB); PG8_STAGE(PG8_SB(0, 1), b2 + hstepB, voffB); PG8_STAGE(PG8_SA(0, 0), a2, voffA);
;             PG8_WAIT_V(8); PG8_WAIT_L(0); PG8_BAR; PG8_MMA(1, 0, At, B0); PG8_MMA(1, 1, At, B1); PG8_BAR; PG8_SCHED;
.LBB0_971:
	ds_read_b128 v[128:131], v191
	ds_read_b128 v[132:135], v191 offset:1024
	ds_read_b128 v[136:139], v191 offset:2048
	ds_read_b128 v[140:143], v191 offset:3072
	ds_read_b128 v[144:147], v192
	ds_read_b128 v[148:151], v192 offset:1024
	ds_read_b128 v[168:171], v192 offset:2048
	ds_read_b128 v[172:175], v192 offset:3072
	s_add_u32 s34, s30, 0xfffc0080
	s_addc_u32 s35, s31, -1
	s_cmp_eq_u32 s74, 12
	s_cselect_b32 s37, s21, s35
	s_cselect_b32 s36, s27, s34
	s_cselect_b32 s35, s19, s73
	s_cselect_b32 s34, s68, s69
	v_lshl_add_u64 v[184:185], s[30:31], 0, v[160:161]
	s_add_i32 m0, s29, 0xc000
	ds_read_b128 v[176:179], v193
	ds_read_b128 v[180:183], v193 offset:1024
	ds_read_b128 v[196:199], v193 offset:2048
	ds_read_b128 v[200:203], v193 offset:3072
	ds_read_b128 v[204:207], v193 offset:4096
	ds_read_b128 v[208:211], v193 offset:5120
	ds_read_b128 v[212:215], v193 offset:6144
	ds_read_b128 v[216:219], v193 offset:7168
	global_load_lds_dwordx4 v[184:185], off
	v_lshl_add_u64 v[184:185], s[30:31], 0, v[162:163]
	s_add_i32 m0, s29, 0xe000
	s_nop 0
	global_load_lds_dwordx4 v[184:185], off
	s_waitcnt vmcnt(8) lgkmcnt(0)
	s_barrier
	s_setprio 1
	v_mfma_f32_16x16x32_bf16 v[124:127], v[128:131], v[176:179], v[124:127]
	v_mfma_f32_16x16x32_bf16 v[120:123], v[136:139], v[176:179], v[120:123]
	v_mfma_f32_16x16x32_bf16 v[108:111], v[128:131], v[196:199], v[108:111]
	v_mfma_f32_16x16x32_bf16 v[104:107], v[136:139], v[196:199], v[104:107]
	v_mfma_f32_16x16x32_bf16 v[92:95], v[128:131], v[204:207], v[92:95]
	v_mfma_f32_16x16x32_bf16 v[88:91], v[136:139], v[204:207], v[88:91]
	v_mfma_f32_16x16x32_bf16 v[76:79], v[128:131], v[212:215], v[76:79]
	v_mfma_f32_16x16x32_bf16 v[72:75], v[136:139], v[212:215], v[72:75]
	v_mfma_f32_16x16x32_bf16 v[124:127], v[132:135], v[180:183], v[124:127]
	v_mfma_f32_16x16x32_bf16 v[120:123], v[140:143], v[180:183], v[120:123]
	v_mfma_f32_16x16x32_bf16 v[108:111], v[132:135], v[200:203], v[108:111]
	v_mfma_f32_16x16x32_bf16 v[104:107], v[140:143], v[200:203], v[104:107]
	v_mfma_f32_16x16x32_bf16 v[92:95], v[132:135], v[208:211], v[92:95]
	v_mfma_f32_16x16x32_bf16 v[88:91], v[140:143], v[208:211], v[88:91]
	v_mfma_f32_16x16x32_bf16 v[76:79], v[132:135], v[216:219], v[76:79]
	v_mfma_f32_16x16x32_bf16 v[72:75], v[140:143], v[216:219], v[72:75]
	s_setprio 0
	s_setprio 1
	v_mfma_f32_16x16x32_bf16 v[116:119], v[144:147], v[176:179], v[116:119]
	v_mfma_f32_16x16x32_bf16 v[112:115], v[168:171], v[176:179], v[112:115]
	v_mfma_f32_16x16x32_bf16 v[100:103], v[144:147], v[196:199], v[100:103]
	v_mfma_f32_16x16x32_bf16 v[96:99], v[168:171], v[196:199], v[96:99]
	v_mfma_f32_16x16x32_bf16 v[84:87], v[144:147], v[204:207], v[84:87]
	v_mfma_f32_16x16x32_bf16 v[80:83], v[168:171], v[204:207], v[80:83]
	v_mfma_f32_16x16x32_bf16 v[68:71], v[144:147], v[212:215], v[68:71]
	v_mfma_f32_16x16x32_bf16 v[64:67], v[168:171], v[212:215], v[64:67]
	v_mfma_f32_16x16x32_bf16 v[116:119], v[148:151], v[180:183], v[116:119]
	v_mfma_f32_16x16x32_bf16 v[112:115], v[172:175], v[180:183], v[112:115]
	v_mfma_f32_16x16x32_bf16 v[100:103], v[148:151], v[200:203], v[100:103]
	v_mfma_f32_16x16x32_bf16 v[96:99], v[172:175], v[200:203], v[96:99]
	v_mfma_f32_16x16x32_bf16 v[84:87], v[148:151], v[208:211], v[84:87]
	v_mfma_f32_16x16x32_bf16 v[80:83], v[172:175], v[208:211], v[80:83]
	v_mfma_f32_16x16x32_bf16 v[68:71], v[148:151], v[216:219], v[68:71]
	v_mfma_f32_16x16x32_bf16 v[64:67], v[172:175], v[216:219], v[64:67]
	s_barrier
	s_setprio 0
	s_add_i32 s58, s49, s39
	v_lshl_add_u64 v[184:185], s[34:35], 0, v[154:155]
	s_mov_b32 m0, s58
	ds_read_b128 v[176:179], v193 offset:16384
	ds_read_b128 v[180:183], v193 offset:17408
	ds_read_b128 v[196:199], v193 offset:18432
	ds_read_b128 v[200:203], v193 offset:19456
	ds_read_b128 v[204:207], v193 offset:20480
	ds_read_b128 v[208:211], v193 offset:21504
	ds_read_b128 v[212:215], v193 offset:22528
	ds_read_b128 v[216:219], v193 offset:23552
	global_load_lds_dwordx4 v[184:185], off
	s_add_i32 m0, s58, 0x2000
	s_add_u32 s58, s34, 0x40000
	v_lshl_add_u64 v[220:221], s[34:35], 0, v[158:159]
	s_addc_u32 s59, s35, 0
	s_add_i32 s75, s66, s39
	global_load_lds_dwordx4 v[220:221], off
	v_lshl_add_u64 v[222:223], s[58:59], 0, v[154:155]
	s_mov_b32 m0, s75
	v_lshl_add_u64 v[224:225], s[36:37], 0, v[156:157]
	global_load_lds_dwordx4 v[222:223], off
	v_lshl_add_u64 v[222:223], s[58:59], 0, v[158:159]
	s_add_i32 m0, s75, 0x2000
	s_nop 0
	global_load_lds_dwordx4 v[222:223], off
	v_lshl_add_u64 v[222:223], s[36:37], 0, v[152:153]
	s_mov_b32 m0, s29
	s_nop 0
	global_load_lds_dwordx4 v[222:223], off
	s_mov_b32 m0, s40
	s_nop 0
	global_load_lds_dwordx4 v[224:225], off
	s_waitcnt vmcnt(8) lgkmcnt(0)
	s_barrier
; #define PG8_STAGE(bufoff, gbase, voff) do { _Pragma("unroll") for (int _i = 0; _i < 2; ++_i) \
;         __builtin_amdgcn_global_load_lds((const unsigned*)((const char*)(gbase) + (voff)[_i]), (PG8_LAS unsigned*)(lds + (bufoff) + ldsw + _i * 8192), 16, 0, 0); } while (0)
; #define PG8_LDA(dst, b, h) do { _Pragma("unroll") for (int m = 0; m < 4; ++m) _Pragma("unroll") for (int k = 0; k < 2; ++k) dst[m][k] = *(const PG8_LAS bf16x8*)(lds + PG8_SA(b, h) + aoff + m * 2048 + k * 1024); } while (0)
; #define PG8_LDB(dst, b, h) do { _Pragma("unroll") for (int n = 0; n < 2; ++n) _Pragma("unroll") for (int k = 0; k < 2; ++k) dst[n][k] = *(const PG8_LAS bf16x8*)(lds + PG8_SB(b, h) + boff + n * 2048 + k * 1024); } while (0)
; #define PG8_MMA(ai, bj, At, Bt) do { __builtin_amdgcn_s_setprio(1); _Pragma("unroll") for (int m = 0; m < 4; ++m) _Pragma("unroll") for (int n = 0; n < 2; ++n) _Pragma("unroll") for (int k = 0; k < 2; ++k) \
;         acc[ai][bj][m][n] = __builtin_amdgcn_mfma_f32_16x16x32_bf16(Bt[n][k], At[m][k], acc[ai][bj][m][n], 0, 0, 0); __builtin_amdgcn_s_setprio(0); } while (0)
; #define PG8_WAIT_V(n) asm volatile("s_waitcnt vmcnt(" #n ")" ::: "memory")
; #define PG8_WAIT_L(n) asm volatile("s_waitcnt lgkmcnt(" #n ")" ::: "memory")
; #define PG8_BAR __builtin_amdgcn_s_barrier()
; #define PG8_SCHED __builtin_amdgcn_sched_barrier(0)
; template <class Epi, class Sched, bool ALIGN_EPI = false, bool SP2 = false>
; __device__ __forceinline__ void gemm_phase(PG8_LAS unsigned char* lds, const Gemm g, const Sched& S, const Epi& E) {
;     ...
;             PG8_WAIT_V(8); PG8_WAIT_L(0); PG8_BAR; PG8_MMA(1, 0, At, B0); PG8_MMA(1, 1, At, B1); PG8_BAR; PG8_SCHED;
;             PG8_LDB(B0, 1, 0); PG8_LDB(B1, 1, 1); PG8_SCHED; PG8_LDA(At, 1, 0); PG8_STAGE(PG8_SA(0, 1), a2 + hstepA, voffA);
;             PG8_WAIT_V(8); PG8_WAIT_L(0); PG8_BAR; PG8_MMA(0, 0, At, B0); PG8_MMA(0, 1, At, B1); PG8_BAR; PG8_SCHED;
	s_setprio 1
	v_mfma_f32_16x16x32_bf16 v[60:63], v[128:131], v[176:179], v[60:63]
	v_mfma_f32_16x16x32_bf16 v[56:59], v[136:139], v[176:179], v[56:59]
	v_mfma_f32_16x16x32_bf16 v[44:47], v[128:131], v[196:199], v[44:47]
	v_mfma_f32_16x16x32_bf16 v[40:43], v[136:139], v[196:199], v[40:43]
	v_mfma_f32_16x16x32_bf16 v[28:31], v[128:131], v[204:207], v[28:31]
	v_mfma_f32_16x16x32_bf16 v[24:27], v[136:139], v[204:207], v[24:27]
	v_mfma_f32_16x16x32_bf16 v[12:15], v[128:131], v[212:215], v[12:15]
	v_mfma_f32_16x16x32_bf16 v[8:11], v[136:139], v[212:215], v[8:11]
	v_mfma_f32_16x16x32_bf16 v[60:63], v[132:135], v[180:183], v[60:63]
	v_mfma_f32_16x16x32_bf16 v[56:59], v[140:143], v[180:183], v[56:59]
	v_mfma_f32_16x16x32_bf16 v[44:47], v[132:135], v[200:203], v[44:47]
	v_mfma_f32_16x16x32_bf16 v[40:43], v[140:143], v[200:203], v[40:43]
	v_mfma_f32_16x16x32_bf16 v[28:31], v[132:135], v[208:211], v[28:31]
	v_mfma_f32_16x16x32_bf16 v[24:27], v[140:143], v[208:211], v[24:27]
	v_mfma_f32_16x16x32_bf16 v[12:15], v[132:135], v[216:219], v[12:15]
	v_mfma_f32_16x16x32_bf16 v[8:11], v[140:143], v[216:219], v[8:11]
	s_setprio 0
	s_setprio 1
	v_mfma_f32_16x16x32_bf16 v[52:55], v[144:147], v[176:179], v[52:55]
	v_mfma_f32_16x16x32_bf16 v[48:51], v[168:171], v[176:179], v[48:51]
	v_mfma_f32_16x16x32_bf16 v[36:39], v[144:147], v[196:199], v[36:39]
	v_mfma_f32_16x16x32_bf16 v[32:35], v[168:171], v[196:199], v[32:35]
	v_mfma_f32_16x16x32_bf16 v[20:23], v[144:147], v[204:207], v[20:23]
	v_mfma_f32_16x16x32_bf16 v[16:19], v[168:171], v[204:207], v[16:19]
	v_mfma_f32_16x16x32_bf16 v[4:7], v[144:147], v[212:215], v[4:7]
	v_mfma_f32_16x16x32_bf16 v[0:3], v[168:171], v[212:215], v[0:3]
	v_mfma_f32_16x16x32_bf16 v[52:55], v[148:151], v[180:183], v[52:55]
	v_mfma_f32_16x16x32_bf16 v[48:51], v[172:175], v[180:183], v[48:51]
	v_mfma_f32_16x16x32_bf16 v[36:39], v[148:151], v[200:203], v[36:39]
	v_mfma_f32_16x16x32_bf16 v[32:35], v[172:175], v[200:203], v[32:35]
	v_mfma_f32_16x16x32_bf16 v[20:23], v[148:151], v[208:211], v[20:23]
	v_mfma_f32_16x16x32_bf16 v[16:19], v[172:175], v[208:211], v[16:19]
	v_mfma_f32_16x16x32_bf16 v[4:7], v[148:151], v[216:219], v[4:7]
	v_mfma_f32_16x16x32_bf16 v[0:3], v[172:175], v[216:219], v[0:3]
	s_barrier
	s_setprio 0
	s_add_i32 s58, 0, 0x18000
	s_add_i32 s59, 0, 0x1c000
	v_add_u32_e32 v140, s58, v189
	v_add_u32_e32 v172, s59, v189
	ds_read_b128 v[128:131], v140
	ds_read_b128 v[132:135], v140 offset:1024
	ds_read_b128 v[136:139], v140 offset:2048
	ds_read_b128 v[140:143], v140 offset:3072
	ds_read_b128 v[144:147], v172
	ds_read_b128 v[148:151], v172 offset:1024
	ds_read_b128 v[168:171], v172 offset:2048
	ds_read_b128 v[172:175], v172 offset:3072
	s_add_u32 s36, s36, 0x40000
	s_addc_u32 s37, s37, 0
	s_mov_b32 m0, s41
	v_lshl_add_u64 v[226:227], s[36:37], 0, v[152:153]
	ds_read_b128 v[176:179], v193 offset:32768
	ds_read_b128 v[180:183], v193 offset:33792
	ds_read_b128 v[196:199], v193 offset:34816
	ds_read_b128 v[200:203], v193 offset:35840
	ds_read_b128 v[204:207], v193 offset:36864
	ds_read_b128 v[208:211], v193 offset:37888
	ds_read_b128 v[212:215], v193 offset:38912
	ds_read_b128 v[216:219], v193 offset:39936
	global_load_lds_dwordx4 v[226:227], off
	v_lshl_add_u64 v[226:227], s[36:37], 0, v[156:157]
	s_mov_b32 m0, s42
	s_nop 0
	global_load_lds_dwordx4 v[226:227], off
	s_waitcnt vmcnt(8) lgkmcnt(0)
	s_barrier
	s_setprio 1
	v_mfma_f32_16x16x32_bf16 v[124:127], v[128:131], v[176:179], v[124:127]
	v_mfma_f32_16x16x32_bf16 v[120:123], v[136:139], v[176:179], v[120:123]
	v_mfma_f32_16x16x32_bf16 v[108:111], v[128:131], v[196:199], v[108:111]
	v_mfma_f32_16x16x32_bf16 v[104:107], v[136:139], v[196:199], v[104:107]
	v_mfma_f32_16x16x32_bf16 v[92:95], v[128:131], v[204:207], v[92:95]
	v_mfma_f32_16x16x32_bf16 v[88:91], v[136:139], v[204:207], v[88:91]
	v_mfma_f32_16x16x32_bf16 v[76:79], v[128:131], v[212:215], v[76:79]
	v_mfma_f32_16x16x32_bf16 v[72:75], v[136:139], v[212:215], v[72:75]
	v_mfma_f32_16x16x32_bf16 v[124:127], v[132:135], v[180:183], v[124:127]
	v_mfma_f32_16x16x32_bf16 v[120:123], v[140:143], v[180:183], v[120:123]
	v_mfma_f32_16x16x32_bf16 v[108:111], v[132:135], v[200:203], v[108:111]
	v_mfma_f32_16x16x32_bf16 v[104:107], v[140:143], v[200:203], v[104:107]
	v_mfma_f32_16x16x32_bf16 v[92:95], v[132:135], v[208:211], v[92:95]
	v_mfma_f32_16x16x32_bf16 v[88:91], v[140:143], v[208:211], v[88:91]
	v_mfma_f32_16x16x32_bf16 v[76:79], v[132:135], v[216:219], v[76:79]
	v_mfma_f32_16x16x32_bf16 v[72:75], v[140:143], v[216:219], v[72:75]
	s_setprio 0
	s_setprio 1
	v_mfma_f32_16x16x32_bf16 v[116:119], v[144:147], v[176:179], v[116:119]
	v_mfma_f32_16x16x32_bf16 v[112:115], v[168:171], v[176:179], v[112:115]
	v_mfma_f32_16x16x32_bf16 v[100:103], v[144:147], v[196:199], v[100:103]
	v_mfma_f32_16x16x32_bf16 v[96:99], v[168:171], v[196:199], v[96:99]
	v_mfma_f32_16x16x32_bf16 v[84:87], v[144:147], v[204:207], v[84:87]
	v_mfma_f32_16x16x32_bf16 v[80:83], v[168:171], v[204:207], v[80:83]
	v_mfma_f32_16x16x32_bf16 v[68:71], v[144:147], v[212:215], v[68:71]
	v_mfma_f32_16x16x32_bf16 v[64:67], v[168:171], v[212:215], v[64:67]
	v_mfma_f32_16x16x32_bf16 v[116:119], v[148:151], v[180:183], v[116:119]
	v_mfma_f32_16x16x32_bf16 v[112:115], v[172:175], v[180:183], v[112:115]
	v_mfma_f32_16x16x32_bf16 v[100:103], v[148:151], v[200:203], v[100:103]
	v_mfma_f32_16x16x32_bf16 v[96:99], v[172:175], v[200:203], v[96:99]
	v_mfma_f32_16x16x32_bf16 v[84:87], v[148:151], v[208:211], v[84:87]
	v_mfma_f32_16x16x32_bf16 v[80:83], v[172:175], v[208:211], v[80:83]
	v_mfma_f32_16x16x32_bf16 v[68:71], v[148:151], v[216:219], v[68:71]
	v_mfma_f32_16x16x32_bf16 v[64:67], v[172:175], v[216:219], v[64:67]
	s_barrier
; #define PG8_STAGE(bufoff, gbase, voff) do { _Pragma("unroll") for (int _i = 0; _i < 2; ++_i) \
;         __builtin_amdgcn_global_load_lds((const unsigned*)((const char*)(gbase) + (voff)[_i]), (PG8_LAS unsigned*)(lds + (bufoff) + ldsw + _i * 8192), 16, 0, 0); } while (0)
; #define PG8_LDA(dst, b, h) do { _Pragma("unroll") for (int m = 0; m < 4; ++m) _Pragma("unroll") for (int k = 0; k < 2; ++k) dst[m][k] = *(const PG8_LAS bf16x8*)(lds + PG8_SA(b, h) + aoff + m * 2048 + k * 1024); } while (0)
; #define PG8_MMA(ai, bj, At, Bt) do { __builtin_amdgcn_s_setprio(1); _Pragma("unroll") for (int m = 0; m < 4; ++m) _Pragma("unroll") for (int n = 0; n < 2; ++n) _Pragma("unroll") for (int k = 0; k < 2; ++k) \
;         acc[ai][bj][m][n] = __builtin_amdgcn_mfma_f32_16x16x32_bf16(Bt[n][k], At[m][k], acc[ai][bj][m][n], 0, 0, 0); __builtin_amdgcn_s_setprio(0); } while (0)
; #define PG8_WAIT_V(n) asm volatile("s_waitcnt vmcnt(" #n ")" ::: "memory")
; #define PG8_WAIT_L(n) asm volatile("s_waitcnt lgkmcnt(" #n ")" ::: "memory")
; #define PG8_BAR __builtin_amdgcn_s_barrier()
; #define PG8_SCHED __builtin_amdgcn_sched_barrier(0)
; template <class Epi, class Sched, bool ALIGN_EPI = false, bool SP2 = false>
; __device__ __forceinline__ void gemm_phase(PG8_LAS unsigned char* lds, const Gemm g, const Sched& S, const Epi& E) {
;     ...
;             PG8_LDA(At, 1, 1); PG8_STAGE(PG8_SB(1, 0), b3, voffB); PG8_STAGE(PG8_SB(1, 1), b3 + hstepB, voffB); PG8_STAGE(PG8_SA(1, 0), a3, voffA);
;             PG8_WAIT_V(8); PG8_WAIT_L(0); PG8_BAR; PG8_MMA(1, 0, At, B0); PG8_MMA(1, 1, At, B1); PG8_BAR; PG8_SCHED;
;     ...
;         if constexpr (ALIGN_EPI) { if (wr == 0) PG8_BAR; }
	s_setprio 0
	s_add_i32 s36, s58, s39
	v_lshl_add_u64 v[184:185], v[184:185], 0, s[14:15]
	s_mov_b32 m0, s36
	ds_read_b128 v[176:179], v193 offset:49152
	ds_read_b128 v[180:183], v193 offset:50176
	ds_read_b128 v[196:199], v193 offset:51200
	ds_read_b128 v[200:203], v193 offset:52224
	ds_read_b128 v[204:207], v193 offset:53248
	ds_read_b128 v[208:211], v193 offset:54272
	ds_read_b128 v[212:215], v193 offset:55296
	ds_read_b128 v[216:219], v193 offset:56320
	global_load_lds_dwordx4 v[184:185], off
	s_add_i32 m0, s36, 0x2000
	s_add_u32 s34, s34, 0x40080
	v_lshl_add_u64 v[184:185], v[220:221], 0, s[14:15]
	s_addc_u32 s35, s35, 0
	s_add_i32 s36, s59, s39
	global_load_lds_dwordx4 v[184:185], off
	v_lshl_add_u64 v[184:185], s[34:35], 0, v[154:155]
	s_mov_b32 m0, s36
	s_nop 0
	global_load_lds_dwordx4 v[184:185], off
	v_lshl_add_u64 v[184:185], s[34:35], 0, v[158:159]
	s_add_i32 m0, s36, 0x2000
	s_nop 0
	global_load_lds_dwordx4 v[184:185], off
	v_lshl_add_u64 v[184:185], v[222:223], 0, s[14:15]
	s_mov_b32 m0, s44
	s_nop 0
	global_load_lds_dwordx4 v[184:185], off
	v_lshl_add_u64 v[184:185], v[224:225], 0, s[14:15]
	s_mov_b32 m0, s45
	s_nop 0
	global_load_lds_dwordx4 v[184:185], off
	s_waitcnt vmcnt(8) lgkmcnt(0)
	s_barrier
	s_setprio 1
	v_mfma_f32_16x16x32_bf16 v[60:63], v[128:131], v[176:179], v[60:63]
	v_mfma_f32_16x16x32_bf16 v[56:59], v[136:139], v[176:179], v[56:59]
	v_mfma_f32_16x16x32_bf16 v[44:47], v[128:131], v[196:199], v[44:47]
	v_mfma_f32_16x16x32_bf16 v[40:43], v[136:139], v[196:199], v[40:43]
	v_mfma_f32_16x16x32_bf16 v[28:31], v[128:131], v[204:207], v[28:31]
	v_mfma_f32_16x16x32_bf16 v[24:27], v[136:139], v[204:207], v[24:27]
	v_mfma_f32_16x16x32_bf16 v[12:15], v[128:131], v[212:215], v[12:15]
	v_mfma_f32_16x16x32_bf16 v[8:11], v[136:139], v[212:215], v[8:11]
	v_mfma_f32_16x16x32_bf16 v[60:63], v[132:135], v[180:183], v[60:63]
	v_mfma_f32_16x16x32_bf16 v[56:59], v[140:143], v[180:183], v[56:59]
	v_mfma_f32_16x16x32_bf16 v[44:47], v[132:135], v[200:203], v[44:47]
	v_mfma_f32_16x16x32_bf16 v[40:43], v[140:143], v[200:203], v[40:43]
	v_mfma_f32_16x16x32_bf16 v[28:31], v[132:135], v[208:211], v[28:31]
	v_mfma_f32_16x16x32_bf16 v[24:27], v[140:143], v[208:211], v[24:27]
	v_mfma_f32_16x16x32_bf16 v[12:15], v[132:135], v[216:219], v[12:15]
	v_mfma_f32_16x16x32_bf16 v[8:11], v[140:143], v[216:219], v[8:11]
	s_setprio 0
	s_setprio 1
	v_mfma_f32_16x16x32_bf16 v[52:55], v[144:147], v[176:179], v[52:55]
	v_mfma_f32_16x16x32_bf16 v[48:51], v[168:171], v[176:179], v[48:51]
	v_mfma_f32_16x16x32_bf16 v[36:39], v[144:147], v[196:199], v[36:39]
	v_mfma_f32_16x16x32_bf16 v[32:35], v[168:171], v[196:199], v[32:35]
	v_mfma_f32_16x16x32_bf16 v[20:23], v[144:147], v[204:207], v[20:23]
	v_mfma_f32_16x16x32_bf16 v[16:19], v[168:171], v[204:207], v[16:19]
	v_mfma_f32_16x16x32_bf16 v[4:7], v[144:147], v[212:215], v[4:7]
	v_mfma_f32_16x16x32_bf16 v[0:3], v[168:171], v[212:215], v[0:3]
	v_mfma_f32_16x16x32_bf16 v[52:55], v[148:151], v[180:183], v[52:55]
	v_mfma_f32_16x16x32_bf16 v[48:51], v[172:175], v[180:183], v[48:51]
	v_mfma_f32_16x16x32_bf16 v[36:39], v[148:151], v[200:203], v[36:39]
	v_mfma_f32_16x16x32_bf16 v[32:35], v[172:175], v[200:203], v[32:35]
	v_mfma_f32_16x16x32_bf16 v[20:23], v[148:151], v[208:211], v[20:23]
	v_mfma_f32_16x16x32_bf16 v[16:19], v[172:175], v[208:211], v[16:19]
	v_mfma_f32_16x16x32_bf16 v[4:7], v[148:151], v[216:219], v[4:7]
	v_mfma_f32_16x16x32_bf16 v[0:3], v[172:175], v[216:219], v[0:3]
	s_barrier
	s_setprio 0
	s_add_i32 s74, s74, 2
	s_add_u32 s30, s30, 0x100
	s_addc_u32 s31, s31, 0
	s_add_u32 s69, s69, 0x100
	s_addc_u32 s73, s73, 0
	s_cmp_gt_u32 s74, 13
	s_cbranch_scc0 .LBB0_971
	s_and_b64 vcc, exec, s[16:17]
	s_cbranch_vccz .LBB0_974
	s_barrier

; #define PG8_STAGE(bufoff, gbase, voff) do { _Pragma("unroll") for (int _i = 0; _i < 2; ++_i) \
;         __builtin_amdgcn_global_load_lds((const unsigned*)((const char*)(gbase) + (voff)[_i]), (PG8_LAS unsigned*)(lds + (bufoff) + ldsw + _i * 8192), 16, 0, 0); } while (0)
; #define PG8_LDA(dst, b, h) do { _Pragma("unroll") for (int m = 0; m < 4; ++m) _Pragma("unroll") for (int k = 0; k < 2; ++k) dst[m][k] = *(const PG8_LAS bf16x8*)(lds + PG8_SA(b, h) + aoff + m * 2048 + k * 1024); } while (0)
; #define PG8_LDB(dst, b, h) do { _Pragma("unroll") for (int n = 0; n < 2; ++n) _Pragma("unroll") for (int k = 0; k < 2; ++k) dst[n][k] = *(const PG8_LAS bf16x8*)(lds + PG8_SB(b, h) + boff + n * 2048 + k * 1024); } while (0)
; #define PG8_MMA(ai, bj, At, Bt) do { __builtin_amdgcn_s_setprio(1); _Pragma("unroll") for (int m = 0; m < 4; ++m) _Pragma("unroll") for (int n = 0; n < 2; ++n) _Pragma("unroll") for (int k = 0; k < 2; ++k) \
;         acc[ai][bj][m][n] = __builtin_amdgcn_mfma_f32_16x16x32_bf16(Bt[n][k], At[m][k], acc[ai][bj][m][n], 0, 0, 0); __builtin_amdgcn_s_setprio(0); } while (0)
; #define PG8_WAIT_V(n) asm volatile("s_waitcnt vmcnt(" #n ")" ::: "memory")
; #define PG8_BAR __builtin_amdgcn_s_barrier()
; template <class Epi, class Sched, bool ALIGN_EPI = false, bool SP2 = false>
; __device__ __forceinline__ void gemm_phase(PG8_LAS unsigned char* lds, const Gemm g, const Sched& S, const Epi& E) {
;     ...
;         for (int t = 0; t < nt; t += 2) {
;             const bool last = (t == nt - 2);
;             const char* a1 = cA + (size_t)(t + 1) * kstep;
;             const char* a2 = last ? nA : cA + (size_t)(t + 2) * kstep; const char* b2 = last ? nB : cB + (size_t)(t + 2) * kstep;
;             const char* a3 = a2 + kstep; const char* b3 = b2 + kstep;
;             if (last && has_next) S.a_ready(nxt);
;             if constexpr (SP2) {
;             PG8_LDB(B0, 0, 0); PG8_LDB(B1, 0, 1); PG8_SCHED; PG8_LDA(At, 0, 0); PG8_STAGE(PG8_SA(1, 1), a1 + hstepA, voffA);
;             PG8_WAIT_V(8); PG8_WAIT_L(0); PG8_BAR; PG8_MMA(0, 0, At, B0); PG8_MMA(0, 1, At, B1); PG8_BAR; PG8_SCHED;
;             PG8_LDA(At, 0, 1); PG8_STAGE(PG8_SB(0, 0), b2, voffB); PG8_STAGE(PG8_SB(0, 1), b2 + hstepB, voffB); PG8_STAGE(PG8_SA(0, 0), a2, voffA);
;             PG8_WAIT_V(8); PG8_WAIT_L(0); PG8_BAR; PG8_MMA(1, 0, At, B0); PG8_MMA(1, 1, At, B1); PG8_BAR; PG8_SCHED;
.LBB0_1055:
	ds_read_b128 v[144:147], v153
	ds_read_b128 v[158:161], v153 offset:1024
	ds_read_b128 v[162:165], v153 offset:2048
	ds_read_b128 v[166:169], v153 offset:3072
	ds_read_b128 v[170:173], v154
	ds_read_b128 v[174:177], v154 offset:1024
	ds_read_b128 v[178:181], v154 offset:2048
	ds_read_b128 v[182:185], v154 offset:3072
	s_add_u32 s28, s26, 0xfffc0080
	s_addc_u32 s29, s27, -1
	s_cmp_eq_u32 s69, 12
	s_cselect_b32 s31, s19, s29
	s_cselect_b32 s30, s49, s28
	s_cselect_b32 s29, s17, s68
	s_cselect_b32 s28, s66, s67
	v_lshl_add_u64 v[148:149], s[26:27], 0, v[136:137]
	s_add_i32 m0, s25, 0xc000
	ds_read_b128 v[188:191], v155
	ds_read_b128 v[192:195], v155 offset:1024
	ds_read_b128 v[196:199], v155 offset:2048
	ds_read_b128 v[200:203], v155 offset:3072
	ds_read_b128 v[204:207], v155 offset:4096
	ds_read_b128 v[208:211], v155 offset:5120
	ds_read_b128 v[212:215], v155 offset:6144
	ds_read_b128 v[216:219], v155 offset:7168
	global_load_lds_dwordx4 v[148:149], off
	v_lshl_add_u64 v[148:149], s[26:27], 0, v[138:139]
	s_add_i32 m0, s25, 0xe000
	s_nop 0
	global_load_lds_dwordx4 v[148:149], off
	s_waitcnt vmcnt(8) lgkmcnt(0)
	s_barrier
	s_setprio 1
	v_mfma_f32_16x16x32_bf16 v[116:119], v[144:147], v[188:191], v[116:119]
	v_mfma_f32_16x16x32_bf16 v[112:115], v[162:165], v[188:191], v[112:115]
	v_mfma_f32_16x16x32_bf16 v[108:111], v[144:147], v[196:199], v[108:111]
	v_mfma_f32_16x16x32_bf16 v[100:103], v[162:165], v[196:199], v[100:103]
	v_mfma_f32_16x16x32_bf16 v[92:95], v[144:147], v[204:207], v[92:95]
	v_mfma_f32_16x16x32_bf16 v[84:87], v[162:165], v[204:207], v[84:87]
	v_mfma_f32_16x16x32_bf16 v[76:79], v[144:147], v[212:215], v[76:79]
	v_mfma_f32_16x16x32_bf16 v[68:71], v[162:165], v[212:215], v[68:71]
	v_mfma_f32_16x16x32_bf16 v[116:119], v[158:161], v[192:195], v[116:119]
	v_mfma_f32_16x16x32_bf16 v[112:115], v[166:169], v[192:195], v[112:115]
	v_mfma_f32_16x16x32_bf16 v[108:111], v[158:161], v[200:203], v[108:111]
	v_mfma_f32_16x16x32_bf16 v[100:103], v[166:169], v[200:203], v[100:103]
	v_mfma_f32_16x16x32_bf16 v[92:95], v[158:161], v[208:211], v[92:95]
	v_mfma_f32_16x16x32_bf16 v[84:87], v[166:169], v[208:211], v[84:87]
	v_mfma_f32_16x16x32_bf16 v[76:79], v[158:161], v[216:219], v[76:79]
	v_mfma_f32_16x16x32_bf16 v[68:71], v[166:169], v[216:219], v[68:71]
	s_setprio 0
	s_setprio 1
	v_mfma_f32_16x16x32_bf16 v[124:127], v[170:173], v[188:191], v[124:127]
	v_mfma_f32_16x16x32_bf16 v[120:123], v[178:181], v[188:191], v[120:123]
	v_mfma_f32_16x16x32_bf16 v[104:107], v[170:173], v[196:199], v[104:107]
	v_mfma_f32_16x16x32_bf16 v[96:99], v[178:181], v[196:199], v[96:99]
	v_mfma_f32_16x16x32_bf16 v[88:91], v[170:173], v[204:207], v[88:91]
	v_mfma_f32_16x16x32_bf16 v[80:83], v[178:181], v[204:207], v[80:83]
	v_mfma_f32_16x16x32_bf16 v[72:75], v[170:173], v[212:215], v[72:75]
	v_mfma_f32_16x16x32_bf16 v[64:67], v[178:181], v[212:215], v[64:67]
	v_mfma_f32_16x16x32_bf16 v[124:127], v[174:177], v[192:195], v[124:127]
	v_mfma_f32_16x16x32_bf16 v[120:123], v[182:185], v[192:195], v[120:123]
	v_mfma_f32_16x16x32_bf16 v[104:107], v[174:177], v[200:203], v[104:107]
	v_mfma_f32_16x16x32_bf16 v[96:99], v[182:185], v[200:203], v[96:99]
	v_mfma_f32_16x16x32_bf16 v[88:91], v[174:177], v[208:211], v[88:91]
	v_mfma_f32_16x16x32_bf16 v[80:83], v[182:185], v[208:211], v[80:83]
	v_mfma_f32_16x16x32_bf16 v[72:75], v[174:177], v[216:219], v[72:75]
	v_mfma_f32_16x16x32_bf16 v[64:67], v[182:185], v[216:219], v[64:67]
	s_barrier
	s_setprio 0
	s_add_i32 s58, s45, s35
	v_lshl_add_u64 v[148:149], s[28:29], 0, v[132:133]
	s_mov_b32 m0, s58
	ds_read_b128 v[188:191], v155 offset:16384
	ds_read_b128 v[192:195], v155 offset:17408
	ds_read_b128 v[196:199], v155 offset:18432
	ds_read_b128 v[200:203], v155 offset:19456
	ds_read_b128 v[204:207], v155 offset:20480
	ds_read_b128 v[208:211], v155 offset:21504
	ds_read_b128 v[212:215], v155 offset:22528
	ds_read_b128 v[216:219], v155 offset:23552
	global_load_lds_dwordx4 v[148:149], off
	s_add_i32 m0, s58, 0x2000
	s_add_u32 s58, s28, 0x40000
	v_lshl_add_u64 v[220:221], s[28:29], 0, v[128:129]
	s_addc_u32 s59, s29, 0
	s_add_i32 s73, s46, s35
	global_load_lds_dwordx4 v[220:221], off
	v_lshl_add_u64 v[222:223], s[58:59], 0, v[132:133]
	s_mov_b32 m0, s73
	v_lshl_add_u64 v[224:225], s[30:31], 0, v[130:131]
	global_load_lds_dwordx4 v[222:223], off
	v_lshl_add_u64 v[222:223], s[58:59], 0, v[128:129]
	s_add_i32 m0, s73, 0x2000
	s_nop 0
	global_load_lds_dwordx4 v[222:223], off
	v_lshl_add_u64 v[222:223], s[30:31], 0, v[134:135]
	s_mov_b32 m0, s25
	s_nop 0
	global_load_lds_dwordx4 v[222:223], off
	s_mov_b32 m0, s38
	s_nop 0
	global_load_lds_dwordx4 v[224:225], off
	s_waitcnt vmcnt(8) lgkmcnt(0)
	s_barrier
; #define PG8_STAGE(bufoff, gbase, voff) do { _Pragma("unroll") for (int _i = 0; _i < 2; ++_i) \
;         __builtin_amdgcn_global_load_lds((const unsigned*)((const char*)(gbase) + (voff)[_i]), (PG8_LAS unsigned*)(lds + (bufoff) + ldsw + _i * 8192), 16, 0, 0); } while (0)
; #define PG8_LDA(dst, b, h) do { _Pragma("unroll") for (int m = 0; m < 4; ++m) _Pragma("unroll") for (int k = 0; k < 2; ++k) dst[m][k] = *(const PG8_LAS bf16x8*)(lds + PG8_SA(b, h) + aoff + m * 2048 + k * 1024); } while (0)
; #define PG8_LDB(dst, b, h) do { _Pragma("unroll") for (int n = 0; n < 2; ++n) _Pragma("unroll") for (int k = 0; k < 2; ++k) dst[n][k] = *(const PG8_LAS bf16x8*)(lds + PG8_SB(b, h) + boff + n * 2048 + k * 1024); } while (0)
; #define PG8_MMA(ai, bj, At, Bt) do { __builtin_amdgcn_s_setprio(1); _Pragma("unroll") for (int m = 0; m < 4; ++m) _Pragma("unroll") for (int n = 0; n < 2; ++n) _Pragma("unroll") for (int k = 0; k < 2; ++k) \
;         acc[ai][bj][m][n] = __builtin_amdgcn_mfma_f32_16x16x32_bf16(Bt[n][k], At[m][k], acc[ai][bj][m][n], 0, 0, 0); __builtin_amdgcn_s_setprio(0); } while (0)
; #define PG8_WAIT_V(n) asm volatile("s_waitcnt vmcnt(" #n ")" ::: "memory")
; #define PG8_WAIT_L(n) asm volatile("s_waitcnt lgkmcnt(" #n ")" ::: "memory")
; #define PG8_BAR __builtin_amdgcn_s_barrier()
; #define PG8_SCHED __builtin_amdgcn_sched_barrier(0)
; template <class Epi, class Sched, bool ALIGN_EPI = false, bool SP2 = false>
; __device__ __forceinline__ void gemm_phase(PG8_LAS unsigned char* lds, const Gemm g, const Sched& S, const Epi& E) {
;     ...
;             PG8_WAIT_V(8); PG8_WAIT_L(0); PG8_BAR; PG8_MMA(1, 0, At, B0); PG8_MMA(1, 1, At, B1); PG8_BAR; PG8_SCHED;
;             PG8_LDB(B0, 1, 0); PG8_LDB(B1, 1, 1); PG8_SCHED; PG8_LDA(At, 1, 0); PG8_STAGE(PG8_SA(0, 1), a2 + hstepA, voffA);
;             PG8_WAIT_V(8); PG8_WAIT_L(0); PG8_BAR; PG8_MMA(0, 0, At, B0); PG8_MMA(0, 1, At, B1); PG8_BAR; PG8_SCHED;
	s_setprio 1
	v_mfma_f32_16x16x32_bf16 v[60:63], v[144:147], v[188:191], v[60:63]
	v_mfma_f32_16x16x32_bf16 v[52:55], v[162:165], v[188:191], v[52:55]
	v_mfma_f32_16x16x32_bf16 v[44:47], v[144:147], v[196:199], v[44:47]
	v_mfma_f32_16x16x32_bf16 v[36:39], v[162:165], v[196:199], v[36:39]
	v_mfma_f32_16x16x32_bf16 v[28:31], v[144:147], v[204:207], v[28:31]
	v_mfma_f32_16x16x32_bf16 v[20:23], v[162:165], v[204:207], v[20:23]
	v_mfma_f32_16x16x32_bf16 v[12:15], v[144:147], v[212:215], v[12:15]
	v_mfma_f32_16x16x32_bf16 v[4:7], v[162:165], v[212:215], v[4:7]
	v_mfma_f32_16x16x32_bf16 v[60:63], v[158:161], v[192:195], v[60:63]
	v_mfma_f32_16x16x32_bf16 v[52:55], v[166:169], v[192:195], v[52:55]
	v_mfma_f32_16x16x32_bf16 v[44:47], v[158:161], v[200:203], v[44:47]
	v_mfma_f32_16x16x32_bf16 v[36:39], v[166:169], v[200:203], v[36:39]
	v_mfma_f32_16x16x32_bf16 v[28:31], v[158:161], v[208:211], v[28:31]
	v_mfma_f32_16x16x32_bf16 v[20:23], v[166:169], v[208:211], v[20:23]
	v_mfma_f32_16x16x32_bf16 v[12:15], v[158:161], v[216:219], v[12:15]
	v_mfma_f32_16x16x32_bf16 v[4:7], v[166:169], v[216:219], v[4:7]
	s_setprio 0
	s_setprio 1
	v_mfma_f32_16x16x32_bf16 v[56:59], v[170:173], v[188:191], v[56:59]
	v_mfma_f32_16x16x32_bf16 v[48:51], v[178:181], v[188:191], v[48:51]
	v_mfma_f32_16x16x32_bf16 v[40:43], v[170:173], v[196:199], v[40:43]
	v_mfma_f32_16x16x32_bf16 v[32:35], v[178:181], v[196:199], v[32:35]
	v_mfma_f32_16x16x32_bf16 v[24:27], v[170:173], v[204:207], v[24:27]
	v_mfma_f32_16x16x32_bf16 v[16:19], v[178:181], v[204:207], v[16:19]
	v_mfma_f32_16x16x32_bf16 v[8:11], v[170:173], v[212:215], v[8:11]
	v_mfma_f32_16x16x32_bf16 v[0:3], v[178:181], v[212:215], v[0:3]
	v_mfma_f32_16x16x32_bf16 v[56:59], v[174:177], v[192:195], v[56:59]
	v_mfma_f32_16x16x32_bf16 v[48:51], v[182:185], v[192:195], v[48:51]
	v_mfma_f32_16x16x32_bf16 v[40:43], v[174:177], v[200:203], v[40:43]
	v_mfma_f32_16x16x32_bf16 v[32:35], v[182:185], v[200:203], v[32:35]
	v_mfma_f32_16x16x32_bf16 v[24:27], v[174:177], v[208:211], v[24:27]
	v_mfma_f32_16x16x32_bf16 v[16:19], v[182:185], v[208:211], v[16:19]
	v_mfma_f32_16x16x32_bf16 v[8:11], v[174:177], v[216:219], v[8:11]
	v_mfma_f32_16x16x32_bf16 v[0:3], v[182:185], v[216:219], v[0:3]
	s_barrier
	s_setprio 0
	s_add_i32 s58, 0, 0x18000
	v_add_u32_e32 v157, s58, v151
	s_add_i32 s59, 0, 0x1c000
	ds_read_b128 v[144:147], v157
	ds_read_b128 v[158:161], v157 offset:1024
	ds_read_b128 v[162:165], v157 offset:2048
	ds_read_b128 v[166:169], v157 offset:3072
	v_add_u32_e32 v157, s59, v151
	ds_read_b128 v[170:173], v157
	ds_read_b128 v[174:177], v157 offset:1024
	ds_read_b128 v[178:181], v157 offset:2048
	ds_read_b128 v[182:185], v157 offset:3072
	s_add_u32 s30, s30, 0x40000
	s_addc_u32 s31, s31, 0
	s_mov_b32 m0, s39
	v_lshl_add_u64 v[226:227], s[30:31], 0, v[134:135]
	ds_read_b128 v[188:191], v155 offset:32768
	ds_read_b128 v[192:195], v155 offset:33792
	ds_read_b128 v[196:199], v155 offset:34816
	ds_read_b128 v[200:203], v155 offset:35840
	ds_read_b128 v[204:207], v155 offset:36864
	ds_read_b128 v[208:211], v155 offset:37888
	ds_read_b128 v[212:215], v155 offset:38912
	ds_read_b128 v[216:219], v155 offset:39936
	global_load_lds_dwordx4 v[226:227], off
	v_lshl_add_u64 v[226:227], s[30:31], 0, v[130:131]
	s_mov_b32 m0, s40
	s_nop 0
	global_load_lds_dwordx4 v[226:227], off
	s_waitcnt vmcnt(8) lgkmcnt(0)
	s_barrier
	s_setprio 1
	v_mfma_f32_16x16x32_bf16 v[116:119], v[144:147], v[188:191], v[116:119]
	v_mfma_f32_16x16x32_bf16 v[112:115], v[162:165], v[188:191], v[112:115]
	v_mfma_f32_16x16x32_bf16 v[108:111], v[144:147], v[196:199], v[108:111]
	v_mfma_f32_16x16x32_bf16 v[100:103], v[162:165], v[196:199], v[100:103]
	v_mfma_f32_16x16x32_bf16 v[92:95], v[144:147], v[204:207], v[92:95]
	v_mfma_f32_16x16x32_bf16 v[84:87], v[162:165], v[204:207], v[84:87]
	v_mfma_f32_16x16x32_bf16 v[76:79], v[144:147], v[212:215], v[76:79]
	v_mfma_f32_16x16x32_bf16 v[68:71], v[162:165], v[212:215], v[68:71]
	v_mfma_f32_16x16x32_bf16 v[116:119], v[158:161], v[192:195], v[116:119]
	v_mfma_f32_16x16x32_bf16 v[112:115], v[166:169], v[192:195], v[112:115]
	v_mfma_f32_16x16x32_bf16 v[108:111], v[158:161], v[200:203], v[108:111]
	v_mfma_f32_16x16x32_bf16 v[100:103], v[166:169], v[200:203], v[100:103]
	v_mfma_f32_16x16x32_bf16 v[92:95], v[158:161], v[208:211], v[92:95]
	v_mfma_f32_16x16x32_bf16 v[84:87], v[166:169], v[208:211], v[84:87]
	v_mfma_f32_16x16x32_bf16 v[76:79], v[158:161], v[216:219], v[76:79]
	v_mfma_f32_16x16x32_bf16 v[68:71], v[166:169], v[216:219], v[68:71]
	s_setprio 0
	s_setprio 1
	v_mfma_f32_16x16x32_bf16 v[124:127], v[170:173], v[188:191], v[124:127]
	v_mfma_f32_16x16x32_bf16 v[120:123], v[178:181], v[188:191], v[120:123]
	v_mfma_f32_16x16x32_bf16 v[104:107], v[170:173], v[196:199], v[104:107]
	v_mfma_f32_16x16x32_bf16 v[96:99], v[178:181], v[196:199], v[96:99]
	v_mfma_f32_16x16x32_bf16 v[88:91], v[170:173], v[204:207], v[88:91]
	v_mfma_f32_16x16x32_bf16 v[80:83], v[178:181], v[204:207], v[80:83]
	v_mfma_f32_16x16x32_bf16 v[72:75], v[170:173], v[212:215], v[72:75]
	v_mfma_f32_16x16x32_bf16 v[64:67], v[178:181], v[212:215], v[64:67]
	v_mfma_f32_16x16x32_bf16 v[124:127], v[174:177], v[192:195], v[124:127]
	v_mfma_f32_16x16x32_bf16 v[120:123], v[182:185], v[192:195], v[120:123]
	v_mfma_f32_16x16x32_bf16 v[104:107], v[174:177], v[200:203], v[104:107]
	v_mfma_f32_16x16x32_bf16 v[96:99], v[182:185], v[200:203], v[96:99]
	v_mfma_f32_16x16x32_bf16 v[88:91], v[174:177], v[208:211], v[88:91]
	v_mfma_f32_16x16x32_bf16 v[80:83], v[182:185], v[208:211], v[80:83]
	v_mfma_f32_16x16x32_bf16 v[72:75], v[174:177], v[216:219], v[72:75]
	v_mfma_f32_16x16x32_bf16 v[64:67], v[182:185], v[216:219], v[64:67]
	s_barrier
; #define PG8_STAGE(bufoff, gbase, voff) do { _Pragma("unroll") for (int _i = 0; _i < 2; ++_i) \
;         __builtin_amdgcn_global_load_lds((const unsigned*)((const char*)(gbase) + (voff)[_i]), (PG8_LAS unsigned*)(lds + (bufoff) + ldsw + _i * 8192), 16, 0, 0); } while (0)
; #define PG8_LDA(dst, b, h) do { _Pragma("unroll") for (int m = 0; m < 4; ++m) _Pragma("unroll") for (int k = 0; k < 2; ++k) dst[m][k] = *(const PG8_LAS bf16x8*)(lds + PG8_SA(b, h) + aoff + m * 2048 + k * 1024); } while (0)
; #define PG8_MMA(ai, bj, At, Bt) do { __builtin_amdgcn_s_setprio(1); _Pragma("unroll") for (int m = 0; m < 4; ++m) _Pragma("unroll") for (int n = 0; n < 2; ++n) _Pragma("unroll") for (int k = 0; k < 2; ++k) \
;         acc[ai][bj][m][n] = __builtin_amdgcn_mfma_f32_16x16x32_bf16(Bt[n][k], At[m][k], acc[ai][bj][m][n], 0, 0, 0); __builtin_amdgcn_s_setprio(0); } while (0)
; #define PG8_WAIT_V(n) asm volatile("s_waitcnt vmcnt(" #n ")" ::: "memory")
; #define PG8_WAIT_L(n) asm volatile("s_waitcnt lgkmcnt(" #n ")" ::: "memory")
; #define PG8_BAR __builtin_amdgcn_s_barrier()
; #define PG8_SCHED __builtin_amdgcn_sched_barrier(0)
; template <class Epi, class Sched, bool ALIGN_EPI = false, bool SP2 = false>
; __device__ __forceinline__ void gemm_phase(PG8_LAS unsigned char* lds, const Gemm g, const Sched& S, const Epi& E) {
;     ...
;             PG8_LDA(At, 1, 1); PG8_STAGE(PG8_SB(1, 0), b3, voffB); PG8_STAGE(PG8_SB(1, 1), b3 + hstepB, voffB); PG8_STAGE(PG8_SA(1, 0), a3, voffA);
;             PG8_WAIT_V(8); PG8_WAIT_L(0); PG8_BAR; PG8_MMA(1, 0, At, B0); PG8_MMA(1, 1, At, B1); PG8_BAR; PG8_SCHED;
;     ...
;         if constexpr (ALIGN_EPI) { if (wr == 0) PG8_BAR; }
	s_setprio 0
	s_add_i32 s30, s58, s35
	v_lshl_add_u64 v[148:149], v[148:149], 0, s[12:13]
	s_mov_b32 m0, s30
	ds_read_b128 v[188:191], v155 offset:49152
	ds_read_b128 v[192:195], v155 offset:50176
	ds_read_b128 v[196:199], v155 offset:51200
	ds_read_b128 v[200:203], v155 offset:52224
	ds_read_b128 v[204:207], v155 offset:53248
	ds_read_b128 v[208:211], v155 offset:54272
	ds_read_b128 v[212:215], v155 offset:55296
	ds_read_b128 v[216:219], v155 offset:56320
	global_load_lds_dwordx4 v[148:149], off
	s_add_i32 m0, s30, 0x2000
	s_add_u32 s28, s28, 0x40080
	v_lshl_add_u64 v[148:149], v[220:221], 0, s[12:13]
	s_addc_u32 s29, s29, 0
	s_add_i32 s30, s59, s35
	global_load_lds_dwordx4 v[148:149], off
	v_lshl_add_u64 v[148:149], s[28:29], 0, v[132:133]
	s_mov_b32 m0, s30
	s_nop 0
	global_load_lds_dwordx4 v[148:149], off
	v_lshl_add_u64 v[148:149], s[28:29], 0, v[128:129]
	s_add_i32 m0, s30, 0x2000
	s_nop 0
	global_load_lds_dwordx4 v[148:149], off
	v_lshl_add_u64 v[148:149], v[222:223], 0, s[12:13]
	s_mov_b32 m0, s42
	s_nop 0
	global_load_lds_dwordx4 v[148:149], off
	v_lshl_add_u64 v[148:149], v[224:225], 0, s[12:13]
	s_mov_b32 m0, s43
	s_nop 0
	global_load_lds_dwordx4 v[148:149], off
	s_waitcnt vmcnt(8) lgkmcnt(0)
	s_barrier
	s_setprio 1
	v_mfma_f32_16x16x32_bf16 v[60:63], v[144:147], v[188:191], v[60:63]
	v_mfma_f32_16x16x32_bf16 v[52:55], v[162:165], v[188:191], v[52:55]
	v_mfma_f32_16x16x32_bf16 v[44:47], v[144:147], v[196:199], v[44:47]
	v_mfma_f32_16x16x32_bf16 v[36:39], v[162:165], v[196:199], v[36:39]
	v_mfma_f32_16x16x32_bf16 v[28:31], v[144:147], v[204:207], v[28:31]
	v_mfma_f32_16x16x32_bf16 v[20:23], v[162:165], v[204:207], v[20:23]
	v_mfma_f32_16x16x32_bf16 v[12:15], v[144:147], v[212:215], v[12:15]
	v_mfma_f32_16x16x32_bf16 v[4:7], v[162:165], v[212:215], v[4:7]
	v_mfma_f32_16x16x32_bf16 v[60:63], v[158:161], v[192:195], v[60:63]
	v_mfma_f32_16x16x32_bf16 v[52:55], v[166:169], v[192:195], v[52:55]
	v_mfma_f32_16x16x32_bf16 v[44:47], v[158:161], v[200:203], v[44:47]
	v_mfma_f32_16x16x32_bf16 v[36:39], v[166:169], v[200:203], v[36:39]
	v_mfma_f32_16x16x32_bf16 v[28:31], v[158:161], v[208:211], v[28:31]
	v_mfma_f32_16x16x32_bf16 v[20:23], v[166:169], v[208:211], v[20:23]
	v_mfma_f32_16x16x32_bf16 v[12:15], v[158:161], v[216:219], v[12:15]
	v_mfma_f32_16x16x32_bf16 v[4:7], v[166:169], v[216:219], v[4:7]
	s_setprio 0
	s_setprio 1
	v_mfma_f32_16x16x32_bf16 v[56:59], v[170:173], v[188:191], v[56:59]
	v_mfma_f32_16x16x32_bf16 v[48:51], v[178:181], v[188:191], v[48:51]
	v_mfma_f32_16x16x32_bf16 v[40:43], v[170:173], v[196:199], v[40:43]
	v_mfma_f32_16x16x32_bf16 v[32:35], v[178:181], v[196:199], v[32:35]
	v_mfma_f32_16x16x32_bf16 v[24:27], v[170:173], v[204:207], v[24:27]
	v_mfma_f32_16x16x32_bf16 v[16:19], v[178:181], v[204:207], v[16:19]
	v_mfma_f32_16x16x32_bf16 v[8:11], v[170:173], v[212:215], v[8:11]
	v_mfma_f32_16x16x32_bf16 v[0:3], v[178:181], v[212:215], v[0:3]
	v_mfma_f32_16x16x32_bf16 v[56:59], v[174:177], v[192:195], v[56:59]
	v_mfma_f32_16x16x32_bf16 v[48:51], v[182:185], v[192:195], v[48:51]
	v_mfma_f32_16x16x32_bf16 v[40:43], v[174:177], v[200:203], v[40:43]
	v_mfma_f32_16x16x32_bf16 v[32:35], v[182:185], v[200:203], v[32:35]
	v_mfma_f32_16x16x32_bf16 v[24:27], v[174:177], v[208:211], v[24:27]
	v_mfma_f32_16x16x32_bf16 v[16:19], v[182:185], v[208:211], v[16:19]
	v_mfma_f32_16x16x32_bf16 v[8:11], v[174:177], v[216:219], v[8:11]
	v_mfma_f32_16x16x32_bf16 v[0:3], v[182:185], v[216:219], v[0:3]
	s_barrier
	s_setprio 0
	s_add_i32 s69, s69, 2
	s_add_u32 s26, s26, 0x100
	s_addc_u32 s27, s27, 0
	s_add_u32 s67, s67, 0x100
	s_addc_u32 s68, s68, 0
	s_cmp_gt_u32 s69, 13
	s_cbranch_scc0 .LBB0_1055
	s_and_b64 vcc, exec, s[14:15]
	s_cbranch_vccz .LBB0_1058
	s_barrier

; #define PG8_STAGE(bufoff, gbase, voff) do { _Pragma("unroll") for (int _i = 0; _i < 2; ++_i) \
;         __builtin_amdgcn_global_load_lds((const unsigned*)((const char*)(gbase) + (voff)[_i]), (PG8_LAS unsigned*)(lds + (bufoff) + ldsw + _i * 8192), 16, 0, 0); } while (0)
; #define PG8_LDA(dst, b, h) do { _Pragma("unroll") for (int m = 0; m < 4; ++m) _Pragma("unroll") for (int k = 0; k < 2; ++k) dst[m][k] = *(const PG8_LAS bf16x8*)(lds + PG8_SA(b, h) + aoff + m * 2048 + k * 1024); } while (0)
; #define PG8_LDB(dst, b, h) do { _Pragma("unroll") for (int n = 0; n < 2; ++n) _Pragma("unroll") for (int k = 0; k < 2; ++k) dst[n][k] = *(const PG8_LAS bf16x8*)(lds + PG8_SB(b, h) + boff + n * 2048 + k * 1024); } while (0)
; #define PG8_MMA(ai, bj, At, Bt) do { __builtin_amdgcn_s_setprio(1); _Pragma("unroll") for (int m = 0; m < 4; ++m) _Pragma("unroll") for (int n = 0; n < 2; ++n) _Pragma("unroll") for (int k = 0; k < 2; ++k) \
;         acc[ai][bj][m][n] = __builtin_amdgcn_mfma_f32_16x16x32_bf16(Bt[n][k], At[m][k], acc[ai][bj][m][n], 0, 0, 0); __builtin_amdgcn_s_setprio(0); } while (0)
; #define PG8_WAIT_V(n) asm volatile("s_waitcnt vmcnt(" #n ")" ::: "memory")
; #define PG8_BAR __builtin_amdgcn_s_barrier()
; template <class Epi, class Sched, bool ALIGN_EPI = false, bool SP2 = false>
; __device__ __forceinline__ void gemm_phase(PG8_LAS unsigned char* lds, const Gemm g, const Sched& S, const Epi& E) {
;     ...
;         for (int t = 0; t < nt; t += 2) {
;             const bool last = (t == nt - 2);
;             const char* a1 = cA + (size_t)(t + 1) * kstep;
;             const char* a2 = last ? nA : cA + (size_t)(t + 2) * kstep; const char* b2 = last ? nB : cB + (size_t)(t + 2) * kstep;
;             const char* a3 = a2 + kstep; const char* b3 = b2 + kstep;
;             if (last && has_next) S.a_ready(nxt);
;             if constexpr (SP2) {
;             PG8_LDB(B0, 0, 0); PG8_LDB(B1, 0, 1); PG8_SCHED; PG8_LDA(At, 0, 0); PG8_STAGE(PG8_SA(1, 1), a1 + hstepA, voffA);
;             PG8_WAIT_V(8); PG8_WAIT_L(0); PG8_BAR; PG8_MMA(0, 0, At, B0); PG8_MMA(0, 1, At, B1); PG8_BAR; PG8_SCHED;
;             PG8_LDA(At, 0, 1); PG8_STAGE(PG8_SB(0, 0), b2, voffB); PG8_STAGE(PG8_SB(0, 1), b2 + hstepB, voffB); PG8_STAGE(PG8_SA(0, 0), a2, voffA);
;             PG8_WAIT_V(8); PG8_WAIT_L(0); PG8_BAR; PG8_MMA(1, 0, At, B0); PG8_MMA(1, 1, At, B1); PG8_BAR; PG8_SCHED;
.LBB0_1129:
	ds_read_b128 v[128:131], v191
	ds_read_b128 v[132:135], v191 offset:1024
	ds_read_b128 v[136:139], v191 offset:2048
	ds_read_b128 v[140:143], v191 offset:3072
	ds_read_b128 v[144:147], v192
	ds_read_b128 v[148:151], v192 offset:1024
	ds_read_b128 v[168:171], v192 offset:2048
	ds_read_b128 v[172:175], v192 offset:3072
	s_add_u32 s24, s22, 0x100
	s_addc_u32 s25, s23, 0
	s_cmp_eq_u32 s69, 40
	s_cselect_b32 s29, s11, s25
	s_cselect_b32 s28, s10, s24
	s_cselect_b32 s27, s21, s68
	s_cselect_b32 s26, s20, s67
	v_lshl_add_u64 v[184:185], s[22:23], 0, v[160:161]
	s_add_i32 m0, s34, 0xc000
	ds_read_b128 v[176:179], v193
	ds_read_b128 v[180:183], v193 offset:1024
	ds_read_b128 v[196:199], v193 offset:2048
	ds_read_b128 v[200:203], v193 offset:3072
	ds_read_b128 v[204:207], v193 offset:4096
	ds_read_b128 v[208:211], v193 offset:5120
	ds_read_b128 v[212:215], v193 offset:6144
	ds_read_b128 v[216:219], v193 offset:7168
	global_load_lds_dwordx4 v[184:185], off
	v_lshl_add_u64 v[184:185], s[22:23], 0, v[162:163]
	s_add_i32 m0, s34, 0xe000
	s_nop 0
	global_load_lds_dwordx4 v[184:185], off
	s_waitcnt vmcnt(8) lgkmcnt(0)
	s_barrier
	s_setprio 1
	v_mfma_f32_16x16x32_bf16 v[124:127], v[128:131], v[176:179], v[124:127]
	v_mfma_f32_16x16x32_bf16 v[120:123], v[136:139], v[176:179], v[120:123]
	v_mfma_f32_16x16x32_bf16 v[108:111], v[128:131], v[196:199], v[108:111]
	v_mfma_f32_16x16x32_bf16 v[104:107], v[136:139], v[196:199], v[104:107]
	v_mfma_f32_16x16x32_bf16 v[92:95], v[128:131], v[204:207], v[92:95]
	v_mfma_f32_16x16x32_bf16 v[88:91], v[136:139], v[204:207], v[88:91]
	v_mfma_f32_16x16x32_bf16 v[76:79], v[128:131], v[212:215], v[76:79]
	v_mfma_f32_16x16x32_bf16 v[72:75], v[136:139], v[212:215], v[72:75]
	v_mfma_f32_16x16x32_bf16 v[124:127], v[132:135], v[180:183], v[124:127]
	v_mfma_f32_16x16x32_bf16 v[120:123], v[140:143], v[180:183], v[120:123]
	v_mfma_f32_16x16x32_bf16 v[108:111], v[132:135], v[200:203], v[108:111]
	v_mfma_f32_16x16x32_bf16 v[104:107], v[140:143], v[200:203], v[104:107]
	v_mfma_f32_16x16x32_bf16 v[92:95], v[132:135], v[208:211], v[92:95]
	v_mfma_f32_16x16x32_bf16 v[88:91], v[140:143], v[208:211], v[88:91]
	v_mfma_f32_16x16x32_bf16 v[76:79], v[132:135], v[216:219], v[76:79]
	v_mfma_f32_16x16x32_bf16 v[72:75], v[140:143], v[216:219], v[72:75]
	s_setprio 0
	s_setprio 1
	v_mfma_f32_16x16x32_bf16 v[116:119], v[144:147], v[176:179], v[116:119]
	v_mfma_f32_16x16x32_bf16 v[112:115], v[168:171], v[176:179], v[112:115]
	v_mfma_f32_16x16x32_bf16 v[100:103], v[144:147], v[196:199], v[100:103]
	v_mfma_f32_16x16x32_bf16 v[96:99], v[168:171], v[196:199], v[96:99]
	v_mfma_f32_16x16x32_bf16 v[84:87], v[144:147], v[204:207], v[84:87]
	v_mfma_f32_16x16x32_bf16 v[80:83], v[168:171], v[204:207], v[80:83]
	v_mfma_f32_16x16x32_bf16 v[68:71], v[144:147], v[212:215], v[68:71]
	v_mfma_f32_16x16x32_bf16 v[64:67], v[168:171], v[212:215], v[64:67]
	v_mfma_f32_16x16x32_bf16 v[116:119], v[148:151], v[180:183], v[116:119]
	v_mfma_f32_16x16x32_bf16 v[112:115], v[172:175], v[180:183], v[112:115]
	v_mfma_f32_16x16x32_bf16 v[100:103], v[148:151], v[200:203], v[100:103]
	v_mfma_f32_16x16x32_bf16 v[96:99], v[172:175], v[200:203], v[96:99]
	v_mfma_f32_16x16x32_bf16 v[84:87], v[148:151], v[208:211], v[84:87]
	v_mfma_f32_16x16x32_bf16 v[80:83], v[172:175], v[208:211], v[80:83]
	v_mfma_f32_16x16x32_bf16 v[68:71], v[148:151], v[216:219], v[68:71]
	v_mfma_f32_16x16x32_bf16 v[64:67], v[172:175], v[216:219], v[64:67]
	s_barrier
	s_setprio 0
	s_add_i32 s22, s44, s31
	v_lshl_add_u64 v[184:185], s[26:27], 0, v[154:155]
	s_mov_b32 m0, s22
	ds_read_b128 v[176:179], v193 offset:16384
	ds_read_b128 v[180:183], v193 offset:17408
	ds_read_b128 v[196:199], v193 offset:18432
	ds_read_b128 v[200:203], v193 offset:19456
	ds_read_b128 v[204:207], v193 offset:20480
	ds_read_b128 v[208:211], v193 offset:21504
	ds_read_b128 v[212:215], v193 offset:22528
	ds_read_b128 v[216:219], v193 offset:23552
	global_load_lds_dwordx4 v[184:185], off
	s_add_i32 m0, s22, 0x2000
	s_add_u32 s22, s26, 0xb0000
	v_lshl_add_u64 v[220:221], s[26:27], 0, v[158:159]
	s_addc_u32 s23, s27, 0
	s_add_i32 s58, s45, s31
	global_load_lds_dwordx4 v[220:221], off
	v_lshl_add_u64 v[222:223], s[22:23], 0, v[154:155]
	s_mov_b32 m0, s58
	v_lshl_add_u64 v[224:225], s[28:29], 0, v[156:157]
	global_load_lds_dwordx4 v[222:223], off
	v_lshl_add_u64 v[222:223], s[22:23], 0, v[158:159]
	s_add_i32 m0, s58, 0x2000
	s_nop 0
	global_load_lds_dwordx4 v[222:223], off
	v_lshl_add_u64 v[222:223], s[28:29], 0, v[152:153]
	s_mov_b32 m0, s34
	s_nop 0
	global_load_lds_dwordx4 v[222:223], off
	s_mov_b32 m0, s35
	s_nop 0
	global_load_lds_dwordx4 v[224:225], off
	s_waitcnt vmcnt(8) lgkmcnt(0)
	s_barrier
; #define PG8_STAGE(bufoff, gbase, voff) do { _Pragma("unroll") for (int _i = 0; _i < 2; ++_i) \
;         __builtin_amdgcn_global_load_lds((const unsigned*)((const char*)(gbase) + (voff)[_i]), (PG8_LAS unsigned*)(lds + (bufoff) + ldsw + _i * 8192), 16, 0, 0); } while (0)
; #define PG8_LDA(dst, b, h) do { _Pragma("unroll") for (int m = 0; m < 4; ++m) _Pragma("unroll") for (int k = 0; k < 2; ++k) dst[m][k] = *(const PG8_LAS bf16x8*)(lds + PG8_SA(b, h) + aoff + m * 2048 + k * 1024); } while (0)
; #define PG8_LDB(dst, b, h) do { _Pragma("unroll") for (int n = 0; n < 2; ++n) _Pragma("unroll") for (int k = 0; k < 2; ++k) dst[n][k] = *(const PG8_LAS bf16x8*)(lds + PG8_SB(b, h) + boff + n * 2048 + k * 1024); } while (0)
; #define PG8_MMA(ai, bj, At, Bt) do { __builtin_amdgcn_s_setprio(1); _Pragma("unroll") for (int m = 0; m < 4; ++m) _Pragma("unroll") for (int n = 0; n < 2; ++n) _Pragma("unroll") for (int k = 0; k < 2; ++k) \
;         acc[ai][bj][m][n] = __builtin_amdgcn_mfma_f32_16x16x32_bf16(Bt[n][k], At[m][k], acc[ai][bj][m][n], 0, 0, 0); __builtin_amdgcn_s_setprio(0); } while (0)
; #define PG8_WAIT_V(n) asm volatile("s_waitcnt vmcnt(" #n ")" ::: "memory")
; #define PG8_WAIT_L(n) asm volatile("s_waitcnt lgkmcnt(" #n ")" ::: "memory")
; #define PG8_BAR __builtin_amdgcn_s_barrier()
; #define PG8_SCHED __builtin_amdgcn_sched_barrier(0)
; template <class Epi, class Sched, bool ALIGN_EPI = false, bool SP2 = false>
; __device__ __forceinline__ void gemm_phase(PG8_LAS unsigned char* lds, const Gemm g, const Sched& S, const Epi& E) {
;     ...
;             PG8_WAIT_V(8); PG8_WAIT_L(0); PG8_BAR; PG8_MMA(1, 0, At, B0); PG8_MMA(1, 1, At, B1); PG8_BAR; PG8_SCHED;
;             PG8_LDB(B0, 1, 0); PG8_LDB(B1, 1, 1); PG8_SCHED; PG8_LDA(At, 1, 0); PG8_STAGE(PG8_SA(0, 1), a2 + hstepA, voffA);
;             PG8_WAIT_V(8); PG8_WAIT_L(0); PG8_BAR; PG8_MMA(0, 0, At, B0); PG8_MMA(0, 1, At, B1); PG8_BAR; PG8_SCHED;
	s_setprio 1
	v_mfma_f32_16x16x32_bf16 v[60:63], v[128:131], v[176:179], v[60:63]
	v_mfma_f32_16x16x32_bf16 v[56:59], v[136:139], v[176:179], v[56:59]
	v_mfma_f32_16x16x32_bf16 v[44:47], v[128:131], v[196:199], v[44:47]
	v_mfma_f32_16x16x32_bf16 v[40:43], v[136:139], v[196:199], v[40:43]
	v_mfma_f32_16x16x32_bf16 v[28:31], v[128:131], v[204:207], v[28:31]
	v_mfma_f32_16x16x32_bf16 v[24:27], v[136:139], v[204:207], v[24:27]
	v_mfma_f32_16x16x32_bf16 v[12:15], v[128:131], v[212:215], v[12:15]
	v_mfma_f32_16x16x32_bf16 v[8:11], v[136:139], v[212:215], v[8:11]
	v_mfma_f32_16x16x32_bf16 v[60:63], v[132:135], v[180:183], v[60:63]
	v_mfma_f32_16x16x32_bf16 v[56:59], v[140:143], v[180:183], v[56:59]
	v_mfma_f32_16x16x32_bf16 v[44:47], v[132:135], v[200:203], v[44:47]
	v_mfma_f32_16x16x32_bf16 v[40:43], v[140:143], v[200:203], v[40:43]
	v_mfma_f32_16x16x32_bf16 v[28:31], v[132:135], v[208:211], v[28:31]
	v_mfma_f32_16x16x32_bf16 v[24:27], v[140:143], v[208:211], v[24:27]
	v_mfma_f32_16x16x32_bf16 v[12:15], v[132:135], v[216:219], v[12:15]
	v_mfma_f32_16x16x32_bf16 v[8:11], v[140:143], v[216:219], v[8:11]
	s_setprio 0
	s_setprio 1
	v_mfma_f32_16x16x32_bf16 v[52:55], v[144:147], v[176:179], v[52:55]
	v_mfma_f32_16x16x32_bf16 v[48:51], v[168:171], v[176:179], v[48:51]
	v_mfma_f32_16x16x32_bf16 v[36:39], v[144:147], v[196:199], v[36:39]
	v_mfma_f32_16x16x32_bf16 v[32:35], v[168:171], v[196:199], v[32:35]
	v_mfma_f32_16x16x32_bf16 v[20:23], v[144:147], v[204:207], v[20:23]
	v_mfma_f32_16x16x32_bf16 v[16:19], v[168:171], v[204:207], v[16:19]
	v_mfma_f32_16x16x32_bf16 v[4:7], v[144:147], v[212:215], v[4:7]
	v_mfma_f32_16x16x32_bf16 v[0:3], v[168:171], v[212:215], v[0:3]
	v_mfma_f32_16x16x32_bf16 v[52:55], v[148:151], v[180:183], v[52:55]
	v_mfma_f32_16x16x32_bf16 v[48:51], v[172:175], v[180:183], v[48:51]
	v_mfma_f32_16x16x32_bf16 v[36:39], v[148:151], v[200:203], v[36:39]
	v_mfma_f32_16x16x32_bf16 v[32:35], v[172:175], v[200:203], v[32:35]
	v_mfma_f32_16x16x32_bf16 v[20:23], v[148:151], v[208:211], v[20:23]
	v_mfma_f32_16x16x32_bf16 v[16:19], v[172:175], v[208:211], v[16:19]
	v_mfma_f32_16x16x32_bf16 v[4:7], v[148:151], v[216:219], v[4:7]
	v_mfma_f32_16x16x32_bf16 v[0:3], v[172:175], v[216:219], v[0:3]
	s_barrier
	s_setprio 0
	s_add_i32 s58, 0, 0x18000
	s_add_i32 s59, 0, 0x1c000
	v_add_u32_e32 v140, s58, v189
	v_add_u32_e32 v172, s59, v189
	ds_read_b128 v[128:131], v140
	ds_read_b128 v[132:135], v140 offset:1024
	ds_read_b128 v[136:139], v140 offset:2048
	ds_read_b128 v[140:143], v140 offset:3072
	ds_read_b128 v[144:147], v172
	ds_read_b128 v[148:151], v172 offset:1024
	ds_read_b128 v[168:171], v172 offset:2048
	ds_read_b128 v[172:175], v172 offset:3072
	s_add_u32 s22, s28, 0xb0000
	s_addc_u32 s23, s29, 0
	s_mov_b32 m0, s36
	v_lshl_add_u64 v[226:227], s[22:23], 0, v[152:153]
	ds_read_b128 v[176:179], v193 offset:32768
	ds_read_b128 v[180:183], v193 offset:33792
	ds_read_b128 v[196:199], v193 offset:34816
	ds_read_b128 v[200:203], v193 offset:35840
	ds_read_b128 v[204:207], v193 offset:36864
	ds_read_b128 v[208:211], v193 offset:37888
	ds_read_b128 v[212:215], v193 offset:38912
	ds_read_b128 v[216:219], v193 offset:39936
	global_load_lds_dwordx4 v[226:227], off
	v_lshl_add_u64 v[226:227], s[22:23], 0, v[156:157]
	s_mov_b32 m0, s37
	s_nop 0
	global_load_lds_dwordx4 v[226:227], off
	s_waitcnt vmcnt(8) lgkmcnt(0)
	s_barrier
	s_setprio 1
	v_mfma_f32_16x16x32_bf16 v[124:127], v[128:131], v[176:179], v[124:127]
	v_mfma_f32_16x16x32_bf16 v[120:123], v[136:139], v[176:179], v[120:123]
	v_mfma_f32_16x16x32_bf16 v[108:111], v[128:131], v[196:199], v[108:111]
	v_mfma_f32_16x16x32_bf16 v[104:107], v[136:139], v[196:199], v[104:107]
	v_mfma_f32_16x16x32_bf16 v[92:95], v[128:131], v[204:207], v[92:95]
	v_mfma_f32_16x16x32_bf16 v[88:91], v[136:139], v[204:207], v[88:91]
	v_mfma_f32_16x16x32_bf16 v[76:79], v[128:131], v[212:215], v[76:79]
	v_mfma_f32_16x16x32_bf16 v[72:75], v[136:139], v[212:215], v[72:75]
	v_mfma_f32_16x16x32_bf16 v[124:127], v[132:135], v[180:183], v[124:127]
	v_mfma_f32_16x16x32_bf16 v[120:123], v[140:143], v[180:183], v[120:123]
	v_mfma_f32_16x16x32_bf16 v[108:111], v[132:135], v[200:203], v[108:111]
	v_mfma_f32_16x16x32_bf16 v[104:107], v[140:143], v[200:203], v[104:107]
	v_mfma_f32_16x16x32_bf16 v[92:95], v[132:135], v[208:211], v[92:95]
	v_mfma_f32_16x16x32_bf16 v[88:91], v[140:143], v[208:211], v[88:91]
	v_mfma_f32_16x16x32_bf16 v[76:79], v[132:135], v[216:219], v[76:79]
	v_mfma_f32_16x16x32_bf16 v[72:75], v[140:143], v[216:219], v[72:75]
	s_setprio 0
	s_setprio 1
	v_mfma_f32_16x16x32_bf16 v[116:119], v[144:147], v[176:179], v[116:119]
	v_mfma_f32_16x16x32_bf16 v[112:115], v[168:171], v[176:179], v[112:115]
	v_mfma_f32_16x16x32_bf16 v[100:103], v[144:147], v[196:199], v[100:103]
	v_mfma_f32_16x16x32_bf16 v[96:99], v[168:171], v[196:199], v[96:99]
	v_mfma_f32_16x16x32_bf16 v[84:87], v[144:147], v[204:207], v[84:87]
	v_mfma_f32_16x16x32_bf16 v[80:83], v[168:171], v[204:207], v[80:83]
	v_mfma_f32_16x16x32_bf16 v[68:71], v[144:147], v[212:215], v[68:71]
	v_mfma_f32_16x16x32_bf16 v[64:67], v[168:171], v[212:215], v[64:67]
	v_mfma_f32_16x16x32_bf16 v[116:119], v[148:151], v[180:183], v[116:119]
	v_mfma_f32_16x16x32_bf16 v[112:115], v[172:175], v[180:183], v[112:115]
	v_mfma_f32_16x16x32_bf16 v[100:103], v[148:151], v[200:203], v[100:103]
	v_mfma_f32_16x16x32_bf16 v[96:99], v[172:175], v[200:203], v[96:99]
	v_mfma_f32_16x16x32_bf16 v[84:87], v[148:151], v[208:211], v[84:87]
	v_mfma_f32_16x16x32_bf16 v[80:83], v[172:175], v[208:211], v[80:83]
	v_mfma_f32_16x16x32_bf16 v[68:71], v[148:151], v[216:219], v[68:71]
	v_mfma_f32_16x16x32_bf16 v[64:67], v[172:175], v[216:219], v[64:67]
	s_barrier
; #define PG8_STAGE(bufoff, gbase, voff) do { _Pragma("unroll") for (int _i = 0; _i < 2; ++_i) \
;         __builtin_amdgcn_global_load_lds((const unsigned*)((const char*)(gbase) + (voff)[_i]), (PG8_LAS unsigned*)(lds + (bufoff) + ldsw + _i * 8192), 16, 0, 0); } while (0)
; #define PG8_LDA(dst, b, h) do { _Pragma("unroll") for (int m = 0; m < 4; ++m) _Pragma("unroll") for (int k = 0; k < 2; ++k) dst[m][k] = *(const PG8_LAS bf16x8*)(lds + PG8_SA(b, h) + aoff + m * 2048 + k * 1024); } while (0)
; #define PG8_MMA(ai, bj, At, Bt) do { __builtin_amdgcn_s_setprio(1); _Pragma("unroll") for (int m = 0; m < 4; ++m) _Pragma("unroll") for (int n = 0; n < 2; ++n) _Pragma("unroll") for (int k = 0; k < 2; ++k) \
;         acc[ai][bj][m][n] = __builtin_amdgcn_mfma_f32_16x16x32_bf16(Bt[n][k], At[m][k], acc[ai][bj][m][n], 0, 0, 0); __builtin_amdgcn_s_setprio(0); } while (0)
; #define PG8_WAIT_V(n) asm volatile("s_waitcnt vmcnt(" #n ")" ::: "memory")
; #define PG8_WAIT_L(n) asm volatile("s_waitcnt lgkmcnt(" #n ")" ::: "memory")
; #define PG8_BAR __builtin_amdgcn_s_barrier()
; #define PG8_SCHED __builtin_amdgcn_sched_barrier(0)
; template <class Epi, class Sched, bool ALIGN_EPI = false, bool SP2 = false>
; __device__ __forceinline__ void gemm_phase(PG8_LAS unsigned char* lds, const Gemm g, const Sched& S, const Epi& E) {
;     ...
;             PG8_LDA(At, 1, 1); PG8_STAGE(PG8_SB(1, 0), b3, voffB); PG8_STAGE(PG8_SB(1, 1), b3 + hstepB, voffB); PG8_STAGE(PG8_SA(1, 0), a3, voffA);
;             PG8_WAIT_V(8); PG8_WAIT_L(0); PG8_BAR; PG8_MMA(1, 0, At, B0); PG8_MMA(1, 1, At, B1); PG8_BAR; PG8_SCHED;
;     ...
;         if constexpr (ALIGN_EPI) { if (wr == 0) PG8_BAR; }
	s_setprio 0
	s_add_i32 s22, s58, s31
	v_lshl_add_u64 v[184:185], v[184:185], 0, s[16:17]
	s_mov_b32 m0, s22
	ds_read_b128 v[176:179], v193 offset:49152
	ds_read_b128 v[180:183], v193 offset:50176
	ds_read_b128 v[196:199], v193 offset:51200
	ds_read_b128 v[200:203], v193 offset:52224
	ds_read_b128 v[204:207], v193 offset:53248
	ds_read_b128 v[208:211], v193 offset:54272
	ds_read_b128 v[212:215], v193 offset:55296
	ds_read_b128 v[216:219], v193 offset:56320
	global_load_lds_dwordx4 v[184:185], off
	s_add_i32 m0, s22, 0x2000
	s_add_u32 s22, s26, 0xb0080
	v_lshl_add_u64 v[184:185], v[220:221], 0, s[16:17]
	s_addc_u32 s23, s27, 0
	s_add_i32 s26, s59, s31
	global_load_lds_dwordx4 v[184:185], off
	v_lshl_add_u64 v[184:185], s[22:23], 0, v[154:155]
	s_mov_b32 m0, s26
	s_nop 0
	global_load_lds_dwordx4 v[184:185], off
	v_lshl_add_u64 v[184:185], s[22:23], 0, v[158:159]
	s_add_i32 m0, s26, 0x2000
	s_nop 0
	global_load_lds_dwordx4 v[184:185], off
	v_lshl_add_u64 v[184:185], v[222:223], 0, s[16:17]
	s_mov_b32 m0, s39
	s_nop 0
	global_load_lds_dwordx4 v[184:185], off
	v_lshl_add_u64 v[184:185], v[224:225], 0, s[16:17]
	s_mov_b32 m0, s40
	s_nop 0
	global_load_lds_dwordx4 v[184:185], off
	s_waitcnt vmcnt(8) lgkmcnt(0)
	s_barrier
	s_setprio 1
	v_mfma_f32_16x16x32_bf16 v[60:63], v[128:131], v[176:179], v[60:63]
	v_mfma_f32_16x16x32_bf16 v[56:59], v[136:139], v[176:179], v[56:59]
	v_mfma_f32_16x16x32_bf16 v[44:47], v[128:131], v[196:199], v[44:47]
	v_mfma_f32_16x16x32_bf16 v[40:43], v[136:139], v[196:199], v[40:43]
	v_mfma_f32_16x16x32_bf16 v[28:31], v[128:131], v[204:207], v[28:31]
	v_mfma_f32_16x16x32_bf16 v[24:27], v[136:139], v[204:207], v[24:27]
	v_mfma_f32_16x16x32_bf16 v[12:15], v[128:131], v[212:215], v[12:15]
	v_mfma_f32_16x16x32_bf16 v[8:11], v[136:139], v[212:215], v[8:11]
	v_mfma_f32_16x16x32_bf16 v[60:63], v[132:135], v[180:183], v[60:63]
	v_mfma_f32_16x16x32_bf16 v[56:59], v[140:143], v[180:183], v[56:59]
	v_mfma_f32_16x16x32_bf16 v[44:47], v[132:135], v[200:203], v[44:47]
	v_mfma_f32_16x16x32_bf16 v[40:43], v[140:143], v[200:203], v[40:43]
	v_mfma_f32_16x16x32_bf16 v[28:31], v[132:135], v[208:211], v[28:31]
	v_mfma_f32_16x16x32_bf16 v[24:27], v[140:143], v[208:211], v[24:27]
	v_mfma_f32_16x16x32_bf16 v[12:15], v[132:135], v[216:219], v[12:15]
	v_mfma_f32_16x16x32_bf16 v[8:11], v[140:143], v[216:219], v[8:11]
	s_setprio 0
	s_setprio 1
	v_mfma_f32_16x16x32_bf16 v[52:55], v[144:147], v[176:179], v[52:55]
	v_mfma_f32_16x16x32_bf16 v[48:51], v[168:171], v[176:179], v[48:51]
	v_mfma_f32_16x16x32_bf16 v[36:39], v[144:147], v[196:199], v[36:39]
	v_mfma_f32_16x16x32_bf16 v[32:35], v[168:171], v[196:199], v[32:35]
	v_mfma_f32_16x16x32_bf16 v[20:23], v[144:147], v[204:207], v[20:23]
	v_mfma_f32_16x16x32_bf16 v[16:19], v[168:171], v[204:207], v[16:19]
	v_mfma_f32_16x16x32_bf16 v[4:7], v[144:147], v[212:215], v[4:7]
	v_mfma_f32_16x16x32_bf16 v[0:3], v[168:171], v[212:215], v[0:3]
	v_mfma_f32_16x16x32_bf16 v[52:55], v[148:151], v[180:183], v[52:55]
	v_mfma_f32_16x16x32_bf16 v[48:51], v[172:175], v[180:183], v[48:51]
	v_mfma_f32_16x16x32_bf16 v[36:39], v[148:151], v[200:203], v[36:39]
	v_mfma_f32_16x16x32_bf16 v[32:35], v[172:175], v[200:203], v[32:35]
	v_mfma_f32_16x16x32_bf16 v[20:23], v[148:151], v[208:211], v[20:23]
	v_mfma_f32_16x16x32_bf16 v[16:19], v[172:175], v[208:211], v[16:19]
	v_mfma_f32_16x16x32_bf16 v[4:7], v[148:151], v[216:219], v[4:7]
	v_mfma_f32_16x16x32_bf16 v[0:3], v[172:175], v[216:219], v[0:3]
	s_barrier
	s_setprio 0
	s_add_i32 s69, s69, 2
	s_add_u32 s67, s67, 0x100
	s_addc_u32 s68, s68, 0
	s_cmp_gt_u32 s69, 41
	s_mov_b64 s[22:23], s[24:25]
	s_cbranch_scc0 .LBB0_1129
	s_and_b64 vcc, exec, s[18:19]
	s_cbranch_vccz .LBB0_1132
	s_barrier

; #define PG8_STAGE(bufoff, gbase, voff) do { _Pragma("unroll") for (int _i = 0; _i < 2; ++_i) \
;         __builtin_amdgcn_global_load_lds((const unsigned*)((const char*)(gbase) + (voff)[_i]), (PG8_LAS unsigned*)(lds + (bufoff) + ldsw + _i * 8192), 16, 0, 0); } while (0)
; #define PG8_LDA(dst, b, h) do { _Pragma("unroll") for (int m = 0; m < 4; ++m) _Pragma("unroll") for (int k = 0; k < 2; ++k) dst[m][k] = *(const PG8_LAS bf16x8*)(lds + PG8_SA(b, h) + aoff + m * 2048 + k * 1024); } while (0)
; #define PG8_LDB(dst, b, h) do { _Pragma("unroll") for (int n = 0; n < 2; ++n) _Pragma("unroll") for (int k = 0; k < 2; ++k) dst[n][k] = *(const PG8_LAS bf16x8*)(lds + PG8_SB(b, h) + boff + n * 2048 + k * 1024); } while (0)
; #define PG8_MMA(ai, bj, At, Bt) do { __builtin_amdgcn_s_setprio(1); _Pragma("unroll") for (int m = 0; m < 4; ++m) _Pragma("unroll") for (int n = 0; n < 2; ++n) _Pragma("unroll") for (int k = 0; k < 2; ++k) \
;         acc[ai][bj][m][n] = __builtin_amdgcn_mfma_f32_16x16x32_bf16(Bt[n][k], At[m][k], acc[ai][bj][m][n], 0, 0, 0); __builtin_amdgcn_s_setprio(0); } while (0)
; #define PG8_WAIT_V(n) asm volatile("s_waitcnt vmcnt(" #n ")" ::: "memory")
; #define PG8_BAR __builtin_amdgcn_s_barrier()
; template <class Epi, class Sched, bool ALIGN_EPI = false, bool SP2 = false>
; __device__ __forceinline__ void gemm_phase(PG8_LAS unsigned char* lds, const Gemm g, const Sched& S, const Epi& E) {
;     ...
;         for (int t = 0; t < nt; t += 2) {
;             const bool last = (t == nt - 2);
;             const char* a1 = cA + (size_t)(t + 1) * kstep;
;             const char* a2 = last ? nA : cA + (size_t)(t + 2) * kstep; const char* b2 = last ? nB : cB + (size_t)(t + 2) * kstep;
;             const char* a3 = a2 + kstep; const char* b3 = b2 + kstep;
;             if (last && has_next) S.a_ready(nxt);
;             if constexpr (SP2) {
;             PG8_LDB(B0, 0, 0); PG8_LDB(B1, 0, 1); PG8_SCHED; PG8_LDA(At, 0, 0); PG8_STAGE(PG8_SA(1, 1), a1 + hstepA, voffA);
;             PG8_WAIT_V(8); PG8_WAIT_L(0); PG8_BAR; PG8_MMA(0, 0, At, B0); PG8_MMA(0, 1, At, B1); PG8_BAR; PG8_SCHED;
;             PG8_LDA(At, 0, 1); PG8_STAGE(PG8_SB(0, 0), b2, voffB); PG8_STAGE(PG8_SB(0, 1), b2 + hstepB, voffB); PG8_STAGE(PG8_SA(0, 0), a2, voffA);
;             PG8_WAIT_V(8); PG8_WAIT_L(0); PG8_BAR; PG8_MMA(1, 0, At, B0); PG8_MMA(1, 1, At, B1); PG8_BAR; PG8_SCHED;
.LBB0_1161:
	s_add_u32 s43, s36, s42
	s_addc_u32 s48, s37, 0
	s_add_u32 s46, s43, 0x100
	s_addc_u32 s47, s48, 0
	s_and_b64 s[44:45], s[40:41], exec
	s_cselect_b32 s45, s25, s47
	s_cselect_b32 s44, s89, s46
	s_add_u32 s42, s34, s42
	s_addc_u32 s46, s35, 0
	s_add_u32 s42, s42, 0x100
	s_addc_u32 s46, s46, 0
	s_and_b64 s[40:41], s[40:41], exec
	s_cselect_b32 s47, s23, s46
	s_cselect_b32 s46, s90, s42
	s_add_u32 s64, s43, 0x10080
	ds_read_b128 v[146:149], v143
	ds_read_b128 v[150:153], v143 offset:1024
	ds_read_b128 v[154:157], v143 offset:2048
	ds_read_b128 v[158:161], v143 offset:3072
	ds_read_b128 v[162:165], v144
	ds_read_b128 v[166:169], v144 offset:1024
	ds_read_b128 v[170:173], v144 offset:2048
	ds_read_b128 v[174:177], v144 offset:3072
	s_addc_u32 s65, s48, 0
	s_add_i32 s97, s82, s67
	s_add_i32 m0, s31, 0xc000
	s_add_i32 s59, s31, 0xe000
	s_add_i32 s58, s97, 0x2000
	s_add_u32 s48, s46, 0x10000
	s_addc_u32 s49, s47, 0
	s_add_i32 vcc_hi, s83, s67
	s_add_i32 vcc_lo, vcc_hi, 0x2000
	s_add_i32 s96, 0, 0x18000
	s_add_i32 s95, 0, 0x1c000
	s_add_u32 s42, s44, 0x10000
	s_addc_u32 s43, s45, 0
	s_add_i32 s94, s96, s67
	s_add_i32 s92, s94, 0x2000
	s_add_u32 s40, s46, 0x10080
	s_addc_u32 s41, s47, 0
	s_add_i32 s93, s95, s67
	s_add_i32 s91, s93, 0x2000
	v_lshl_add_u64 v[212:213], s[64:65], 0, v[134:135]
	ds_read_b128 v[178:181], v145
	ds_read_b128 v[182:185], v145 offset:1024
	ds_read_b128 v[188:191], v145 offset:2048
	ds_read_b128 v[192:195], v145 offset:3072
	ds_read_b128 v[196:199], v145 offset:4096
	ds_read_b128 v[200:203], v145 offset:5120
	ds_read_b128 v[204:207], v145 offset:6144
	ds_read_b128 v[208:211], v145 offset:7168
	global_load_lds_dwordx4 v[212:213], off
	v_lshl_add_u64 v[212:213], s[64:65], 0, v[130:131]
	s_mov_b32 m0, s59
	s_nop 0
	global_load_lds_dwordx4 v[212:213], off
	s_waitcnt vmcnt(8) lgkmcnt(0)
	s_barrier
	s_setprio 1
	v_mfma_f32_16x16x32_bf16 v[124:127], v[146:149], v[178:181], v[124:127]
	v_mfma_f32_16x16x32_bf16 v[120:123], v[154:157], v[178:181], v[120:123]
	v_mfma_f32_16x16x32_bf16 v[116:119], v[146:149], v[188:191], v[116:119]
	v_mfma_f32_16x16x32_bf16 v[108:111], v[154:157], v[188:191], v[108:111]
	v_mfma_f32_16x16x32_bf16 v[100:103], v[146:149], v[196:199], v[100:103]
	v_mfma_f32_16x16x32_bf16 v[92:95], v[154:157], v[196:199], v[92:95]
	v_mfma_f32_16x16x32_bf16 v[84:87], v[146:149], v[204:207], v[84:87]
	v_mfma_f32_16x16x32_bf16 v[76:79], v[154:157], v[204:207], v[76:79]
	v_mfma_f32_16x16x32_bf16 v[124:127], v[150:153], v[182:185], v[124:127]
	v_mfma_f32_16x16x32_bf16 v[120:123], v[158:161], v[182:185], v[120:123]
	v_mfma_f32_16x16x32_bf16 v[116:119], v[150:153], v[192:195], v[116:119]
	v_mfma_f32_16x16x32_bf16 v[108:111], v[158:161], v[192:195], v[108:111]
	v_mfma_f32_16x16x32_bf16 v[100:103], v[150:153], v[200:203], v[100:103]
	v_mfma_f32_16x16x32_bf16 v[92:95], v[158:161], v[200:203], v[92:95]
	v_mfma_f32_16x16x32_bf16 v[84:87], v[150:153], v[208:211], v[84:87]
	v_mfma_f32_16x16x32_bf16 v[76:79], v[158:161], v[208:211], v[76:79]
	s_setprio 0
	s_setprio 1
	v_mfma_f32_16x16x32_bf16 v[112:115], v[162:165], v[178:181], v[112:115]
	v_mfma_f32_16x16x32_bf16 v[104:107], v[170:173], v[178:181], v[104:107]
	v_mfma_f32_16x16x32_bf16 v[96:99], v[162:165], v[188:191], v[96:99]
	v_mfma_f32_16x16x32_bf16 v[88:91], v[170:173], v[188:191], v[88:91]
	v_mfma_f32_16x16x32_bf16 v[80:83], v[162:165], v[196:199], v[80:83]
	v_mfma_f32_16x16x32_bf16 v[72:75], v[170:173], v[196:199], v[72:75]
	v_mfma_f32_16x16x32_bf16 v[68:71], v[162:165], v[204:207], v[68:71]
	v_mfma_f32_16x16x32_bf16 v[64:67], v[170:173], v[204:207], v[64:67]
	v_mfma_f32_16x16x32_bf16 v[112:115], v[166:169], v[182:185], v[112:115]
	v_mfma_f32_16x16x32_bf16 v[104:107], v[174:177], v[182:185], v[104:107]
	v_mfma_f32_16x16x32_bf16 v[96:99], v[166:169], v[192:195], v[96:99]
	v_mfma_f32_16x16x32_bf16 v[88:91], v[174:177], v[192:195], v[88:91]
	v_mfma_f32_16x16x32_bf16 v[80:83], v[166:169], v[200:203], v[80:83]
	v_mfma_f32_16x16x32_bf16 v[72:75], v[174:177], v[200:203], v[72:75]
	v_mfma_f32_16x16x32_bf16 v[68:71], v[166:169], v[208:211], v[68:71]
	v_mfma_f32_16x16x32_bf16 v[64:67], v[174:177], v[208:211], v[64:67]
	s_barrier
	s_setprio 0
	s_mov_b32 m0, s97
	v_lshl_add_u64 v[212:213], s[46:47], 0, v[132:133]
	ds_read_b128 v[178:181], v145 offset:16384
	ds_read_b128 v[182:185], v145 offset:17408
	ds_read_b128 v[188:191], v145 offset:18432
	ds_read_b128 v[192:195], v145 offset:19456
	ds_read_b128 v[196:199], v145 offset:20480
	ds_read_b128 v[200:203], v145 offset:21504
	ds_read_b128 v[204:207], v145 offset:22528
	ds_read_b128 v[208:211], v145 offset:23552
	global_load_lds_dwordx4 v[212:213], off
	v_lshl_add_u64 v[214:215], s[46:47], 0, v[128:129]
	s_mov_b32 m0, s58
	v_lshl_add_u64 v[216:217], s[48:49], 0, v[132:133]
	global_load_lds_dwordx4 v[214:215], off
	s_mov_b32 m0, vcc_hi
	v_lshl_add_u64 v[218:219], s[44:45], 0, v[130:131]
	global_load_lds_dwordx4 v[216:217], off
	v_lshl_add_u64 v[216:217], s[48:49], 0, v[128:129]
	s_mov_b32 m0, vcc_lo
	s_nop 0
	global_load_lds_dwordx4 v[216:217], off
	v_lshl_add_u64 v[216:217], s[44:45], 0, v[134:135]
	s_mov_b32 m0, s31
	s_nop 0
	global_load_lds_dwordx4 v[216:217], off
	s_mov_b32 m0, s74
	s_nop 0
	global_load_lds_dwordx4 v[218:219], off
	s_waitcnt vmcnt(8) lgkmcnt(0)
	s_barrier
; #define PG8_STAGE(bufoff, gbase, voff) do { _Pragma("unroll") for (int _i = 0; _i < 2; ++_i) \
;         __builtin_amdgcn_global_load_lds((const unsigned*)((const char*)(gbase) + (voff)[_i]), (PG8_LAS unsigned*)(lds + (bufoff) + ldsw + _i * 8192), 16, 0, 0); } while (0)
; #define PG8_LDA(dst, b, h) do { _Pragma("unroll") for (int m = 0; m < 4; ++m) _Pragma("unroll") for (int k = 0; k < 2; ++k) dst[m][k] = *(const PG8_LAS bf16x8*)(lds + PG8_SA(b, h) + aoff + m * 2048 + k * 1024); } while (0)
; #define PG8_LDB(dst, b, h) do { _Pragma("unroll") for (int n = 0; n < 2; ++n) _Pragma("unroll") for (int k = 0; k < 2; ++k) dst[n][k] = *(const PG8_LAS bf16x8*)(lds + PG8_SB(b, h) + boff + n * 2048 + k * 1024); } while (0)
; #define PG8_MMA(ai, bj, At, Bt) do { __builtin_amdgcn_s_setprio(1); _Pragma("unroll") for (int m = 0; m < 4; ++m) _Pragma("unroll") for (int n = 0; n < 2; ++n) _Pragma("unroll") for (int k = 0; k < 2; ++k) \
;         acc[ai][bj][m][n] = __builtin_amdgcn_mfma_f32_16x16x32_bf16(Bt[n][k], At[m][k], acc[ai][bj][m][n], 0, 0, 0); __builtin_amdgcn_s_setprio(0); } while (0)
; #define PG8_WAIT_V(n) asm volatile("s_waitcnt vmcnt(" #n ")" ::: "memory")
; #define PG8_WAIT_L(n) asm volatile("s_waitcnt lgkmcnt(" #n ")" ::: "memory")
; #define PG8_BAR __builtin_amdgcn_s_barrier()
; #define PG8_SCHED __builtin_amdgcn_sched_barrier(0)
; template <class Epi, class Sched, bool ALIGN_EPI = false, bool SP2 = false>
; __device__ __forceinline__ void gemm_phase(PG8_LAS unsigned char* lds, const Gemm g, const Sched& S, const Epi& E) {
;     ...
;             PG8_WAIT_V(8); PG8_WAIT_L(0); PG8_BAR; PG8_MMA(1, 0, At, B0); PG8_MMA(1, 1, At, B1); PG8_BAR; PG8_SCHED;
;             PG8_LDB(B0, 1, 0); PG8_LDB(B1, 1, 1); PG8_SCHED; PG8_LDA(At, 1, 0); PG8_STAGE(PG8_SA(0, 1), a2 + hstepA, voffA);
;             PG8_WAIT_V(8); PG8_WAIT_L(0); PG8_BAR; PG8_MMA(0, 0, At, B0); PG8_MMA(0, 1, At, B1); PG8_BAR; PG8_SCHED;
	s_setprio 1
	v_mfma_f32_16x16x32_bf16 v[60:63], v[146:149], v[178:181], v[60:63]
	v_mfma_f32_16x16x32_bf16 v[56:59], v[154:157], v[178:181], v[56:59]
	v_mfma_f32_16x16x32_bf16 v[52:55], v[146:149], v[188:191], v[52:55]
	v_mfma_f32_16x16x32_bf16 v[44:47], v[154:157], v[188:191], v[44:47]
	v_mfma_f32_16x16x32_bf16 v[36:39], v[146:149], v[196:199], v[36:39]
	v_mfma_f32_16x16x32_bf16 v[28:31], v[154:157], v[196:199], v[28:31]
	v_mfma_f32_16x16x32_bf16 v[20:23], v[146:149], v[204:207], v[20:23]
	v_mfma_f32_16x16x32_bf16 v[12:15], v[154:157], v[204:207], v[12:15]
	v_mfma_f32_16x16x32_bf16 v[60:63], v[150:153], v[182:185], v[60:63]
	v_mfma_f32_16x16x32_bf16 v[56:59], v[158:161], v[182:185], v[56:59]
	v_mfma_f32_16x16x32_bf16 v[52:55], v[150:153], v[192:195], v[52:55]
	v_mfma_f32_16x16x32_bf16 v[44:47], v[158:161], v[192:195], v[44:47]
	v_mfma_f32_16x16x32_bf16 v[36:39], v[150:153], v[200:203], v[36:39]
	v_mfma_f32_16x16x32_bf16 v[28:31], v[158:161], v[200:203], v[28:31]
	v_mfma_f32_16x16x32_bf16 v[20:23], v[150:153], v[208:211], v[20:23]
	v_mfma_f32_16x16x32_bf16 v[12:15], v[158:161], v[208:211], v[12:15]
	s_setprio 0
	s_setprio 1
	v_mfma_f32_16x16x32_bf16 v[48:51], v[162:165], v[178:181], v[48:51]
	v_mfma_f32_16x16x32_bf16 v[40:43], v[170:173], v[178:181], v[40:43]
	v_mfma_f32_16x16x32_bf16 v[32:35], v[162:165], v[188:191], v[32:35]
	v_mfma_f32_16x16x32_bf16 v[24:27], v[170:173], v[188:191], v[24:27]
	v_mfma_f32_16x16x32_bf16 v[16:19], v[162:165], v[196:199], v[16:19]
	v_mfma_f32_16x16x32_bf16 v[8:11], v[170:173], v[196:199], v[8:11]
	v_mfma_f32_16x16x32_bf16 v[4:7], v[162:165], v[204:207], v[4:7]
	v_mfma_f32_16x16x32_bf16 v[0:3], v[170:173], v[204:207], v[0:3]
	v_mfma_f32_16x16x32_bf16 v[48:51], v[166:169], v[182:185], v[48:51]
	v_mfma_f32_16x16x32_bf16 v[40:43], v[174:177], v[182:185], v[40:43]
	v_mfma_f32_16x16x32_bf16 v[32:35], v[166:169], v[192:195], v[32:35]
	v_mfma_f32_16x16x32_bf16 v[24:27], v[174:177], v[192:195], v[24:27]
	v_mfma_f32_16x16x32_bf16 v[16:19], v[166:169], v[200:203], v[16:19]
	v_mfma_f32_16x16x32_bf16 v[8:11], v[174:177], v[200:203], v[8:11]
	v_mfma_f32_16x16x32_bf16 v[4:7], v[166:169], v[208:211], v[4:7]
	v_mfma_f32_16x16x32_bf16 v[0:3], v[174:177], v[208:211], v[0:3]
	s_barrier
	s_setprio 0
	v_add_u32_e32 v158, s96, v141
	v_add_u32_e32 v174, s95, v141
	ds_read_b128 v[146:149], v158
	ds_read_b128 v[150:153], v158 offset:1024
	ds_read_b128 v[154:157], v158 offset:2048
	ds_read_b128 v[158:161], v158 offset:3072
	ds_read_b128 v[162:165], v174
	ds_read_b128 v[166:169], v174 offset:1024
	ds_read_b128 v[170:173], v174 offset:2048
	ds_read_b128 v[174:177], v174 offset:3072
	s_mov_b32 m0, s75
	v_lshl_add_u64 v[220:221], s[42:43], 0, v[134:135]
	ds_read_b128 v[178:181], v145 offset:32768
	ds_read_b128 v[182:185], v145 offset:33792
	ds_read_b128 v[188:191], v145 offset:34816
	ds_read_b128 v[192:195], v145 offset:35840
	ds_read_b128 v[196:199], v145 offset:36864
	ds_read_b128 v[200:203], v145 offset:37888
	ds_read_b128 v[204:207], v145 offset:38912
	ds_read_b128 v[208:211], v145 offset:39936
	global_load_lds_dwordx4 v[220:221], off
	v_lshl_add_u64 v[220:221], s[42:43], 0, v[130:131]
	s_mov_b32 m0, s76
	s_nop 0
	global_load_lds_dwordx4 v[220:221], off
	s_waitcnt vmcnt(8) lgkmcnt(0)
	s_barrier
	s_setprio 1
	v_mfma_f32_16x16x32_bf16 v[124:127], v[146:149], v[178:181], v[124:127]
	v_mfma_f32_16x16x32_bf16 v[120:123], v[154:157], v[178:181], v[120:123]
	v_mfma_f32_16x16x32_bf16 v[116:119], v[146:149], v[188:191], v[116:119]
	v_mfma_f32_16x16x32_bf16 v[108:111], v[154:157], v[188:191], v[108:111]
	v_mfma_f32_16x16x32_bf16 v[100:103], v[146:149], v[196:199], v[100:103]
	v_mfma_f32_16x16x32_bf16 v[92:95], v[154:157], v[196:199], v[92:95]
	v_mfma_f32_16x16x32_bf16 v[84:87], v[146:149], v[204:207], v[84:87]
	v_mfma_f32_16x16x32_bf16 v[76:79], v[154:157], v[204:207], v[76:79]
	v_mfma_f32_16x16x32_bf16 v[124:127], v[150:153], v[182:185], v[124:127]
	v_mfma_f32_16x16x32_bf16 v[120:123], v[158:161], v[182:185], v[120:123]
	v_mfma_f32_16x16x32_bf16 v[116:119], v[150:153], v[192:195], v[116:119]
	v_mfma_f32_16x16x32_bf16 v[108:111], v[158:161], v[192:195], v[108:111]
	v_mfma_f32_16x16x32_bf16 v[100:103], v[150:153], v[200:203], v[100:103]
	v_mfma_f32_16x16x32_bf16 v[92:95], v[158:161], v[200:203], v[92:95]
	v_mfma_f32_16x16x32_bf16 v[84:87], v[150:153], v[208:211], v[84:87]
	v_mfma_f32_16x16x32_bf16 v[76:79], v[158:161], v[208:211], v[76:79]
	s_setprio 0
	s_setprio 1
	v_mfma_f32_16x16x32_bf16 v[112:115], v[162:165], v[178:181], v[112:115]
	v_mfma_f32_16x16x32_bf16 v[104:107], v[170:173], v[178:181], v[104:107]
	v_mfma_f32_16x16x32_bf16 v[96:99], v[162:165], v[188:191], v[96:99]
	v_mfma_f32_16x16x32_bf16 v[88:91], v[170:173], v[188:191], v[88:91]
	v_mfma_f32_16x16x32_bf16 v[80:83], v[162:165], v[196:199], v[80:83]
	v_mfma_f32_16x16x32_bf16 v[72:75], v[170:173], v[196:199], v[72:75]
	v_mfma_f32_16x16x32_bf16 v[68:71], v[162:165], v[204:207], v[68:71]
	v_mfma_f32_16x16x32_bf16 v[64:67], v[170:173], v[204:207], v[64:67]
	v_mfma_f32_16x16x32_bf16 v[112:115], v[166:169], v[182:185], v[112:115]
	v_mfma_f32_16x16x32_bf16 v[104:107], v[174:177], v[182:185], v[104:107]
	v_mfma_f32_16x16x32_bf16 v[96:99], v[166:169], v[192:195], v[96:99]
	v_mfma_f32_16x16x32_bf16 v[88:91], v[174:177], v[192:195], v[88:91]
	v_mfma_f32_16x16x32_bf16 v[80:83], v[166:169], v[200:203], v[80:83]
	v_mfma_f32_16x16x32_bf16 v[72:75], v[174:177], v[200:203], v[72:75]
	v_mfma_f32_16x16x32_bf16 v[68:71], v[166:169], v[208:211], v[68:71]
	v_mfma_f32_16x16x32_bf16 v[64:67], v[174:177], v[208:211], v[64:67]
	s_barrier
; #define PG8_STAGE(bufoff, gbase, voff) do { _Pragma("unroll") for (int _i = 0; _i < 2; ++_i) \
;         __builtin_amdgcn_global_load_lds((const unsigned*)((const char*)(gbase) + (voff)[_i]), (PG8_LAS unsigned*)(lds + (bufoff) + ldsw + _i * 8192), 16, 0, 0); } while (0)
; #define PG8_LDA(dst, b, h) do { _Pragma("unroll") for (int m = 0; m < 4; ++m) _Pragma("unroll") for (int k = 0; k < 2; ++k) dst[m][k] = *(const PG8_LAS bf16x8*)(lds + PG8_SA(b, h) + aoff + m * 2048 + k * 1024); } while (0)
; #define PG8_MMA(ai, bj, At, Bt) do { __builtin_amdgcn_s_setprio(1); _Pragma("unroll") for (int m = 0; m < 4; ++m) _Pragma("unroll") for (int n = 0; n < 2; ++n) _Pragma("unroll") for (int k = 0; k < 2; ++k) \
;         acc[ai][bj][m][n] = __builtin_amdgcn_mfma_f32_16x16x32_bf16(Bt[n][k], At[m][k], acc[ai][bj][m][n], 0, 0, 0); __builtin_amdgcn_s_setprio(0); } while (0)
; #define PG8_WAIT_V(n) asm volatile("s_waitcnt vmcnt(" #n ")" ::: "memory")
; #define PG8_WAIT_L(n) asm volatile("s_waitcnt lgkmcnt(" #n ")" ::: "memory")
; #define PG8_BAR __builtin_amdgcn_s_barrier()
; #define PG8_SCHED __builtin_amdgcn_sched_barrier(0)
; template <class Epi, class Sched, bool ALIGN_EPI = false, bool SP2 = false>
; __device__ __forceinline__ void gemm_phase(PG8_LAS unsigned char* lds, const Gemm g, const Sched& S, const Epi& E) {
;     ...
;             PG8_LDA(At, 1, 1); PG8_STAGE(PG8_SB(1, 0), b3, voffB); PG8_STAGE(PG8_SB(1, 1), b3 + hstepB, voffB); PG8_STAGE(PG8_SA(1, 0), a3, voffA);
;             PG8_WAIT_V(8); PG8_WAIT_L(0); PG8_BAR; PG8_MMA(1, 0, At, B0); PG8_MMA(1, 1, At, B1); PG8_BAR; PG8_SCHED;
	s_setprio 0
	s_mov_b32 m0, s94
	v_lshl_add_u64 v[212:213], v[212:213], 0, s[10:11]
	ds_read_b128 v[178:181], v145 offset:49152
	ds_read_b128 v[182:185], v145 offset:50176
	ds_read_b128 v[188:191], v145 offset:51200
	ds_read_b128 v[192:195], v145 offset:52224
	ds_read_b128 v[196:199], v145 offset:53248
	ds_read_b128 v[200:203], v145 offset:54272
	ds_read_b128 v[204:207], v145 offset:55296
	ds_read_b128 v[208:211], v145 offset:56320
	global_load_lds_dwordx4 v[212:213], off
	v_lshl_add_u64 v[212:213], v[214:215], 0, s[10:11]
	s_mov_b32 m0, s92
	s_nop 0
	global_load_lds_dwordx4 v[212:213], off
	v_lshl_add_u64 v[212:213], s[40:41], 0, v[132:133]
	s_mov_b32 m0, s93
	s_nop 0
	global_load_lds_dwordx4 v[212:213], off
	v_lshl_add_u64 v[212:213], s[40:41], 0, v[128:129]
	s_mov_b32 m0, s91
	s_nop 0
	global_load_lds_dwordx4 v[212:213], off
	v_lshl_add_u64 v[212:213], v[216:217], 0, s[10:11]
	s_mov_b32 m0, s78
	s_nop 0
	global_load_lds_dwordx4 v[212:213], off
	v_lshl_add_u64 v[212:213], v[218:219], 0, s[10:11]
	s_mov_b32 m0, s79
	s_nop 0
	global_load_lds_dwordx4 v[212:213], off
	s_waitcnt vmcnt(8) lgkmcnt(0)
	s_barrier
	s_setprio 1
	v_mfma_f32_16x16x32_bf16 v[60:63], v[146:149], v[178:181], v[60:63]
	v_mfma_f32_16x16x32_bf16 v[56:59], v[154:157], v[178:181], v[56:59]
	v_mfma_f32_16x16x32_bf16 v[52:55], v[146:149], v[188:191], v[52:55]
	v_mfma_f32_16x16x32_bf16 v[44:47], v[154:157], v[188:191], v[44:47]
	v_mfma_f32_16x16x32_bf16 v[36:39], v[146:149], v[196:199], v[36:39]
	v_mfma_f32_16x16x32_bf16 v[28:31], v[154:157], v[196:199], v[28:31]
	v_mfma_f32_16x16x32_bf16 v[20:23], v[146:149], v[204:207], v[20:23]
	v_mfma_f32_16x16x32_bf16 v[12:15], v[154:157], v[204:207], v[12:15]
	v_mfma_f32_16x16x32_bf16 v[60:63], v[150:153], v[182:185], v[60:63]
	v_mfma_f32_16x16x32_bf16 v[56:59], v[158:161], v[182:185], v[56:59]
	v_mfma_f32_16x16x32_bf16 v[52:55], v[150:153], v[192:195], v[52:55]
	v_mfma_f32_16x16x32_bf16 v[44:47], v[158:161], v[192:195], v[44:47]
	v_mfma_f32_16x16x32_bf16 v[36:39], v[150:153], v[200:203], v[36:39]
	v_mfma_f32_16x16x32_bf16 v[28:31], v[158:161], v[200:203], v[28:31]
	v_mfma_f32_16x16x32_bf16 v[20:23], v[150:153], v[208:211], v[20:23]
	v_mfma_f32_16x16x32_bf16 v[12:15], v[158:161], v[208:211], v[12:15]
	s_setprio 0
	s_setprio 1
	v_mfma_f32_16x16x32_bf16 v[48:51], v[162:165], v[178:181], v[48:51]
	v_mfma_f32_16x16x32_bf16 v[40:43], v[170:173], v[178:181], v[40:43]
	v_mfma_f32_16x16x32_bf16 v[32:35], v[162:165], v[188:191], v[32:35]
	v_mfma_f32_16x16x32_bf16 v[24:27], v[170:173], v[188:191], v[24:27]
	v_mfma_f32_16x16x32_bf16 v[16:19], v[162:165], v[196:199], v[16:19]
	v_mfma_f32_16x16x32_bf16 v[8:11], v[170:173], v[196:199], v[8:11]
	v_mfma_f32_16x16x32_bf16 v[4:7], v[162:165], v[204:207], v[4:7]
	v_mfma_f32_16x16x32_bf16 v[0:3], v[170:173], v[204:207], v[0:3]
	v_mfma_f32_16x16x32_bf16 v[48:51], v[166:169], v[182:185], v[48:51]
	v_mfma_f32_16x16x32_bf16 v[40:43], v[174:177], v[182:185], v[40:43]
	v_mfma_f32_16x16x32_bf16 v[32:35], v[166:169], v[192:195], v[32:35]
	v_mfma_f32_16x16x32_bf16 v[24:27], v[174:177], v[192:195], v[24:27]
	v_mfma_f32_16x16x32_bf16 v[16:19], v[166:169], v[200:203], v[16:19]
	v_mfma_f32_16x16x32_bf16 v[8:11], v[174:177], v[200:203], v[8:11]
	v_mfma_f32_16x16x32_bf16 v[4:7], v[166:169], v[208:211], v[4:7]
	v_mfma_f32_16x16x32_bf16 v[0:3], v[174:177], v[208:211], v[0:3]
	s_barrier
	s_setprio 0
	s_movk_i32 s42, 0x100
	s_andn2_b64 vcc, exec, s[38:39]
	s_mov_b64 s[40:41], -1
	s_mov_b64 s[38:39], 0
	s_cbranch_vccz .LBB0_1161
	s_and_b64 vcc, exec, s[14:15]
	s_cbranch_vccz .LBB0_1164
	s_barrier

; #define PG8_STAGE(bufoff, gbase, voff) do { _Pragma("unroll") for (int _i = 0; _i < 2; ++_i) \
;         __builtin_amdgcn_global_load_lds((const unsigned*)((const char*)(gbase) + (voff)[_i]), (PG8_LAS unsigned*)(lds + (bufoff) + ldsw + _i * 8192), 16, 0, 0); } while (0)
; #define PG8_LDA(dst, b, h) do { _Pragma("unroll") for (int m = 0; m < 4; ++m) _Pragma("unroll") for (int k = 0; k < 2; ++k) dst[m][k] = *(const PG8_LAS bf16x8*)(lds + PG8_SA(b, h) + aoff + m * 2048 + k * 1024); } while (0)
; #define PG8_LDB(dst, b, h) do { _Pragma("unroll") for (int n = 0; n < 2; ++n) _Pragma("unroll") for (int k = 0; k < 2; ++k) dst[n][k] = *(const PG8_LAS bf16x8*)(lds + PG8_SB(b, h) + boff + n * 2048 + k * 1024); } while (0)
; #define PG8_MMA(ai, bj, At, Bt) do { __builtin_amdgcn_s_setprio(1); _Pragma("unroll") for (int m = 0; m < 4; ++m) _Pragma("unroll") for (int n = 0; n < 2; ++n) _Pragma("unroll") for (int k = 0; k < 2; ++k) \
;         acc[ai][bj][m][n] = __builtin_amdgcn_mfma_f32_16x16x32_bf16(Bt[n][k], At[m][k], acc[ai][bj][m][n], 0, 0, 0); __builtin_amdgcn_s_setprio(0); } while (0)
; #define PG8_WAIT_V(n) asm volatile("s_waitcnt vmcnt(" #n ")" ::: "memory")
; #define PG8_BAR __builtin_amdgcn_s_barrier()
; template <class Epi, class Sched, bool ALIGN_EPI = false, bool SP2 = false>
; __device__ __forceinline__ void gemm_phase(PG8_LAS unsigned char* lds, const Gemm g, const Sched& S, const Epi& E) {
;     ...
;         for (int t = 0; t < nt; t += 2) {
;             const bool last = (t == nt - 2);
;             const char* a1 = cA + (size_t)(t + 1) * kstep;
;             const char* a2 = last ? nA : cA + (size_t)(t + 2) * kstep; const char* b2 = last ? nB : cB + (size_t)(t + 2) * kstep;
;             const char* a3 = a2 + kstep; const char* b3 = b2 + kstep;
;             if (last && has_next) S.a_ready(nxt);
;             if constexpr (SP2) {
;             PG8_LDB(B0, 0, 0); PG8_LDB(B1, 0, 1); PG8_SCHED; PG8_LDA(At, 0, 0); PG8_STAGE(PG8_SA(1, 1), a1 + hstepA, voffA);
;             PG8_WAIT_V(8); PG8_WAIT_L(0); PG8_BAR; PG8_MMA(0, 0, At, B0); PG8_MMA(0, 1, At, B1); PG8_BAR; PG8_SCHED;
;             PG8_LDA(At, 0, 1); PG8_STAGE(PG8_SB(0, 0), b2, voffB); PG8_STAGE(PG8_SB(0, 1), b2 + hstepB, voffB); PG8_STAGE(PG8_SA(0, 0), a2, voffA);
;             PG8_WAIT_V(8); PG8_WAIT_L(0); PG8_BAR; PG8_MMA(1, 0, At, B0); PG8_MMA(1, 1, At, B1); PG8_BAR; PG8_SCHED;
.LBB0_1231:
	ds_read_b128 v[112:115], v185
	ds_read_b128 v[116:119], v185 offset:1024
	ds_read_b128 v[128:131], v185 offset:2048
	ds_read_b128 v[140:143], v185 offset:3072
	ds_read_b128 v[144:147], v188
	ds_read_b128 v[148:151], v188 offset:1024
	ds_read_b128 v[168:171], v188 offset:2048
	ds_read_b128 v[172:175], v188 offset:3072
	s_add_u32 s34, s30, 0xfffc0080
	s_addc_u32 s35, s31, -1
	s_cmp_eq_u32 s69, 12
	s_cselect_b32 s37, s21, s35
	s_cselect_b32 s36, s27, s34
	s_cselect_b32 s35, s19, s68
	s_cselect_b32 s34, s66, s67
	v_lshl_add_u64 v[180:181], s[30:31], 0, v[160:161]
	s_add_i32 m0, s29, 0xc000
	ds_read_b128 v[176:179], v189
	ds_read_b128 v[192:195], v189 offset:1024
	ds_read_b128 v[196:199], v189 offset:2048
	ds_read_b128 v[200:203], v189 offset:3072
	ds_read_b128 v[204:207], v189 offset:4096
	ds_read_b128 v[208:211], v189 offset:5120
	ds_read_b128 v[212:215], v189 offset:6144
	ds_read_b128 v[216:219], v189 offset:7168
	global_load_lds_dwordx4 v[180:181], off
	v_lshl_add_u64 v[180:181], s[30:31], 0, v[162:163]
	s_add_i32 m0, s29, 0xe000
	s_nop 0
	global_load_lds_dwordx4 v[180:181], off
	s_waitcnt vmcnt(8) lgkmcnt(0)
	s_barrier
	s_setprio 1
	v_mfma_f32_16x16x32_bf16 v[136:139], v[112:115], v[176:179], v[136:139]
	v_mfma_f32_16x16x32_bf16 v[132:135], v[128:131], v[176:179], v[132:135]
	v_mfma_f32_16x16x32_bf16 v[108:111], v[112:115], v[196:199], v[108:111]
	v_mfma_f32_16x16x32_bf16 v[104:107], v[128:131], v[196:199], v[104:107]
	v_mfma_f32_16x16x32_bf16 v[92:95], v[112:115], v[204:207], v[92:95]
	v_mfma_f32_16x16x32_bf16 v[88:91], v[128:131], v[204:207], v[88:91]
	v_mfma_f32_16x16x32_bf16 v[76:79], v[112:115], v[212:215], v[76:79]
	v_mfma_f32_16x16x32_bf16 v[72:75], v[128:131], v[212:215], v[72:75]
	v_mfma_f32_16x16x32_bf16 v[136:139], v[116:119], v[192:195], v[136:139]
	v_mfma_f32_16x16x32_bf16 v[132:135], v[140:143], v[192:195], v[132:135]
	v_mfma_f32_16x16x32_bf16 v[108:111], v[116:119], v[200:203], v[108:111]
	v_mfma_f32_16x16x32_bf16 v[104:107], v[140:143], v[200:203], v[104:107]
	v_mfma_f32_16x16x32_bf16 v[92:95], v[116:119], v[208:211], v[92:95]
	v_mfma_f32_16x16x32_bf16 v[88:91], v[140:143], v[208:211], v[88:91]
	v_mfma_f32_16x16x32_bf16 v[76:79], v[116:119], v[216:219], v[76:79]
	v_mfma_f32_16x16x32_bf16 v[72:75], v[140:143], v[216:219], v[72:75]
	s_setprio 0
	s_setprio 1
	v_mfma_f32_16x16x32_bf16 v[124:127], v[144:147], v[176:179], v[124:127]
	v_mfma_f32_16x16x32_bf16 v[120:123], v[168:171], v[176:179], v[120:123]
	v_mfma_f32_16x16x32_bf16 v[100:103], v[144:147], v[196:199], v[100:103]
	v_mfma_f32_16x16x32_bf16 v[96:99], v[168:171], v[196:199], v[96:99]
	v_mfma_f32_16x16x32_bf16 v[84:87], v[144:147], v[204:207], v[84:87]
	v_mfma_f32_16x16x32_bf16 v[80:83], v[168:171], v[204:207], v[80:83]
	v_mfma_f32_16x16x32_bf16 v[68:71], v[144:147], v[212:215], v[68:71]
	v_mfma_f32_16x16x32_bf16 v[64:67], v[168:171], v[212:215], v[64:67]
	v_mfma_f32_16x16x32_bf16 v[124:127], v[148:151], v[192:195], v[124:127]
	v_mfma_f32_16x16x32_bf16 v[120:123], v[172:175], v[192:195], v[120:123]
	v_mfma_f32_16x16x32_bf16 v[100:103], v[148:151], v[200:203], v[100:103]
	v_mfma_f32_16x16x32_bf16 v[96:99], v[172:175], v[200:203], v[96:99]
	v_mfma_f32_16x16x32_bf16 v[84:87], v[148:151], v[208:211], v[84:87]
	v_mfma_f32_16x16x32_bf16 v[80:83], v[172:175], v[208:211], v[80:83]
	v_mfma_f32_16x16x32_bf16 v[68:71], v[148:151], v[216:219], v[68:71]
	v_mfma_f32_16x16x32_bf16 v[64:67], v[172:175], v[216:219], v[64:67]
	s_barrier
	s_setprio 0
	s_add_i32 s58, s49, s39
	v_lshl_add_u64 v[180:181], s[34:35], 0, v[154:155]
	s_mov_b32 m0, s58
	ds_read_b128 v[176:179], v189 offset:16384
	ds_read_b128 v[192:195], v189 offset:17408
	ds_read_b128 v[196:199], v189 offset:18432
	ds_read_b128 v[200:203], v189 offset:19456
	ds_read_b128 v[204:207], v189 offset:20480
	ds_read_b128 v[208:211], v189 offset:21504
	ds_read_b128 v[212:215], v189 offset:22528
	ds_read_b128 v[216:219], v189 offset:23552
	global_load_lds_dwordx4 v[180:181], off
	s_add_i32 m0, s58, 0x2000
	s_add_u32 s58, s34, 0x40000
	v_lshl_add_u64 v[220:221], s[34:35], 0, v[158:159]
	s_addc_u32 s59, s35, 0
	s_add_i32 s73, s64, s39
	global_load_lds_dwordx4 v[220:221], off
	v_lshl_add_u64 v[222:223], s[58:59], 0, v[154:155]
	s_mov_b32 m0, s73
	v_lshl_add_u64 v[224:225], s[36:37], 0, v[156:157]
	global_load_lds_dwordx4 v[222:223], off
	v_lshl_add_u64 v[222:223], s[58:59], 0, v[158:159]
	s_add_i32 m0, s73, 0x2000
	s_nop 0
	global_load_lds_dwordx4 v[222:223], off
	v_lshl_add_u64 v[222:223], s[36:37], 0, v[152:153]
	s_mov_b32 m0, s29
	s_nop 0
	global_load_lds_dwordx4 v[222:223], off
	s_mov_b32 m0, s40
	s_nop 0
	global_load_lds_dwordx4 v[224:225], off
	s_waitcnt vmcnt(8) lgkmcnt(0)
	s_barrier
; #define PG8_STAGE(bufoff, gbase, voff) do { _Pragma("unroll") for (int _i = 0; _i < 2; ++_i) \
;         __builtin_amdgcn_global_load_lds((const unsigned*)((const char*)(gbase) + (voff)[_i]), (PG8_LAS unsigned*)(lds + (bufoff) + ldsw + _i * 8192), 16, 0, 0); } while (0)
; #define PG8_LDA(dst, b, h) do { _Pragma("unroll") for (int m = 0; m < 4; ++m) _Pragma("unroll") for (int k = 0; k < 2; ++k) dst[m][k] = *(const PG8_LAS bf16x8*)(lds + PG8_SA(b, h) + aoff + m * 2048 + k * 1024); } while (0)
; #define PG8_LDB(dst, b, h) do { _Pragma("unroll") for (int n = 0; n < 2; ++n) _Pragma("unroll") for (int k = 0; k < 2; ++k) dst[n][k] = *(const PG8_LAS bf16x8*)(lds + PG8_SB(b, h) + boff + n * 2048 + k * 1024); } while (0)
; #define PG8_MMA(ai, bj, At, Bt) do { __builtin_amdgcn_s_setprio(1); _Pragma("unroll") for (int m = 0; m < 4; ++m) _Pragma("unroll") for (int n = 0; n < 2; ++n) _Pragma("unroll") for (int k = 0; k < 2; ++k) \
;         acc[ai][bj][m][n] = __builtin_amdgcn_mfma_f32_16x16x32_bf16(Bt[n][k], At[m][k], acc[ai][bj][m][n], 0, 0, 0); __builtin_amdgcn_s_setprio(0); } while (0)
; #define PG8_WAIT_V(n) asm volatile("s_waitcnt vmcnt(" #n ")" ::: "memory")
; #define PG8_WAIT_L(n) asm volatile("s_waitcnt lgkmcnt(" #n ")" ::: "memory")
; #define PG8_BAR __builtin_amdgcn_s_barrier()
; #define PG8_SCHED __builtin_amdgcn_sched_barrier(0)
; template <class Epi, class Sched, bool ALIGN_EPI = false, bool SP2 = false>
; __device__ __forceinline__ void gemm_phase(PG8_LAS unsigned char* lds, const Gemm g, const Sched& S, const Epi& E) {
;     ...
;             PG8_WAIT_V(8); PG8_WAIT_L(0); PG8_BAR; PG8_MMA(1, 0, At, B0); PG8_MMA(1, 1, At, B1); PG8_BAR; PG8_SCHED;
;             PG8_LDB(B0, 1, 0); PG8_LDB(B1, 1, 1); PG8_SCHED; PG8_LDA(At, 1, 0); PG8_STAGE(PG8_SA(0, 1), a2 + hstepA, voffA);
;             PG8_WAIT_V(8); PG8_WAIT_L(0); PG8_BAR; PG8_MMA(0, 0, At, B0); PG8_MMA(0, 1, At, B1); PG8_BAR; PG8_SCHED;
	s_setprio 1
	v_mfma_f32_16x16x32_bf16 v[60:63], v[112:115], v[176:179], v[60:63]
	v_mfma_f32_16x16x32_bf16 v[56:59], v[128:131], v[176:179], v[56:59]
	v_mfma_f32_16x16x32_bf16 v[44:47], v[112:115], v[196:199], v[44:47]
	v_mfma_f32_16x16x32_bf16 v[40:43], v[128:131], v[196:199], v[40:43]
	v_mfma_f32_16x16x32_bf16 v[28:31], v[112:115], v[204:207], v[28:31]
	v_mfma_f32_16x16x32_bf16 v[24:27], v[128:131], v[204:207], v[24:27]
	v_mfma_f32_16x16x32_bf16 v[12:15], v[112:115], v[212:215], v[12:15]
	v_mfma_f32_16x16x32_bf16 v[8:11], v[128:131], v[212:215], v[8:11]
	v_mfma_f32_16x16x32_bf16 v[60:63], v[116:119], v[192:195], v[60:63]
	v_mfma_f32_16x16x32_bf16 v[56:59], v[140:143], v[192:195], v[56:59]
	v_mfma_f32_16x16x32_bf16 v[44:47], v[116:119], v[200:203], v[44:47]
	v_mfma_f32_16x16x32_bf16 v[40:43], v[140:143], v[200:203], v[40:43]
	v_mfma_f32_16x16x32_bf16 v[28:31], v[116:119], v[208:211], v[28:31]
	v_mfma_f32_16x16x32_bf16 v[24:27], v[140:143], v[208:211], v[24:27]
	v_mfma_f32_16x16x32_bf16 v[12:15], v[116:119], v[216:219], v[12:15]
	v_mfma_f32_16x16x32_bf16 v[8:11], v[140:143], v[216:219], v[8:11]
	s_setprio 0
	s_setprio 1
	v_mfma_f32_16x16x32_bf16 v[52:55], v[144:147], v[176:179], v[52:55]
	v_mfma_f32_16x16x32_bf16 v[48:51], v[168:171], v[176:179], v[48:51]
	v_mfma_f32_16x16x32_bf16 v[36:39], v[144:147], v[196:199], v[36:39]
	v_mfma_f32_16x16x32_bf16 v[32:35], v[168:171], v[196:199], v[32:35]
	v_mfma_f32_16x16x32_bf16 v[20:23], v[144:147], v[204:207], v[20:23]
	v_mfma_f32_16x16x32_bf16 v[16:19], v[168:171], v[204:207], v[16:19]
	v_mfma_f32_16x16x32_bf16 v[4:7], v[144:147], v[212:215], v[4:7]
	v_mfma_f32_16x16x32_bf16 v[0:3], v[168:171], v[212:215], v[0:3]
	v_mfma_f32_16x16x32_bf16 v[52:55], v[148:151], v[192:195], v[52:55]
	v_mfma_f32_16x16x32_bf16 v[48:51], v[172:175], v[192:195], v[48:51]
	v_mfma_f32_16x16x32_bf16 v[36:39], v[148:151], v[200:203], v[36:39]
	v_mfma_f32_16x16x32_bf16 v[32:35], v[172:175], v[200:203], v[32:35]
	v_mfma_f32_16x16x32_bf16 v[20:23], v[148:151], v[208:211], v[20:23]
	v_mfma_f32_16x16x32_bf16 v[16:19], v[172:175], v[208:211], v[16:19]
	v_mfma_f32_16x16x32_bf16 v[4:7], v[148:151], v[216:219], v[4:7]
	v_mfma_f32_16x16x32_bf16 v[0:3], v[172:175], v[216:219], v[0:3]
	s_barrier
	s_setprio 0
	s_add_i32 s58, 0, 0x18000
	s_add_i32 s59, 0, 0x1c000
	v_add_u32_e32 v140, s58, v183
	v_add_u32_e32 v172, s59, v183
	ds_read_b128 v[112:115], v140
	ds_read_b128 v[116:119], v140 offset:1024
	ds_read_b128 v[128:131], v140 offset:2048
	ds_read_b128 v[140:143], v140 offset:3072
	ds_read_b128 v[144:147], v172
	ds_read_b128 v[148:151], v172 offset:1024
	ds_read_b128 v[168:171], v172 offset:2048
	ds_read_b128 v[172:175], v172 offset:3072
	s_add_u32 s36, s36, 0x40000
	s_addc_u32 s37, s37, 0
	s_mov_b32 m0, s41
	v_lshl_add_u64 v[226:227], s[36:37], 0, v[152:153]
	ds_read_b128 v[176:179], v189 offset:32768
	ds_read_b128 v[192:195], v189 offset:33792
	ds_read_b128 v[196:199], v189 offset:34816
	ds_read_b128 v[200:203], v189 offset:35840
	ds_read_b128 v[204:207], v189 offset:36864
	ds_read_b128 v[208:211], v189 offset:37888
	ds_read_b128 v[212:215], v189 offset:38912
	ds_read_b128 v[216:219], v189 offset:39936
	global_load_lds_dwordx4 v[226:227], off
	v_lshl_add_u64 v[226:227], s[36:37], 0, v[156:157]
	s_mov_b32 m0, s42
	s_nop 0
	global_load_lds_dwordx4 v[226:227], off
	s_waitcnt vmcnt(8) lgkmcnt(0)
	s_barrier
	s_setprio 1
	v_mfma_f32_16x16x32_bf16 v[136:139], v[112:115], v[176:179], v[136:139]
	v_mfma_f32_16x16x32_bf16 v[132:135], v[128:131], v[176:179], v[132:135]
	v_mfma_f32_16x16x32_bf16 v[108:111], v[112:115], v[196:199], v[108:111]
	v_mfma_f32_16x16x32_bf16 v[104:107], v[128:131], v[196:199], v[104:107]
	v_mfma_f32_16x16x32_bf16 v[92:95], v[112:115], v[204:207], v[92:95]
	v_mfma_f32_16x16x32_bf16 v[88:91], v[128:131], v[204:207], v[88:91]
	v_mfma_f32_16x16x32_bf16 v[76:79], v[112:115], v[212:215], v[76:79]
	v_mfma_f32_16x16x32_bf16 v[72:75], v[128:131], v[212:215], v[72:75]
	v_mfma_f32_16x16x32_bf16 v[136:139], v[116:119], v[192:195], v[136:139]
	v_mfma_f32_16x16x32_bf16 v[132:135], v[140:143], v[192:195], v[132:135]
	v_mfma_f32_16x16x32_bf16 v[108:111], v[116:119], v[200:203], v[108:111]
	v_mfma_f32_16x16x32_bf16 v[104:107], v[140:143], v[200:203], v[104:107]
	v_mfma_f32_16x16x32_bf16 v[92:95], v[116:119], v[208:211], v[92:95]
	v_mfma_f32_16x16x32_bf16 v[88:91], v[140:143], v[208:211], v[88:91]
	v_mfma_f32_16x16x32_bf16 v[76:79], v[116:119], v[216:219], v[76:79]
	v_mfma_f32_16x16x32_bf16 v[72:75], v[140:143], v[216:219], v[72:75]
	s_setprio 0
	s_setprio 1
	v_mfma_f32_16x16x32_bf16 v[124:127], v[144:147], v[176:179], v[124:127]
	v_mfma_f32_16x16x32_bf16 v[120:123], v[168:171], v[176:179], v[120:123]
	v_mfma_f32_16x16x32_bf16 v[100:103], v[144:147], v[196:199], v[100:103]
	v_mfma_f32_16x16x32_bf16 v[96:99], v[168:171], v[196:199], v[96:99]
	v_mfma_f32_16x16x32_bf16 v[84:87], v[144:147], v[204:207], v[84:87]
	v_mfma_f32_16x16x32_bf16 v[80:83], v[168:171], v[204:207], v[80:83]
	v_mfma_f32_16x16x32_bf16 v[68:71], v[144:147], v[212:215], v[68:71]
	v_mfma_f32_16x16x32_bf16 v[64:67], v[168:171], v[212:215], v[64:67]
	v_mfma_f32_16x16x32_bf16 v[124:127], v[148:151], v[192:195], v[124:127]
	v_mfma_f32_16x16x32_bf16 v[120:123], v[172:175], v[192:195], v[120:123]
	v_mfma_f32_16x16x32_bf16 v[100:103], v[148:151], v[200:203], v[100:103]
	v_mfma_f32_16x16x32_bf16 v[96:99], v[172:175], v[200:203], v[96:99]
	v_mfma_f32_16x16x32_bf16 v[84:87], v[148:151], v[208:211], v[84:87]
	v_mfma_f32_16x16x32_bf16 v[80:83], v[172:175], v[208:211], v[80:83]
	v_mfma_f32_16x16x32_bf16 v[68:71], v[148:151], v[216:219], v[68:71]
	v_mfma_f32_16x16x32_bf16 v[64:67], v[172:175], v[216:219], v[64:67]
	s_barrier
; #define PG8_STAGE(bufoff, gbase, voff) do { _Pragma("unroll") for (int _i = 0; _i < 2; ++_i) \
;         __builtin_amdgcn_global_load_lds((const unsigned*)((const char*)(gbase) + (voff)[_i]), (PG8_LAS unsigned*)(lds + (bufoff) + ldsw + _i * 8192), 16, 0, 0); } while (0)
; #define PG8_LDA(dst, b, h) do { _Pragma("unroll") for (int m = 0; m < 4; ++m) _Pragma("unroll") for (int k = 0; k < 2; ++k) dst[m][k] = *(const PG8_LAS bf16x8*)(lds + PG8_SA(b, h) + aoff + m * 2048 + k * 1024); } while (0)
; #define PG8_MMA(ai, bj, At, Bt) do { __builtin_amdgcn_s_setprio(1); _Pragma("unroll") for (int m = 0; m < 4; ++m) _Pragma("unroll") for (int n = 0; n < 2; ++n) _Pragma("unroll") for (int k = 0; k < 2; ++k) \
;         acc[ai][bj][m][n] = __builtin_amdgcn_mfma_f32_16x16x32_bf16(Bt[n][k], At[m][k], acc[ai][bj][m][n], 0, 0, 0); __builtin_amdgcn_s_setprio(0); } while (0)
; #define PG8_WAIT_V(n) asm volatile("s_waitcnt vmcnt(" #n ")" ::: "memory")
; #define PG8_WAIT_L(n) asm volatile("s_waitcnt lgkmcnt(" #n ")" ::: "memory")
; #define PG8_BAR __builtin_amdgcn_s_barrier()
; #define PG8_SCHED __builtin_amdgcn_sched_barrier(0)
; template <class Epi, class Sched, bool ALIGN_EPI = false, bool SP2 = false>
; __device__ __forceinline__ void gemm_phase(PG8_LAS unsigned char* lds, const Gemm g, const Sched& S, const Epi& E) {
;     ...
;             PG8_LDA(At, 1, 1); PG8_STAGE(PG8_SB(1, 0), b3, voffB); PG8_STAGE(PG8_SB(1, 1), b3 + hstepB, voffB); PG8_STAGE(PG8_SA(1, 0), a3, voffA);
;             PG8_WAIT_V(8); PG8_WAIT_L(0); PG8_BAR; PG8_MMA(1, 0, At, B0); PG8_MMA(1, 1, At, B1); PG8_BAR; PG8_SCHED;
	s_setprio 0
	s_add_i32 s36, s58, s39
	v_lshl_add_u64 v[180:181], v[180:181], 0, s[14:15]
	s_mov_b32 m0, s36
	ds_read_b128 v[176:179], v189 offset:49152
	ds_read_b128 v[192:195], v189 offset:50176
	ds_read_b128 v[196:199], v189 offset:51200
	ds_read_b128 v[200:203], v189 offset:52224
	ds_read_b128 v[204:207], v189 offset:53248
	ds_read_b128 v[208:211], v189 offset:54272
	ds_read_b128 v[212:215], v189 offset:55296
	ds_read_b128 v[216:219], v189 offset:56320
	global_load_lds_dwordx4 v[180:181], off
	s_add_i32 m0, s36, 0x2000
	s_add_u32 s34, s34, 0x40080
	v_lshl_add_u64 v[180:181], v[220:221], 0, s[14:15]
	s_addc_u32 s35, s35, 0
	s_add_i32 s36, s59, s39
	global_load_lds_dwordx4 v[180:181], off
	v_lshl_add_u64 v[180:181], s[34:35], 0, v[154:155]
	s_mov_b32 m0, s36
	s_nop 0
	global_load_lds_dwordx4 v[180:181], off
	v_lshl_add_u64 v[180:181], s[34:35], 0, v[158:159]
	s_add_i32 m0, s36, 0x2000
	s_nop 0
	global_load_lds_dwordx4 v[180:181], off
	v_lshl_add_u64 v[180:181], v[222:223], 0, s[14:15]
	s_mov_b32 m0, s44
	s_nop 0
	global_load_lds_dwordx4 v[180:181], off
	v_lshl_add_u64 v[180:181], v[224:225], 0, s[14:15]
	s_mov_b32 m0, s45
	s_nop 0
	global_load_lds_dwordx4 v[180:181], off
	s_waitcnt vmcnt(8) lgkmcnt(0)
	s_barrier
	s_setprio 1
	v_mfma_f32_16x16x32_bf16 v[60:63], v[112:115], v[176:179], v[60:63]
	v_mfma_f32_16x16x32_bf16 v[56:59], v[128:131], v[176:179], v[56:59]
	v_mfma_f32_16x16x32_bf16 v[44:47], v[112:115], v[196:199], v[44:47]
	v_mfma_f32_16x16x32_bf16 v[40:43], v[128:131], v[196:199], v[40:43]
	v_mfma_f32_16x16x32_bf16 v[28:31], v[112:115], v[204:207], v[28:31]
	v_mfma_f32_16x16x32_bf16 v[24:27], v[128:131], v[204:207], v[24:27]
	v_mfma_f32_16x16x32_bf16 v[12:15], v[112:115], v[212:215], v[12:15]
	v_mfma_f32_16x16x32_bf16 v[8:11], v[128:131], v[212:215], v[8:11]
	v_mfma_f32_16x16x32_bf16 v[60:63], v[116:119], v[192:195], v[60:63]
	v_mfma_f32_16x16x32_bf16 v[56:59], v[140:143], v[192:195], v[56:59]
	v_mfma_f32_16x16x32_bf16 v[44:47], v[116:119], v[200:203], v[44:47]
	v_mfma_f32_16x16x32_bf16 v[40:43], v[140:143], v[200:203], v[40:43]
	v_mfma_f32_16x16x32_bf16 v[28:31], v[116:119], v[208:211], v[28:31]
	v_mfma_f32_16x16x32_bf16 v[24:27], v[140:143], v[208:211], v[24:27]
	v_mfma_f32_16x16x32_bf16 v[12:15], v[116:119], v[216:219], v[12:15]
	v_mfma_f32_16x16x32_bf16 v[8:11], v[140:143], v[216:219], v[8:11]
	s_setprio 0
	s_setprio 1
	v_mfma_f32_16x16x32_bf16 v[52:55], v[144:147], v[176:179], v[52:55]
	v_mfma_f32_16x16x32_bf16 v[48:51], v[168:171], v[176:179], v[48:51]
	v_mfma_f32_16x16x32_bf16 v[36:39], v[144:147], v[196:199], v[36:39]
	v_mfma_f32_16x16x32_bf16 v[32:35], v[168:171], v[196:199], v[32:35]
	v_mfma_f32_16x16x32_bf16 v[20:23], v[144:147], v[204:207], v[20:23]
	v_mfma_f32_16x16x32_bf16 v[16:19], v[168:171], v[204:207], v[16:19]
	v_mfma_f32_16x16x32_bf16 v[4:7], v[144:147], v[212:215], v[4:7]
	v_mfma_f32_16x16x32_bf16 v[0:3], v[168:171], v[212:215], v[0:3]
	v_mfma_f32_16x16x32_bf16 v[52:55], v[148:151], v[192:195], v[52:55]
	v_mfma_f32_16x16x32_bf16 v[48:51], v[172:175], v[192:195], v[48:51]
	v_mfma_f32_16x16x32_bf16 v[36:39], v[148:151], v[200:203], v[36:39]
	v_mfma_f32_16x16x32_bf16 v[32:35], v[172:175], v[200:203], v[32:35]
	v_mfma_f32_16x16x32_bf16 v[20:23], v[148:151], v[208:211], v[20:23]
	v_mfma_f32_16x16x32_bf16 v[16:19], v[172:175], v[208:211], v[16:19]
	v_mfma_f32_16x16x32_bf16 v[4:7], v[148:151], v[216:219], v[4:7]
	v_mfma_f32_16x16x32_bf16 v[0:3], v[172:175], v[216:219], v[0:3]
	s_barrier
	s_setprio 0
	s_add_i32 s69, s69, 2
	s_add_u32 s30, s30, 0x100
	s_addc_u32 s31, s31, 0
	s_add_u32 s67, s67, 0x100
	s_addc_u32 s68, s68, 0
	s_cmp_gt_u32 s69, 13
	s_cbranch_scc0 .LBB0_1231
	s_and_b64 vcc, exec, s[16:17]
	s_cbranch_vccz .LBB0_1234
	s_barrier
